# combined small de-serialisations: plain GEMM epilogue copies batched, in1 transposed copy with whole-line stores, retention Q fragments loaded once per unit, conv d-loop fillers interleaved
# speedup vs baseline: 1.0022x; 1.0022x over previous
; #define G_LOADA(kt_) { _Pragma("unroll") for (int i = 0; i < 4; ++i) ra[i] = al(lrow + 64 * i, (kt_) * 64 + lck * 8); }
; #define G_LOADB(kt_) { _Pragma("unroll") for (int i = 0; i < 4; ++i) rb[i] = bl(lrow + 64 * i, (kt_) * 64 + lck * 8); }
; #define G_STOREA(buf_) { bf16_t* nA = sA + (buf_) * 256 * GLD; _Pragma("unroll") for (int i = 0; i < 4; ++i) *(u32x4*)(nA + (lrow + 64 * i) * GLD + lck * 8) = ra[i]; }
; #define G_STOREB(buf_) { bf16_t* nB = sB + (buf_) * 256 * GLD; _Pragma("unroll") for (int i = 0; i < 4; ++i) *(u32x4*)(nB + (lrow + 64 * i) * GLD + lck * 8) = rb[i]; }
; template <class AL, class BL, class EP>
; DI void gemm_tile256(AL al, BL bl, EP ep, int K, char* smem) {
;     ...
;   G_LOADA(0); G_LOADB(0);
;   __syncthreads();
;   G_STOREA(0); G_STOREB(0);
;   if (KT > 1) G_LOADB(1);
;   __syncthreads();
;   for (int kt = 0; kt < KT; kt += 2) {
;     G_STEP(0, kt);
;     if (kt + 1 >= KT) break;
;     G_STEP(1, kt + 1);
;   }
.Lgk_ph1_loop:
	s_waitcnt lgkmcnt(0)
	v_mfma_f32_32x32x16_bf16 v[112:127], v[208:211], v[172:175], v[112:127]
	ds_read_b128 v[216:219], v198
	ds_read_b128 v[188:191], v171
	v_mfma_f32_32x32x16_bf16 v[96:111], v[212:215], v[172:175], v[96:111]
	ds_read_b128 v[220:223], v198 offset:2048
	ds_read_b128 v[192:195], v171 offset:2048
	v_mfma_f32_32x32x16_bf16 v[80:95], v[208:211], v[176:179], v[80:95]
	ds_read_b128 v[200:203], v171 offset:4096
	ds_read_b128 v[204:207], v171 offset:6144
	v_mfma_f32_32x32x16_bf16 v[64:79], v[212:215], v[176:179], v[64:79]
	s_add_u32 m0, s32, 0x22000
	s_nop 0
	global_load_lds_dwordx4 v[234:235], off
	v_lshl_add_u64 v[234:235], v[234:235], 0, s[38:39]
	v_mfma_f32_32x32x16_bf16 v[48:63], v[208:211], v[180:183], v[48:63]
	v_mfma_f32_32x32x16_bf16 v[32:47], v[212:215], v[180:183], v[32:47]
	v_mfma_f32_32x32x16_bf16 v[16:31], v[208:211], v[184:187], v[16:31]
	v_mfma_f32_32x32x16_bf16 v[0:15], v[212:215], v[184:187], v[0:15]
	s_add_u32 m0, s32, 0x26000
	s_nop 0
	global_load_lds_dwordx4 v[238:239], off
	v_lshl_add_u64 v[238:239], v[238:239], 0, s[38:39]
	s_waitcnt lgkmcnt(0)
	s_waitcnt vmcnt(12)
	s_barrier
	s_waitcnt lgkmcnt(0)
	v_mfma_f32_32x32x16_bf16 v[112:127], v[216:219], v[188:191], v[112:127]
	ds_read_b128 v[208:211], v197 offset:32768
	ds_read_b128 v[172:175], v132 offset:32768
	v_mfma_f32_32x32x16_bf16 v[96:111], v[220:223], v[188:191], v[96:111]
	ds_read_b128 v[212:215], v197 offset:34816
	ds_read_b128 v[176:179], v132 offset:34816
	v_mfma_f32_32x32x16_bf16 v[80:95], v[216:219], v[192:195], v[80:95]
	ds_read_b128 v[180:183], v132 offset:36864
	ds_read_b128 v[184:187], v132 offset:38912
	v_mfma_f32_32x32x16_bf16 v[64:79], v[220:223], v[192:195], v[64:79]
	s_add_u32 m0, s32, 0x0
	s_nop 0
	global_load_lds_dwordx4 v[232:233], off
	v_lshl_add_u64 v[232:233], v[232:233], 0, s[38:39]
	v_mfma_f32_32x32x16_bf16 v[48:63], v[216:219], v[200:203], v[48:63]
	v_mfma_f32_32x32x16_bf16 v[32:47], v[220:223], v[200:203], v[32:47]
	v_mfma_f32_32x32x16_bf16 v[16:31], v[216:219], v[204:207], v[16:31]
	v_mfma_f32_32x32x16_bf16 v[0:15], v[220:223], v[204:207], v[0:15]
	s_add_u32 m0, s32, 0x4000
	s_nop 0
	global_load_lds_dwordx4 v[236:237], off
	v_lshl_add_u64 v[236:237], v[236:237], 0, s[38:39]
	s_waitcnt lgkmcnt(0)
	v_mfma_f32_32x32x16_bf16 v[112:127], v[208:211], v[172:175], v[112:127]
	ds_read_b128 v[216:219], v198 offset:32768
	ds_read_b128 v[188:191], v171 offset:32768
	v_mfma_f32_32x32x16_bf16 v[96:111], v[212:215], v[172:175], v[96:111]
	ds_read_b128 v[220:223], v198 offset:34816
	ds_read_b128 v[192:195], v171 offset:34816
	v_mfma_f32_32x32x16_bf16 v[80:95], v[208:211], v[176:179], v[80:95]
	ds_read_b128 v[200:203], v171 offset:36864
	ds_read_b128 v[204:207], v171 offset:38912
	v_mfma_f32_32x32x16_bf16 v[64:79], v[212:215], v[176:179], v[64:79]
	s_add_u32 m0, s32, 0x2000
	s_nop 0
	global_load_lds_dwordx4 v[234:235], off
	v_lshl_add_u64 v[234:235], v[234:235], 0, s[38:39]
	v_mfma_f32_32x32x16_bf16 v[48:63], v[208:211], v[180:183], v[48:63]
	v_mfma_f32_32x32x16_bf16 v[32:47], v[212:215], v[180:183], v[32:47]
	v_mfma_f32_32x32x16_bf16 v[16:31], v[208:211], v[184:187], v[16:31]
	v_mfma_f32_32x32x16_bf16 v[0:15], v[212:215], v[184:187], v[0:15]
	s_add_u32 m0, s32, 0x6000
	s_nop 0
	global_load_lds_dwordx4 v[238:239], off
	v_lshl_add_u64 v[238:239], v[238:239], 0, s[38:39]
	s_waitcnt lgkmcnt(0)
	s_waitcnt vmcnt(12)
	s_barrier
	s_waitcnt lgkmcnt(0)
	v_mfma_f32_32x32x16_bf16 v[112:127], v[216:219], v[188:191], v[112:127]
	ds_read_b128 v[208:211], v225
	ds_read_b128 v[172:175], v199
	v_mfma_f32_32x32x16_bf16 v[96:111], v[220:223], v[188:191], v[96:111]
	ds_read_b128 v[212:215], v225 offset:2048
	ds_read_b128 v[176:179], v199 offset:2048
	v_mfma_f32_32x32x16_bf16 v[80:95], v[216:219], v[192:195], v[80:95]
	ds_read_b128 v[180:183], v199 offset:4096
	ds_read_b128 v[184:187], v199 offset:6144
	v_mfma_f32_32x32x16_bf16 v[64:79], v[220:223], v[192:195], v[64:79]
	s_add_u32 m0, s32, 0x8000
	s_nop 0
	global_load_lds_dwordx4 v[232:233], off
	v_lshl_add_u64 v[232:233], v[232:233], 0, s[38:39]
	v_mfma_f32_32x32x16_bf16 v[48:63], v[216:219], v[200:203], v[48:63]
	v_mfma_f32_32x32x16_bf16 v[32:47], v[220:223], v[200:203], v[32:47]
	v_mfma_f32_32x32x16_bf16 v[16:31], v[216:219], v[204:207], v[16:31]
	v_mfma_f32_32x32x16_bf16 v[0:15], v[220:223], v[204:207], v[0:15]
	s_add_u32 m0, s32, 0xc000
	s_nop 0
	global_load_lds_dwordx4 v[236:237], off
	v_lshl_add_u64 v[236:237], v[236:237], 0, s[38:39]
	s_waitcnt lgkmcnt(0)
	v_mfma_f32_32x32x16_bf16 v[112:127], v[208:211], v[172:175], v[112:127]
	ds_read_b128 v[216:219], v226
	ds_read_b128 v[188:191], v224
	v_mfma_f32_32x32x16_bf16 v[96:111], v[212:215], v[172:175], v[96:111]
	ds_read_b128 v[220:223], v226 offset:2048
	ds_read_b128 v[192:195], v224 offset:2048
	v_mfma_f32_32x32x16_bf16 v[80:95], v[208:211], v[176:179], v[80:95]
	ds_read_b128 v[200:203], v224 offset:4096
	ds_read_b128 v[204:207], v224 offset:6144
	v_mfma_f32_32x32x16_bf16 v[64:79], v[212:215], v[176:179], v[64:79]
	s_add_u32 m0, s32, 0xa000
	s_nop 0
	global_load_lds_dwordx4 v[234:235], off
	v_lshl_add_u64 v[234:235], v[234:235], 0, s[38:39]
	v_mfma_f32_32x32x16_bf16 v[48:63], v[208:211], v[180:183], v[48:63]
	v_mfma_f32_32x32x16_bf16 v[32:47], v[212:215], v[180:183], v[32:47]
	v_mfma_f32_32x32x16_bf16 v[16:31], v[208:211], v[184:187], v[16:31]
	v_mfma_f32_32x32x16_bf16 v[0:15], v[212:215], v[184:187], v[0:15]
	s_add_u32 m0, s32, 0xe000
	s_nop 0
	global_load_lds_dwordx4 v[238:239], off
	v_lshl_add_u64 v[238:239], v[238:239], 0, s[38:39]
	s_waitcnt lgkmcnt(0)
	s_waitcnt vmcnt(12)
	s_barrier
; #define G_LOADA(kt_) { _Pragma("unroll") for (int i = 0; i < 4; ++i) ra[i] = al(lrow + 64 * i, (kt_) * 64 + lck * 8); }
; #define G_LOADB(kt_) { _Pragma("unroll") for (int i = 0; i < 4; ++i) rb[i] = bl(lrow + 64 * i, (kt_) * 64 + lck * 8); }
; #define G_STOREA(buf_) { bf16_t* nA = sA + (buf_) * 256 * GLD; _Pragma("unroll") for (int i = 0; i < 4; ++i) *(u32x4*)(nA + (lrow + 64 * i) * GLD + lck * 8) = ra[i]; }
; #define G_STOREB(buf_) { bf16_t* nB = sB + (buf_) * 256 * GLD; _Pragma("unroll") for (int i = 0; i < 4; ++i) *(u32x4*)(nB + (lrow + 64 * i) * GLD + lck * 8) = rb[i]; }
; template <class AL, class BL, class EP>
; DI void gemm_tile256(AL al, BL bl, EP ep, int K, char* smem) {
;     ...
;   G_LOADA(0); G_LOADB(0);
;   __syncthreads();
;   G_STOREA(0); G_STOREB(0);
;   if (KT > 1) G_LOADB(1);
;   __syncthreads();
;   for (int kt = 0; kt < KT; kt += 2) {
;     G_STEP(0, kt);
;     if (kt + 1 >= KT) break;
;     G_STEP(1, kt + 1);
;   }
	s_waitcnt lgkmcnt(0)
	v_mfma_f32_32x32x16_bf16 v[112:127], v[216:219], v[188:191], v[112:127]
	ds_read_b128 v[208:211], v225 offset:32768
	ds_read_b128 v[172:175], v199 offset:32768
	v_mfma_f32_32x32x16_bf16 v[96:111], v[220:223], v[188:191], v[96:111]
	ds_read_b128 v[212:215], v225 offset:34816
	ds_read_b128 v[176:179], v199 offset:34816
	v_mfma_f32_32x32x16_bf16 v[80:95], v[216:219], v[192:195], v[80:95]
	ds_read_b128 v[180:183], v199 offset:36864
	ds_read_b128 v[184:187], v199 offset:38912
	v_mfma_f32_32x32x16_bf16 v[64:79], v[220:223], v[192:195], v[64:79]
	s_add_u32 m0, s32, 0x10000
	s_nop 0
	global_load_lds_dwordx4 v[232:233], off
	v_lshl_add_u64 v[232:233], v[232:233], 0, s[38:39]
	v_mfma_f32_32x32x16_bf16 v[48:63], v[216:219], v[200:203], v[48:63]
	v_mfma_f32_32x32x16_bf16 v[32:47], v[220:223], v[200:203], v[32:47]
	v_mfma_f32_32x32x16_bf16 v[16:31], v[216:219], v[204:207], v[16:31]
	v_mfma_f32_32x32x16_bf16 v[0:15], v[220:223], v[204:207], v[0:15]
	s_add_u32 m0, s32, 0x14000
	s_nop 0
	global_load_lds_dwordx4 v[236:237], off
	v_lshl_add_u64 v[236:237], v[236:237], 0, s[38:39]
	s_waitcnt lgkmcnt(0)
	v_mfma_f32_32x32x16_bf16 v[112:127], v[208:211], v[172:175], v[112:127]
	ds_read_b128 v[216:219], v226 offset:32768
	ds_read_b128 v[188:191], v224 offset:32768
	v_mfma_f32_32x32x16_bf16 v[96:111], v[212:215], v[172:175], v[96:111]
	ds_read_b128 v[220:223], v226 offset:34816
	ds_read_b128 v[192:195], v224 offset:34816
	v_mfma_f32_32x32x16_bf16 v[80:95], v[208:211], v[176:179], v[80:95]
	ds_read_b128 v[200:203], v224 offset:36864
	ds_read_b128 v[204:207], v224 offset:38912
	v_mfma_f32_32x32x16_bf16 v[64:79], v[212:215], v[176:179], v[64:79]
	s_add_u32 m0, s32, 0x12000
	s_nop 0
	global_load_lds_dwordx4 v[234:235], off
	v_lshl_add_u64 v[234:235], v[234:235], 0, s[38:39]
	v_mfma_f32_32x32x16_bf16 v[48:63], v[208:211], v[180:183], v[48:63]
	v_mfma_f32_32x32x16_bf16 v[32:47], v[212:215], v[180:183], v[32:47]
	v_mfma_f32_32x32x16_bf16 v[16:31], v[208:211], v[184:187], v[16:31]
	v_mfma_f32_32x32x16_bf16 v[0:15], v[212:215], v[184:187], v[0:15]
	s_add_u32 m0, s32, 0x16000
	s_nop 0
	global_load_lds_dwordx4 v[238:239], off
	v_lshl_add_u64 v[238:239], v[238:239], 0, s[38:39]
	s_waitcnt lgkmcnt(0)
	s_waitcnt vmcnt(12)
	s_barrier
	s_waitcnt lgkmcnt(0)
	v_mfma_f32_32x32x16_bf16 v[112:127], v[216:219], v[188:191], v[112:127]
	ds_read_b128 v[208:211], v229
	ds_read_b128 v[172:175], v227
	v_mfma_f32_32x32x16_bf16 v[96:111], v[220:223], v[188:191], v[96:111]
	ds_read_b128 v[212:215], v229 offset:2048
	ds_read_b128 v[176:179], v227 offset:2048
	v_mfma_f32_32x32x16_bf16 v[80:95], v[216:219], v[192:195], v[80:95]
	ds_read_b128 v[180:183], v227 offset:4096
	ds_read_b128 v[184:187], v227 offset:6144
	v_mfma_f32_32x32x16_bf16 v[64:79], v[220:223], v[192:195], v[64:79]
	s_add_u32 m0, s32, 0x18000
	s_nop 0
	global_load_lds_dwordx4 v[232:233], off
	v_lshl_add_u64 v[232:233], v[232:233], 0, s[38:39]
	v_mfma_f32_32x32x16_bf16 v[48:63], v[216:219], v[200:203], v[48:63]
	v_mfma_f32_32x32x16_bf16 v[32:47], v[220:223], v[200:203], v[32:47]
	v_mfma_f32_32x32x16_bf16 v[16:31], v[216:219], v[204:207], v[16:31]
	v_mfma_f32_32x32x16_bf16 v[0:15], v[220:223], v[204:207], v[0:15]
	s_add_u32 m0, s32, 0x1c000
	s_nop 0
	global_load_lds_dwordx4 v[236:237], off
	v_lshl_add_u64 v[236:237], v[236:237], 0, s[38:39]
	s_waitcnt lgkmcnt(0)
	v_mfma_f32_32x32x16_bf16 v[112:127], v[208:211], v[172:175], v[112:127]
	ds_read_b128 v[216:219], v230
	ds_read_b128 v[188:191], v228
	v_mfma_f32_32x32x16_bf16 v[96:111], v[212:215], v[172:175], v[96:111]
	ds_read_b128 v[220:223], v230 offset:2048
	ds_read_b128 v[192:195], v228 offset:2048
	v_mfma_f32_32x32x16_bf16 v[80:95], v[208:211], v[176:179], v[80:95]
	ds_read_b128 v[200:203], v228 offset:4096
	ds_read_b128 v[204:207], v228 offset:6144
	v_mfma_f32_32x32x16_bf16 v[64:79], v[212:215], v[176:179], v[64:79]
	s_add_u32 m0, s32, 0x1a000
	s_nop 0
	global_load_lds_dwordx4 v[234:235], off
	v_lshl_add_u64 v[234:235], v[234:235], 0, s[38:39]
	v_mfma_f32_32x32x16_bf16 v[48:63], v[208:211], v[180:183], v[48:63]
	v_mfma_f32_32x32x16_bf16 v[32:47], v[212:215], v[180:183], v[32:47]
	v_mfma_f32_32x32x16_bf16 v[16:31], v[208:211], v[184:187], v[16:31]
	v_mfma_f32_32x32x16_bf16 v[0:15], v[212:215], v[184:187], v[0:15]
	s_add_u32 m0, s32, 0x1e000
	s_nop 0
	global_load_lds_dwordx4 v[238:239], off
	v_lshl_add_u64 v[238:239], v[238:239], 0, s[38:39]
	s_waitcnt lgkmcnt(0)
	s_waitcnt vmcnt(12)
	s_barrier
	s_waitcnt lgkmcnt(0)
	v_mfma_f32_32x32x16_bf16 v[112:127], v[216:219], v[188:191], v[112:127]
	ds_read_b128 v[208:211], v197
	ds_read_b128 v[172:175], v132
	v_mfma_f32_32x32x16_bf16 v[96:111], v[220:223], v[188:191], v[96:111]
	ds_read_b128 v[212:215], v197 offset:2048
	ds_read_b128 v[176:179], v132 offset:2048
	v_mfma_f32_32x32x16_bf16 v[80:95], v[216:219], v[192:195], v[80:95]
	ds_read_b128 v[180:183], v132 offset:4096
	ds_read_b128 v[184:187], v132 offset:6144
	v_mfma_f32_32x32x16_bf16 v[64:79], v[220:223], v[192:195], v[64:79]
	s_add_u32 m0, s32, 0x20000
	s_nop 0
	global_load_lds_dwordx4 v[232:233], off
	v_lshl_add_u64 v[232:233], v[232:233], 0, s[38:39]
	v_mfma_f32_32x32x16_bf16 v[48:63], v[216:219], v[200:203], v[48:63]
	v_mfma_f32_32x32x16_bf16 v[32:47], v[220:223], v[200:203], v[32:47]
	v_mfma_f32_32x32x16_bf16 v[16:31], v[216:219], v[204:207], v[16:31]
	v_mfma_f32_32x32x16_bf16 v[0:15], v[220:223], v[204:207], v[0:15]
	s_add_u32 m0, s32, 0x24000
	s_nop 0
	global_load_lds_dwordx4 v[236:237], off
	v_lshl_add_u64 v[236:237], v[236:237], 0, s[38:39]
	s_sub_u32 s54, s54, 1
	s_cmp_lg_u32 s54, 0
	s_cbranch_scc1 .Lgk_ph1_loop
; #define G_LOADA(kt_) { _Pragma("unroll") for (int i = 0; i < 4; ++i) ra[i] = al(lrow + 64 * i, (kt_) * 64 + lck * 8); }
; #define G_LOADB(kt_) { _Pragma("unroll") for (int i = 0; i < 4; ++i) rb[i] = bl(lrow + 64 * i, (kt_) * 64 + lck * 8); }
; #define G_STOREA(buf_) { bf16_t* nA = sA + (buf_) * 256 * GLD; _Pragma("unroll") for (int i = 0; i < 4; ++i) *(u32x4*)(nA + (lrow + 64 * i) * GLD + lck * 8) = ra[i]; }
; #define G_STOREB(buf_) { bf16_t* nB = sB + (buf_) * 256 * GLD; _Pragma("unroll") for (int i = 0; i < 4; ++i) *(u32x4*)(nB + (lrow + 64 * i) * GLD + lck * 8) = rb[i]; }
; template <class AL, class BL, class EP>
; DI void gemm_tile256(AL al, BL bl, EP ep, int K, char* smem) {
;     ...
;   G_LOADA(0); G_LOADB(0);
;   __syncthreads();
;   G_STOREA(0); G_STOREB(0);
;   if (KT > 1) G_LOADB(1);
;   __syncthreads();
;   for (int kt = 0; kt < KT; kt += 2) {
;     G_STEP(0, kt);
;     if (kt + 1 >= KT) break;
;     G_STEP(1, kt + 1);
;   }
	s_waitcnt lgkmcnt(0)
	v_mfma_f32_32x32x16_bf16 v[112:127], v[208:211], v[172:175], v[112:127]
	ds_read_b128 v[216:219], v198
	ds_read_b128 v[188:191], v171
	v_mfma_f32_32x32x16_bf16 v[96:111], v[212:215], v[172:175], v[96:111]
	ds_read_b128 v[220:223], v198 offset:2048
	ds_read_b128 v[192:195], v171 offset:2048
	v_mfma_f32_32x32x16_bf16 v[80:95], v[208:211], v[176:179], v[80:95]
	ds_read_b128 v[200:203], v171 offset:4096
	ds_read_b128 v[204:207], v171 offset:6144
	v_mfma_f32_32x32x16_bf16 v[64:79], v[212:215], v[176:179], v[64:79]
	s_add_u32 m0, s32, 0x22000
	s_nop 0
	global_load_lds_dwordx4 v[234:235], off
	v_lshl_add_u64 v[234:235], v[234:235], 0, s[38:39]
	v_mfma_f32_32x32x16_bf16 v[48:63], v[208:211], v[180:183], v[48:63]
	v_mfma_f32_32x32x16_bf16 v[32:47], v[212:215], v[180:183], v[32:47]
	v_mfma_f32_32x32x16_bf16 v[16:31], v[208:211], v[184:187], v[16:31]
	v_mfma_f32_32x32x16_bf16 v[0:15], v[212:215], v[184:187], v[0:15]
	s_add_u32 m0, s32, 0x26000
	s_nop 0
	global_load_lds_dwordx4 v[238:239], off
	v_lshl_add_u64 v[238:239], v[238:239], 0, s[38:39]
	s_waitcnt lgkmcnt(0)
	s_waitcnt vmcnt(12)
	s_barrier
	s_waitcnt lgkmcnt(0)
	v_mfma_f32_32x32x16_bf16 v[112:127], v[216:219], v[188:191], v[112:127]
	ds_read_b128 v[208:211], v197 offset:32768
	ds_read_b128 v[172:175], v132 offset:32768
	v_mfma_f32_32x32x16_bf16 v[96:111], v[220:223], v[188:191], v[96:111]
	ds_read_b128 v[212:215], v197 offset:34816
	ds_read_b128 v[176:179], v132 offset:34816
	v_mfma_f32_32x32x16_bf16 v[80:95], v[216:219], v[192:195], v[80:95]
	ds_read_b128 v[180:183], v132 offset:36864
	ds_read_b128 v[184:187], v132 offset:38912
	v_mfma_f32_32x32x16_bf16 v[64:79], v[220:223], v[192:195], v[64:79]
	s_add_u32 m0, s32, 0x0
	s_nop 0
	global_load_lds_dwordx4 v[232:233], off
	v_lshl_add_u64 v[232:233], v[232:233], 0, s[38:39]
	v_mfma_f32_32x32x16_bf16 v[48:63], v[216:219], v[200:203], v[48:63]
	v_mfma_f32_32x32x16_bf16 v[32:47], v[220:223], v[200:203], v[32:47]
	v_mfma_f32_32x32x16_bf16 v[16:31], v[216:219], v[204:207], v[16:31]
	v_mfma_f32_32x32x16_bf16 v[0:15], v[220:223], v[204:207], v[0:15]
	s_add_u32 m0, s32, 0x4000
	s_nop 0
	global_load_lds_dwordx4 v[236:237], off
	v_lshl_add_u64 v[236:237], v[236:237], 0, s[38:39]
	s_waitcnt lgkmcnt(0)
	v_mfma_f32_32x32x16_bf16 v[112:127], v[208:211], v[172:175], v[112:127]
	ds_read_b128 v[216:219], v198 offset:32768
	ds_read_b128 v[188:191], v171 offset:32768
	v_mfma_f32_32x32x16_bf16 v[96:111], v[212:215], v[172:175], v[96:111]
	ds_read_b128 v[220:223], v198 offset:34816
	ds_read_b128 v[192:195], v171 offset:34816
	v_mfma_f32_32x32x16_bf16 v[80:95], v[208:211], v[176:179], v[80:95]
	ds_read_b128 v[200:203], v171 offset:36864
	ds_read_b128 v[204:207], v171 offset:38912
	v_mfma_f32_32x32x16_bf16 v[64:79], v[212:215], v[176:179], v[64:79]
	s_add_u32 m0, s32, 0x2000
	s_nop 0
	global_load_lds_dwordx4 v[234:235], off
	v_lshl_add_u64 v[234:235], v[234:235], 0, s[38:39]
	v_mfma_f32_32x32x16_bf16 v[48:63], v[208:211], v[180:183], v[48:63]
	v_mfma_f32_32x32x16_bf16 v[32:47], v[212:215], v[180:183], v[32:47]
	v_mfma_f32_32x32x16_bf16 v[16:31], v[208:211], v[184:187], v[16:31]
	v_mfma_f32_32x32x16_bf16 v[0:15], v[212:215], v[184:187], v[0:15]
	s_add_u32 m0, s32, 0x6000
	s_nop 0
	global_load_lds_dwordx4 v[238:239], off
	v_lshl_add_u64 v[238:239], v[238:239], 0, s[38:39]
	s_waitcnt lgkmcnt(0)
	s_waitcnt vmcnt(12)
	s_barrier
	s_waitcnt lgkmcnt(0)
	v_mfma_f32_32x32x16_bf16 v[112:127], v[216:219], v[188:191], v[112:127]
	ds_read_b128 v[208:211], v225
	ds_read_b128 v[172:175], v199
	v_mfma_f32_32x32x16_bf16 v[96:111], v[220:223], v[188:191], v[96:111]
	ds_read_b128 v[212:215], v225 offset:2048
	ds_read_b128 v[176:179], v199 offset:2048
	v_mfma_f32_32x32x16_bf16 v[80:95], v[216:219], v[192:195], v[80:95]
	ds_read_b128 v[180:183], v199 offset:4096
	ds_read_b128 v[184:187], v199 offset:6144
	v_mfma_f32_32x32x16_bf16 v[64:79], v[220:223], v[192:195], v[64:79]
	s_add_u32 m0, s32, 0x8000
	s_nop 0
	global_load_lds_dwordx4 v[232:233], off
	v_lshl_add_u64 v[232:233], v[232:233], 0, s[38:39]
	v_mfma_f32_32x32x16_bf16 v[48:63], v[216:219], v[200:203], v[48:63]
	v_mfma_f32_32x32x16_bf16 v[32:47], v[220:223], v[200:203], v[32:47]
	v_mfma_f32_32x32x16_bf16 v[16:31], v[216:219], v[204:207], v[16:31]
	v_mfma_f32_32x32x16_bf16 v[0:15], v[220:223], v[204:207], v[0:15]
	s_add_u32 m0, s32, 0xc000
	s_nop 0
	global_load_lds_dwordx4 v[236:237], off
	v_lshl_add_u64 v[236:237], v[236:237], 0, s[38:39]
	s_waitcnt lgkmcnt(0)
	v_mfma_f32_32x32x16_bf16 v[112:127], v[208:211], v[172:175], v[112:127]
	ds_read_b128 v[216:219], v226
	ds_read_b128 v[188:191], v224
	v_mfma_f32_32x32x16_bf16 v[96:111], v[212:215], v[172:175], v[96:111]
	ds_read_b128 v[220:223], v226 offset:2048
	ds_read_b128 v[192:195], v224 offset:2048
	v_mfma_f32_32x32x16_bf16 v[80:95], v[208:211], v[176:179], v[80:95]
	ds_read_b128 v[200:203], v224 offset:4096
	ds_read_b128 v[204:207], v224 offset:6144
	v_mfma_f32_32x32x16_bf16 v[64:79], v[212:215], v[176:179], v[64:79]
	s_add_u32 m0, s32, 0xa000
	s_nop 0
	global_load_lds_dwordx4 v[234:235], off
	v_lshl_add_u64 v[234:235], v[234:235], 0, s[38:39]
	v_mfma_f32_32x32x16_bf16 v[48:63], v[208:211], v[180:183], v[48:63]
	v_mfma_f32_32x32x16_bf16 v[32:47], v[212:215], v[180:183], v[32:47]
	v_mfma_f32_32x32x16_bf16 v[16:31], v[208:211], v[184:187], v[16:31]
	v_mfma_f32_32x32x16_bf16 v[0:15], v[212:215], v[184:187], v[0:15]
	s_add_u32 m0, s32, 0xe000
	s_nop 0
	global_load_lds_dwordx4 v[238:239], off
	v_lshl_add_u64 v[238:239], v[238:239], 0, s[38:39]
	s_waitcnt lgkmcnt(0)
	s_waitcnt vmcnt(12)
	s_barrier
; #define G_LOADA(kt_) { _Pragma("unroll") for (int i = 0; i < 4; ++i) ra[i] = al(lrow + 64 * i, (kt_) * 64 + lck * 8); }
; #define G_LOADB(kt_) { _Pragma("unroll") for (int i = 0; i < 4; ++i) rb[i] = bl(lrow + 64 * i, (kt_) * 64 + lck * 8); }
; #define G_STOREA(buf_) { bf16_t* nA = sA + (buf_) * 256 * GLD; _Pragma("unroll") for (int i = 0; i < 4; ++i) *(u32x4*)(nA + (lrow + 64 * i) * GLD + lck * 8) = ra[i]; }
; #define G_STOREB(buf_) { bf16_t* nB = sB + (buf_) * 256 * GLD; _Pragma("unroll") for (int i = 0; i < 4; ++i) *(u32x4*)(nB + (lrow + 64 * i) * GLD + lck * 8) = rb[i]; }
; template <class AL, class BL, class EP>
; DI void gemm_tile256(AL al, BL bl, EP ep, int K, char* smem) {
;     ...
;   G_LOADA(0); G_LOADB(0);
;   __syncthreads();
;   G_STOREA(0); G_STOREB(0);
;   if (KT > 1) G_LOADB(1);
;   __syncthreads();
;   for (int kt = 0; kt < KT; kt += 2) {
;     G_STEP(0, kt);
;     if (kt + 1 >= KT) break;
;     G_STEP(1, kt + 1);
;   }
	s_waitcnt lgkmcnt(0)
	v_mfma_f32_32x32x16_bf16 v[112:127], v[216:219], v[188:191], v[112:127]
	ds_read_b128 v[208:211], v225 offset:32768
	ds_read_b128 v[172:175], v199 offset:32768
	v_mfma_f32_32x32x16_bf16 v[96:111], v[220:223], v[188:191], v[96:111]
	ds_read_b128 v[212:215], v225 offset:34816
	ds_read_b128 v[176:179], v199 offset:34816
	v_mfma_f32_32x32x16_bf16 v[80:95], v[216:219], v[192:195], v[80:95]
	ds_read_b128 v[180:183], v199 offset:36864
	ds_read_b128 v[184:187], v199 offset:38912
	v_mfma_f32_32x32x16_bf16 v[64:79], v[220:223], v[192:195], v[64:79]
	v_mfma_f32_32x32x16_bf16 v[48:63], v[216:219], v[200:203], v[48:63]
	v_mfma_f32_32x32x16_bf16 v[32:47], v[220:223], v[200:203], v[32:47]
	v_mfma_f32_32x32x16_bf16 v[16:31], v[216:219], v[204:207], v[16:31]
	v_mfma_f32_32x32x16_bf16 v[0:15], v[220:223], v[204:207], v[0:15]
	s_waitcnt lgkmcnt(0)
	v_mfma_f32_32x32x16_bf16 v[112:127], v[208:211], v[172:175], v[112:127]
	ds_read_b128 v[216:219], v226 offset:32768
	ds_read_b128 v[188:191], v224 offset:32768
	v_mfma_f32_32x32x16_bf16 v[96:111], v[212:215], v[172:175], v[96:111]
	ds_read_b128 v[220:223], v226 offset:34816
	ds_read_b128 v[192:195], v224 offset:34816
	v_mfma_f32_32x32x16_bf16 v[80:95], v[208:211], v[176:179], v[80:95]
	ds_read_b128 v[200:203], v224 offset:36864
	ds_read_b128 v[204:207], v224 offset:38912
	v_mfma_f32_32x32x16_bf16 v[64:79], v[212:215], v[176:179], v[64:79]
	v_mfma_f32_32x32x16_bf16 v[48:63], v[208:211], v[180:183], v[48:63]
	v_mfma_f32_32x32x16_bf16 v[32:47], v[212:215], v[180:183], v[32:47]
	v_mfma_f32_32x32x16_bf16 v[16:31], v[208:211], v[184:187], v[16:31]
	v_mfma_f32_32x32x16_bf16 v[0:15], v[212:215], v[184:187], v[0:15]
	s_waitcnt lgkmcnt(0)
	s_waitcnt vmcnt(8)
	s_barrier
	s_waitcnt lgkmcnt(0)
	v_mfma_f32_32x32x16_bf16 v[112:127], v[216:219], v[188:191], v[112:127]
	ds_read_b128 v[208:211], v229
	ds_read_b128 v[172:175], v227
	v_mfma_f32_32x32x16_bf16 v[96:111], v[220:223], v[188:191], v[96:111]
	ds_read_b128 v[212:215], v229 offset:2048
	ds_read_b128 v[176:179], v227 offset:2048
	v_mfma_f32_32x32x16_bf16 v[80:95], v[216:219], v[192:195], v[80:95]
	ds_read_b128 v[180:183], v227 offset:4096
	ds_read_b128 v[184:187], v227 offset:6144
	v_mfma_f32_32x32x16_bf16 v[64:79], v[220:223], v[192:195], v[64:79]
	v_mfma_f32_32x32x16_bf16 v[48:63], v[216:219], v[200:203], v[48:63]
	v_mfma_f32_32x32x16_bf16 v[32:47], v[220:223], v[200:203], v[32:47]
	v_mfma_f32_32x32x16_bf16 v[16:31], v[216:219], v[204:207], v[16:31]
	v_mfma_f32_32x32x16_bf16 v[0:15], v[220:223], v[204:207], v[0:15]
	s_waitcnt lgkmcnt(0)
	v_mfma_f32_32x32x16_bf16 v[112:127], v[208:211], v[172:175], v[112:127]
	ds_read_b128 v[216:219], v230
	ds_read_b128 v[188:191], v228
	v_mfma_f32_32x32x16_bf16 v[96:111], v[212:215], v[172:175], v[96:111]
	ds_read_b128 v[220:223], v230 offset:2048
	ds_read_b128 v[192:195], v228 offset:2048
	v_mfma_f32_32x32x16_bf16 v[80:95], v[208:211], v[176:179], v[80:95]
	ds_read_b128 v[200:203], v228 offset:4096
	ds_read_b128 v[204:207], v228 offset:6144
	v_mfma_f32_32x32x16_bf16 v[64:79], v[212:215], v[176:179], v[64:79]
	v_mfma_f32_32x32x16_bf16 v[48:63], v[208:211], v[180:183], v[48:63]
	v_mfma_f32_32x32x16_bf16 v[32:47], v[212:215], v[180:183], v[32:47]
	v_mfma_f32_32x32x16_bf16 v[16:31], v[208:211], v[184:187], v[16:31]
	v_mfma_f32_32x32x16_bf16 v[0:15], v[212:215], v[184:187], v[0:15]
	s_waitcnt lgkmcnt(0)
	s_waitcnt vmcnt(4)
	s_barrier
	s_waitcnt lgkmcnt(0)
	v_mfma_f32_32x32x16_bf16 v[112:127], v[216:219], v[188:191], v[112:127]
	ds_read_b128 v[208:211], v197
	ds_read_b128 v[172:175], v132
	v_mfma_f32_32x32x16_bf16 v[96:111], v[220:223], v[188:191], v[96:111]
	ds_read_b128 v[212:215], v197 offset:2048
	ds_read_b128 v[176:179], v132 offset:2048
	v_mfma_f32_32x32x16_bf16 v[80:95], v[216:219], v[192:195], v[80:95]
	ds_read_b128 v[180:183], v132 offset:4096
	ds_read_b128 v[184:187], v132 offset:6144
	v_mfma_f32_32x32x16_bf16 v[64:79], v[220:223], v[192:195], v[64:79]
	v_mfma_f32_32x32x16_bf16 v[48:63], v[216:219], v[200:203], v[48:63]
	v_mfma_f32_32x32x16_bf16 v[32:47], v[220:223], v[200:203], v[32:47]
	v_mfma_f32_32x32x16_bf16 v[16:31], v[216:219], v[204:207], v[16:31]
	v_mfma_f32_32x32x16_bf16 v[0:15], v[220:223], v[204:207], v[0:15]
	s_waitcnt lgkmcnt(0)
	v_mfma_f32_32x32x16_bf16 v[112:127], v[208:211], v[172:175], v[112:127]
	ds_read_b128 v[216:219], v198
	ds_read_b128 v[188:191], v171
	v_mfma_f32_32x32x16_bf16 v[96:111], v[212:215], v[172:175], v[96:111]
	ds_read_b128 v[220:223], v198 offset:2048
	ds_read_b128 v[192:195], v171 offset:2048
	v_mfma_f32_32x32x16_bf16 v[80:95], v[208:211], v[176:179], v[80:95]
	ds_read_b128 v[200:203], v171 offset:4096
	ds_read_b128 v[204:207], v171 offset:6144
	v_mfma_f32_32x32x16_bf16 v[64:79], v[212:215], v[176:179], v[64:79]
	v_mfma_f32_32x32x16_bf16 v[48:63], v[208:211], v[180:183], v[48:63]
	v_mfma_f32_32x32x16_bf16 v[32:47], v[212:215], v[180:183], v[32:47]
	v_mfma_f32_32x32x16_bf16 v[16:31], v[208:211], v[184:187], v[16:31]
	v_mfma_f32_32x32x16_bf16 v[0:15], v[212:215], v[184:187], v[0:15]
	s_waitcnt lgkmcnt(0)
	s_waitcnt vmcnt(0)
	s_barrier
; DI unsigned pack2(float a, float b) { f2_t f = {a, b}; bf2_t r = __builtin_convertvector(f, bf2_t); return __builtin_bit_cast(unsigned, r); }
; template <class AL, class BL, class EP>
; DI void gemm_tile256(AL al, BL bl, EP ep, int K, char* smem) {
;     ...
;   if constexpr (EP::kBf16) {
;     bf16_t* sCb = (bf16_t*)smem;
; #pragma unroll
;     for (int i = 0; i < 4; ++i)
; #pragma unroll
;       for (int j = 0; j < 2; ++j)
; #pragma unroll
;         for (int g = 0; g < 4; ++g) {
;           u32x2 v = {pack2(acc[i][j][4 * g], acc[i][j][4 * g + 1]), pack2(acc[i][j][4 * g + 2], acc[i][j][4 * g + 3])};
;           *(u32x2*)(sCb + (128 * wm + 32 * i + r) * BLD + 64 * wn + 32 * j + 8 * g + 4 * h) = v;
;         }
;     __syncthreads();
	s_waitcnt lgkmcnt(0)
	v_mfma_f32_32x32x16_bf16 v[112:127], v[216:219], v[188:191], v[112:127]
	ds_read_b128 v[208:211], v197 offset:32768
	ds_read_b128 v[172:175], v132 offset:32768
	v_mfma_f32_32x32x16_bf16 v[96:111], v[220:223], v[188:191], v[96:111]
	ds_read_b128 v[212:215], v197 offset:34816
	ds_read_b128 v[176:179], v132 offset:34816
	v_mfma_f32_32x32x16_bf16 v[80:95], v[216:219], v[192:195], v[80:95]
	ds_read_b128 v[180:183], v132 offset:36864
	ds_read_b128 v[184:187], v132 offset:38912
	v_mfma_f32_32x32x16_bf16 v[64:79], v[220:223], v[192:195], v[64:79]
	v_mfma_f32_32x32x16_bf16 v[48:63], v[216:219], v[200:203], v[48:63]
	v_mfma_f32_32x32x16_bf16 v[32:47], v[220:223], v[200:203], v[32:47]
	v_mfma_f32_32x32x16_bf16 v[16:31], v[216:219], v[204:207], v[16:31]
	v_mfma_f32_32x32x16_bf16 v[0:15], v[220:223], v[204:207], v[0:15]
	s_waitcnt lgkmcnt(0)
	v_mfma_f32_32x32x16_bf16 v[112:127], v[208:211], v[172:175], v[112:127]
	ds_read_b128 v[216:219], v198 offset:32768
	ds_read_b128 v[188:191], v171 offset:32768
	v_mfma_f32_32x32x16_bf16 v[96:111], v[212:215], v[172:175], v[96:111]
	ds_read_b128 v[220:223], v198 offset:34816
	ds_read_b128 v[192:195], v171 offset:34816
	v_mfma_f32_32x32x16_bf16 v[80:95], v[208:211], v[176:179], v[80:95]
	ds_read_b128 v[200:203], v171 offset:36864
	ds_read_b128 v[204:207], v171 offset:38912
	v_mfma_f32_32x32x16_bf16 v[64:79], v[212:215], v[176:179], v[64:79]
	v_mfma_f32_32x32x16_bf16 v[48:63], v[208:211], v[180:183], v[48:63]
	v_mfma_f32_32x32x16_bf16 v[32:47], v[212:215], v[180:183], v[32:47]
	v_mfma_f32_32x32x16_bf16 v[16:31], v[208:211], v[184:187], v[16:31]
	v_mfma_f32_32x32x16_bf16 v[0:15], v[212:215], v[184:187], v[0:15]
	s_waitcnt lgkmcnt(0)
	s_waitcnt lgkmcnt(0)
	v_mfma_f32_32x32x16_bf16 v[112:127], v[216:219], v[188:191], v[112:127]
	v_mfma_f32_32x32x16_bf16 v[96:111], v[220:223], v[188:191], v[96:111]
	v_mfma_f32_32x32x16_bf16 v[80:95], v[216:219], v[192:195], v[80:95]
	v_mfma_f32_32x32x16_bf16 v[64:79], v[220:223], v[192:195], v[64:79]
	v_mfma_f32_32x32x16_bf16 v[48:63], v[216:219], v[200:203], v[48:63]
	v_mfma_f32_32x32x16_bf16 v[32:47], v[220:223], v[200:203], v[32:47]
	v_mfma_f32_32x32x16_bf16 v[16:31], v[216:219], v[204:207], v[16:31]
	v_mfma_f32_32x32x16_bf16 v[0:15], v[220:223], v[204:207], v[0:15]
	s_nop 15
	s_nop 3
	v_lshl_or_b32 v128, v128, 7, v170
	s_waitcnt lgkmcnt(4)
	v_mad_u64_u32 v[130:131], s[0:1], v133, s43, v[128:129]
	s_waitcnt lgkmcnt(0)
	s_barrier
	s_nop 8
	v_cvt_pk_bf16_f32 v112, v112, v113
	v_cvt_pk_bf16_f32 v113, v114, v115
	v_cvt_pk_bf16_f32 v114, v116, v117
	v_cvt_pk_bf16_f32 v115, v118, v119
	ds_write2_b64 v130, v[112:113], v[114:115] offset1:2
	v_cvt_pk_bf16_f32 v112, v120, v121
	v_cvt_pk_bf16_f32 v113, v122, v123
	v_cvt_pk_bf16_f32 v114, v124, v125
	s_nop 3
	v_cvt_pk_bf16_f32 v16, v16, v17
	v_cvt_pk_bf16_f32 v17, v18, v19
	v_cvt_pk_bf16_f32 v18, v20, v21
	v_add_u32_e32 v20, 0xc000, v130
	v_cvt_pk_bf16_f32 v19, v22, v23
	v_cvt_pk_bf16_f32 v115, v126, v127
	ds_write2_b64 v20, v[16:17], v[18:19] offset0:192 offset1:194
	v_cvt_pk_bf16_f32 v0, v0, v1
	v_cvt_pk_bf16_f32 v1, v2, v3
	v_cvt_pk_bf16_f32 v2, v4, v5
	v_cvt_pk_bf16_f32 v3, v6, v7
	ds_write2_b64 v20, v[0:1], v[2:3] offset0:200 offset1:202
	v_cvt_pk_bf16_f32 v0, v8, v9
	v_cvt_pk_bf16_f32 v1, v10, v11
	s_nop 3
	v_cvt_pk_bf16_f32 v96, v96, v97
	v_cvt_pk_bf16_f32 v97, v98, v99
	v_cvt_pk_bf16_f32 v98, v100, v101
	v_cvt_pk_bf16_f32 v99, v102, v103
	v_cvt_pk_bf16_f32 v2, v12, v13
	v_cvt_pk_bf16_f32 v3, v14, v15
	ds_write2_b64 v130, v[96:97], v[98:99] offset0:8 offset1:10
	v_cvt_pk_bf16_f32 v80, v80, v81
	v_cvt_pk_bf16_f32 v81, v82, v83
	v_cvt_pk_bf16_f32 v82, v84, v85
	v_cvt_pk_bf16_f32 v83, v86, v87
	v_add_u32_e32 v84, 0x4000, v130
	v_cvt_pk_bf16_f32 v96, v104, v105
	v_cvt_pk_bf16_f32 v97, v106, v107
	s_nop 3
	v_cvt_pk_bf16_f32 v64, v64, v65
	v_cvt_pk_bf16_f32 v65, v66, v67
	v_cvt_pk_bf16_f32 v66, v68, v69
	v_cvt_pk_bf16_f32 v67, v70, v71
	v_cvt_pk_bf16_f32 v98, v108, v109
	v_cvt_pk_bf16_f32 v99, v110, v111
	ds_write2_b64 v84, v[80:81], v[82:83] offset0:64 offset1:66
	v_cvt_pk_bf16_f32 v48, v48, v49
	v_cvt_pk_bf16_f32 v49, v50, v51
	v_cvt_pk_bf16_f32 v50, v52, v53
	v_cvt_pk_bf16_f32 v51, v54, v55
	v_add_u32_e32 v52, 0x8000, v130
	v_cvt_pk_bf16_f32 v80, v88, v89
	v_cvt_pk_bf16_f32 v81, v90, v91
	s_nop 4
	v_cvt_pk_bf16_f32 v32, v32, v33
	v_cvt_pk_bf16_f32 v33, v34, v35
	v_cvt_pk_bf16_f32 v34, v36, v37
	v_cvt_pk_bf16_f32 v35, v38, v39
	v_cvt_pk_bf16_f32 v82, v92, v93
	v_cvt_pk_bf16_f32 v83, v94, v95
	ds_write2_b64 v84, v[64:65], v[66:67] offset0:72 offset1:74
	v_cvt_pk_bf16_f32 v64, v72, v73
	v_cvt_pk_bf16_f32 v65, v74, v75
	v_cvt_pk_bf16_f32 v66, v76, v77
	v_cvt_pk_bf16_f32 v67, v78, v79
	ds_write2_b64 v52, v[48:49], v[50:51] offset0:128 offset1:130
	v_cvt_pk_bf16_f32 v48, v56, v57
	v_cvt_pk_bf16_f32 v49, v58, v59
	v_cvt_pk_bf16_f32 v50, v60, v61
	v_cvt_pk_bf16_f32 v51, v62, v63
	ds_write2_b64 v52, v[32:33], v[34:35] offset0:136 offset1:138
	v_cvt_pk_bf16_f32 v32, v40, v41
	v_cvt_pk_bf16_f32 v33, v42, v43
	v_cvt_pk_bf16_f32 v34, v44, v45
	v_cvt_pk_bf16_f32 v35, v46, v47
	v_cvt_pk_bf16_f32 v16, v24, v25
	v_cvt_pk_bf16_f32 v17, v26, v27
	v_cvt_pk_bf16_f32 v18, v28, v29
	v_cvt_pk_bf16_f32 v19, v30, v31
	ds_write2_b64 v20, v[0:1], v[2:3] offset0:204 offset1:206
	v_mov_b32_e32 v2, v196
	ds_write2_b64 v130, v[112:113], v[114:115] offset0:4 offset1:6
	ds_write2_b64 v130, v[96:97], v[98:99] offset0:12 offset1:14
	ds_write2_b64 v84, v[80:81], v[82:83] offset0:68 offset1:70
	ds_write2_b64 v84, v[64:65], v[66:67] offset0:76 offset1:78
	ds_write2_b64 v52, v[48:49], v[50:51] offset0:132 offset1:134
	ds_write2_b64 v52, v[32:33], v[34:35] offset0:140 offset1:142
	ds_write2_b64 v20, v[16:17], v[18:19] offset0:196 offset1:198
	s_waitcnt lgkmcnt(0)
	s_barrier
; DI int tid512() { int t = threadIdx_x_raw(); asm volatile("" : "+v"(t)); return t; }
;   DI void operator()(const bf16_t* sCb) const {
;     for (int id = tid512(); id < 8192; id += 512) {
;       int row = id >> 5, c8 = (id & 31) * 8, n = n0 + c8;
;       if (n < N) *(u32x4*)(dst + (size_t)(m0 + row) * ld + n) = *(const u32x4*)(sCb + row * BLD + c8);
;     }
;   }
	s_nop 0
	v_cmp_gt_i32_e32 vcc, s44, v2
	s_and_saveexec_b64 s[0:1], vcc
	s_cbranch_execz .LBB0_161
	v_lshlrev_b32_e32 v3, 3, v2
	v_and_b32_e32 v1, 0xf8, v3
	v_or_b32_e32 v0, v1, v169
	v_cmp_gt_i32_e32 vcc, s45, v0
	s_and_saveexec_b64 s[38:39], vcc
	s_cbranch_execz .Lep_done_161
	v_ashrrev_i32_e32 v8, 5, v2
	v_mul_lo_u32 v4, v8, s43
	v_lshl_add_u32 v1, v1, 1, v4
	v_add_u32_e32 v10, 0x10800, v1
	ds_read_b128 v[64:67], v1
	ds_read_b128 v[68:71], v1 offset:8448
	ds_read_b128 v[72:75], v1 offset:16896
	ds_read_b128 v[76:79], v1 offset:25344
	ds_read_b128 v[80:83], v1 offset:33792
	ds_read_b128 v[84:87], v1 offset:42240
	ds_read_b128 v[88:91], v1 offset:50688
	ds_read_b128 v[92:95], v1 offset:59136
	ds_read_b128 v[96:99], v10
	ds_read_b128 v[100:103], v10 offset:8448
	ds_read_b128 v[104:107], v10 offset:16896
	ds_read_b128 v[108:111], v10 offset:25344
	ds_read_b128 v[112:115], v10 offset:33792
	ds_read_b128 v[116:119], v10 offset:42240
	ds_read_b128 v[120:123], v10 offset:50688
	ds_read_b128 v[124:127], v10 offset:59136
	v_and_b32_e32 v1, 0xf8, v3
	v_or_b32_e32 v0, v1, v169
	v_ashrrev_i32_e32 v8, 5, v2
	v_add_u32_e32 v1, v8, v168
	v_mov_b64_e32 v[8:9], s[72:73]
	v_mad_i64_i32 v[8:9], s[48:49], v1, s46, v[8:9]
	v_ashrrev_i32_e32 v1, 31, v0
	v_lshl_add_u64 v[0:1], v[0:1], 1, v[8:9]
	s_waitcnt lgkmcnt(15)
	global_store_dwordx4 v[0:1], v[64:67], off
	v_add_u32_e32 v2, 0x200, v2
	v_and_b32_e32 v1, 0xf8, v3
	v_or_b32_e32 v0, v1, v169
	v_ashrrev_i32_e32 v8, 5, v2
	v_add_u32_e32 v1, v8, v168
	v_mov_b64_e32 v[8:9], s[72:73]
	v_mad_i64_i32 v[8:9], s[48:49], v1, s46, v[8:9]
	v_ashrrev_i32_e32 v1, 31, v0
	v_lshl_add_u64 v[0:1], v[0:1], 1, v[8:9]
	s_waitcnt lgkmcnt(14)
	global_store_dwordx4 v[0:1], v[68:71], off
	v_add_u32_e32 v2, 0x200, v2
	v_and_b32_e32 v1, 0xf8, v3
	v_or_b32_e32 v0, v1, v169
	v_ashrrev_i32_e32 v8, 5, v2
	v_add_u32_e32 v1, v8, v168
	v_mov_b64_e32 v[8:9], s[72:73]
	v_mad_i64_i32 v[8:9], s[48:49], v1, s46, v[8:9]
	v_ashrrev_i32_e32 v1, 31, v0
	v_lshl_add_u64 v[0:1], v[0:1], 1, v[8:9]
	s_waitcnt lgkmcnt(13)
	global_store_dwordx4 v[0:1], v[72:75], off
	v_add_u32_e32 v2, 0x200, v2
	v_and_b32_e32 v1, 0xf8, v3
	v_or_b32_e32 v0, v1, v169
	v_ashrrev_i32_e32 v8, 5, v2
	v_add_u32_e32 v1, v8, v168
	v_mov_b64_e32 v[8:9], s[72:73]
	v_mad_i64_i32 v[8:9], s[48:49], v1, s46, v[8:9]
	v_ashrrev_i32_e32 v1, 31, v0
	v_lshl_add_u64 v[0:1], v[0:1], 1, v[8:9]
	s_waitcnt lgkmcnt(12)
	global_store_dwordx4 v[0:1], v[76:79], off
	v_add_u32_e32 v2, 0x200, v2
	v_and_b32_e32 v1, 0xf8, v3
	v_or_b32_e32 v0, v1, v169
	v_ashrrev_i32_e32 v8, 5, v2
	v_add_u32_e32 v1, v8, v168
	v_mov_b64_e32 v[8:9], s[72:73]
	v_mad_i64_i32 v[8:9], s[48:49], v1, s46, v[8:9]
	v_ashrrev_i32_e32 v1, 31, v0
	v_lshl_add_u64 v[0:1], v[0:1], 1, v[8:9]
	s_waitcnt lgkmcnt(11)
	global_store_dwordx4 v[0:1], v[80:83], off
	v_add_u32_e32 v2, 0x200, v2
	v_and_b32_e32 v1, 0xf8, v3
	v_or_b32_e32 v0, v1, v169
	v_ashrrev_i32_e32 v8, 5, v2
	v_add_u32_e32 v1, v8, v168
	v_mov_b64_e32 v[8:9], s[72:73]
	v_mad_i64_i32 v[8:9], s[48:49], v1, s46, v[8:9]
	v_ashrrev_i32_e32 v1, 31, v0
	v_lshl_add_u64 v[0:1], v[0:1], 1, v[8:9]
	s_waitcnt lgkmcnt(10)
	global_store_dwordx4 v[0:1], v[84:87], off
	v_add_u32_e32 v2, 0x200, v2
	v_and_b32_e32 v1, 0xf8, v3
	v_or_b32_e32 v0, v1, v169
	v_ashrrev_i32_e32 v8, 5, v2
	v_add_u32_e32 v1, v8, v168
	v_mov_b64_e32 v[8:9], s[72:73]
	v_mad_i64_i32 v[8:9], s[48:49], v1, s46, v[8:9]
	v_ashrrev_i32_e32 v1, 31, v0
	v_lshl_add_u64 v[0:1], v[0:1], 1, v[8:9]
	s_waitcnt lgkmcnt(9)
	global_store_dwordx4 v[0:1], v[88:91], off
	v_add_u32_e32 v2, 0x200, v2
	v_and_b32_e32 v1, 0xf8, v3
	v_or_b32_e32 v0, v1, v169
	v_ashrrev_i32_e32 v8, 5, v2
	v_add_u32_e32 v1, v8, v168
	v_mov_b64_e32 v[8:9], s[72:73]
	v_mad_i64_i32 v[8:9], s[48:49], v1, s46, v[8:9]
	v_ashrrev_i32_e32 v1, 31, v0
	v_lshl_add_u64 v[0:1], v[0:1], 1, v[8:9]
	s_waitcnt lgkmcnt(8)
	global_store_dwordx4 v[0:1], v[92:95], off
	v_add_u32_e32 v2, 0x200, v2
	v_and_b32_e32 v1, 0xf8, v3
	v_or_b32_e32 v0, v1, v169
	v_ashrrev_i32_e32 v8, 5, v2
	v_add_u32_e32 v1, v8, v168
	v_mov_b64_e32 v[8:9], s[72:73]
	v_mad_i64_i32 v[8:9], s[48:49], v1, s46, v[8:9]
	v_ashrrev_i32_e32 v1, 31, v0
	v_lshl_add_u64 v[0:1], v[0:1], 1, v[8:9]
	s_waitcnt lgkmcnt(7)
	global_store_dwordx4 v[0:1], v[96:99], off
	v_add_u32_e32 v2, 0x200, v2
	v_and_b32_e32 v1, 0xf8, v3
	v_or_b32_e32 v0, v1, v169
	v_ashrrev_i32_e32 v8, 5, v2
	v_add_u32_e32 v1, v8, v168
	v_mov_b64_e32 v[8:9], s[72:73]
	v_mad_i64_i32 v[8:9], s[48:49], v1, s46, v[8:9]
	v_ashrrev_i32_e32 v1, 31, v0
	v_lshl_add_u64 v[0:1], v[0:1], 1, v[8:9]
	s_waitcnt lgkmcnt(6)
	global_store_dwordx4 v[0:1], v[100:103], off
	v_add_u32_e32 v2, 0x200, v2
	v_and_b32_e32 v1, 0xf8, v3
	v_or_b32_e32 v0, v1, v169
	v_ashrrev_i32_e32 v8, 5, v2
	v_add_u32_e32 v1, v8, v168
	v_mov_b64_e32 v[8:9], s[72:73]
	v_mad_i64_i32 v[8:9], s[48:49], v1, s46, v[8:9]
	v_ashrrev_i32_e32 v1, 31, v0
	v_lshl_add_u64 v[0:1], v[0:1], 1, v[8:9]
	s_waitcnt lgkmcnt(5)
	global_store_dwordx4 v[0:1], v[104:107], off
	v_add_u32_e32 v2, 0x200, v2
	v_and_b32_e32 v1, 0xf8, v3
	v_or_b32_e32 v0, v1, v169
	v_ashrrev_i32_e32 v8, 5, v2
	v_add_u32_e32 v1, v8, v168
	v_mov_b64_e32 v[8:9], s[72:73]
	v_mad_i64_i32 v[8:9], s[48:49], v1, s46, v[8:9]
	v_ashrrev_i32_e32 v1, 31, v0
	v_lshl_add_u64 v[0:1], v[0:1], 1, v[8:9]
	s_waitcnt lgkmcnt(4)
	global_store_dwordx4 v[0:1], v[108:111], off
	v_add_u32_e32 v2, 0x200, v2
	v_and_b32_e32 v1, 0xf8, v3
	v_or_b32_e32 v0, v1, v169
	v_ashrrev_i32_e32 v8, 5, v2
	v_add_u32_e32 v1, v8, v168
	v_mov_b64_e32 v[8:9], s[72:73]
	v_mad_i64_i32 v[8:9], s[48:49], v1, s46, v[8:9]
	v_ashrrev_i32_e32 v1, 31, v0
	v_lshl_add_u64 v[0:1], v[0:1], 1, v[8:9]
	s_waitcnt lgkmcnt(3)
	global_store_dwordx4 v[0:1], v[112:115], off
	v_add_u32_e32 v2, 0x200, v2
	v_and_b32_e32 v1, 0xf8, v3
	v_or_b32_e32 v0, v1, v169
	v_ashrrev_i32_e32 v8, 5, v2
	v_add_u32_e32 v1, v8, v168
	v_mov_b64_e32 v[8:9], s[72:73]
	v_mad_i64_i32 v[8:9], s[48:49], v1, s46, v[8:9]
	v_ashrrev_i32_e32 v1, 31, v0
	v_lshl_add_u64 v[0:1], v[0:1], 1, v[8:9]
	s_waitcnt lgkmcnt(2)
	global_store_dwordx4 v[0:1], v[116:119], off
	v_add_u32_e32 v2, 0x200, v2
	v_and_b32_e32 v1, 0xf8, v3
	v_or_b32_e32 v0, v1, v169
	v_ashrrev_i32_e32 v8, 5, v2
	v_add_u32_e32 v1, v8, v168
	v_mov_b64_e32 v[8:9], s[72:73]
	v_mad_i64_i32 v[8:9], s[48:49], v1, s46, v[8:9]
	v_ashrrev_i32_e32 v1, 31, v0
	v_lshl_add_u64 v[0:1], v[0:1], 1, v[8:9]
	s_waitcnt lgkmcnt(1)
	global_store_dwordx4 v[0:1], v[120:123], off
	v_add_u32_e32 v2, 0x200, v2
	v_and_b32_e32 v1, 0xf8, v3
	v_or_b32_e32 v0, v1, v169
	v_ashrrev_i32_e32 v8, 5, v2
	v_add_u32_e32 v1, v8, v168
	v_mov_b64_e32 v[8:9], s[72:73]
	v_mad_i64_i32 v[8:9], s[48:49], v1, s46, v[8:9]
	v_ashrrev_i32_e32 v1, 31, v0
	v_lshl_add_u64 v[0:1], v[0:1], 1, v[8:9]
	s_waitcnt lgkmcnt(0)
	global_store_dwordx4 v[0:1], v[124:127], off
.Lep_done_161:
	s_or_b64 exec, exec, s[38:39]
	s_branch .LBB0_161

; #define G_LOADA(kt_) { _Pragma("unroll") for (int i = 0; i < 4; ++i) ra[i] = al(lrow + 64 * i, (kt_) * 64 + lck * 8); }
; #define G_LOADB(kt_) { _Pragma("unroll") for (int i = 0; i < 4; ++i) rb[i] = bl(lrow + 64 * i, (kt_) * 64 + lck * 8); }
; #define G_STOREA(buf_) { bf16_t* nA = sA + (buf_) * 256 * GLD; _Pragma("unroll") for (int i = 0; i < 4; ++i) *(u32x4*)(nA + (lrow + 64 * i) * GLD + lck * 8) = ra[i]; }
; #define G_STOREB(buf_) { bf16_t* nB = sB + (buf_) * 256 * GLD; _Pragma("unroll") for (int i = 0; i < 4; ++i) *(u32x4*)(nB + (lrow + 64 * i) * GLD + lck * 8) = rb[i]; }
; template <class AL, class BL, class EP>
; DI void gemm_tile256(AL al, BL bl, EP ep, int K, char* smem) {
;     ...
;   G_LOADA(0); G_LOADB(0);
;   __syncthreads();
;   G_STOREA(0); G_STOREB(0);
;   if (KT > 1) G_LOADB(1);
;   __syncthreads();
;   for (int kt = 0; kt < KT; kt += 2) {
;     G_STEP(0, kt);
;     if (kt + 1 >= KT) break;
;     G_STEP(1, kt + 1);
;   }
.Lgk_ph4_loop:
	s_waitcnt lgkmcnt(0)
	v_mfma_f32_32x32x16_bf16 v[112:127], v[184:187], v[152:155], v[112:127]
	ds_read_b128 v[192:195], v199
	ds_read_b128 v[168:171], v151
	v_mfma_f32_32x32x16_bf16 v[96:111], v[188:191], v[152:155], v[96:111]
	ds_read_b128 v[200:203], v199 offset:2048
	ds_read_b128 v[172:175], v151 offset:2048
	v_mfma_f32_32x32x16_bf16 v[80:95], v[184:187], v[156:159], v[80:95]
	ds_read_b128 v[176:179], v151 offset:4096
	ds_read_b128 v[180:183], v151 offset:6144
	v_mfma_f32_32x32x16_bf16 v[64:79], v[188:191], v[156:159], v[64:79]
	s_add_u32 m0, s19, 0x22000
	s_nop 0
	global_load_lds_dwordx4 v[214:215], off
	v_lshl_add_u64 v[214:215], v[214:215], 0, s[4:5]
	v_mfma_f32_32x32x16_bf16 v[48:63], v[184:187], v[160:163], v[48:63]
	v_mfma_f32_32x32x16_bf16 v[32:47], v[188:191], v[160:163], v[32:47]
	v_mfma_f32_32x32x16_bf16 v[16:31], v[184:187], v[164:167], v[16:31]
	v_mfma_f32_32x32x16_bf16 v[0:15], v[188:191], v[164:167], v[0:15]
	s_add_u32 m0, s19, 0x26000
	s_nop 0
	global_load_lds_dwordx4 v[218:219], off
	v_lshl_add_u64 v[218:219], v[218:219], 0, s[4:5]
	s_waitcnt lgkmcnt(0)
	s_waitcnt vmcnt(12)
	s_barrier
	s_waitcnt lgkmcnt(0)
	v_mfma_f32_32x32x16_bf16 v[112:127], v[192:195], v[168:171], v[112:127]
	ds_read_b128 v[184:187], v198 offset:32768
	ds_read_b128 v[152:155], v132 offset:32768
	v_mfma_f32_32x32x16_bf16 v[96:111], v[200:203], v[168:171], v[96:111]
	ds_read_b128 v[188:191], v198 offset:34816
	ds_read_b128 v[156:159], v132 offset:34816
	v_mfma_f32_32x32x16_bf16 v[80:95], v[192:195], v[172:175], v[80:95]
	ds_read_b128 v[160:163], v132 offset:36864
	ds_read_b128 v[164:167], v132 offset:38912
	v_mfma_f32_32x32x16_bf16 v[64:79], v[200:203], v[172:175], v[64:79]
	s_add_u32 m0, s19, 0x0
	s_nop 0
	global_load_lds_dwordx4 v[212:213], off
	v_lshl_add_u64 v[212:213], v[212:213], 0, s[4:5]
	v_mfma_f32_32x32x16_bf16 v[48:63], v[192:195], v[176:179], v[48:63]
	v_mfma_f32_32x32x16_bf16 v[32:47], v[200:203], v[176:179], v[32:47]
	v_mfma_f32_32x32x16_bf16 v[16:31], v[192:195], v[180:183], v[16:31]
	v_mfma_f32_32x32x16_bf16 v[0:15], v[200:203], v[180:183], v[0:15]
	s_add_u32 m0, s19, 0x4000
	s_nop 0
	global_load_lds_dwordx4 v[216:217], off
	v_lshl_add_u64 v[216:217], v[216:217], 0, s[4:5]
	s_waitcnt lgkmcnt(0)
	v_mfma_f32_32x32x16_bf16 v[112:127], v[184:187], v[152:155], v[112:127]
	ds_read_b128 v[192:195], v199 offset:32768
	ds_read_b128 v[168:171], v151 offset:32768
	v_mfma_f32_32x32x16_bf16 v[96:111], v[188:191], v[152:155], v[96:111]
	ds_read_b128 v[200:203], v199 offset:34816
	ds_read_b128 v[172:175], v151 offset:34816
	v_mfma_f32_32x32x16_bf16 v[80:95], v[184:187], v[156:159], v[80:95]
	ds_read_b128 v[176:179], v151 offset:36864
	ds_read_b128 v[180:183], v151 offset:38912
	v_mfma_f32_32x32x16_bf16 v[64:79], v[188:191], v[156:159], v[64:79]
	s_add_u32 m0, s19, 0x2000
	s_nop 0
	global_load_lds_dwordx4 v[214:215], off
	v_lshl_add_u64 v[214:215], v[214:215], 0, s[4:5]
	v_mfma_f32_32x32x16_bf16 v[48:63], v[184:187], v[160:163], v[48:63]
	v_mfma_f32_32x32x16_bf16 v[32:47], v[188:191], v[160:163], v[32:47]
	v_mfma_f32_32x32x16_bf16 v[16:31], v[184:187], v[164:167], v[16:31]
	v_mfma_f32_32x32x16_bf16 v[0:15], v[188:191], v[164:167], v[0:15]
	s_add_u32 m0, s19, 0x6000
	s_nop 0
	global_load_lds_dwordx4 v[218:219], off
	v_lshl_add_u64 v[218:219], v[218:219], 0, s[4:5]
	s_waitcnt lgkmcnt(0)
	s_waitcnt vmcnt(12)
	s_barrier
	s_waitcnt lgkmcnt(0)
	v_mfma_f32_32x32x16_bf16 v[112:127], v[192:195], v[168:171], v[112:127]
	ds_read_b128 v[184:187], v206
	ds_read_b128 v[152:155], v204
	v_mfma_f32_32x32x16_bf16 v[96:111], v[200:203], v[168:171], v[96:111]
	ds_read_b128 v[188:191], v206 offset:2048
	ds_read_b128 v[156:159], v204 offset:2048
	v_mfma_f32_32x32x16_bf16 v[80:95], v[192:195], v[172:175], v[80:95]
	ds_read_b128 v[160:163], v204 offset:4096
	ds_read_b128 v[164:167], v204 offset:6144
	v_mfma_f32_32x32x16_bf16 v[64:79], v[200:203], v[172:175], v[64:79]
	s_add_u32 m0, s19, 0x8000
	s_nop 0
	global_load_lds_dwordx4 v[212:213], off
	v_lshl_add_u64 v[212:213], v[212:213], 0, s[4:5]
	v_mfma_f32_32x32x16_bf16 v[48:63], v[192:195], v[176:179], v[48:63]
	v_mfma_f32_32x32x16_bf16 v[32:47], v[200:203], v[176:179], v[32:47]
	v_mfma_f32_32x32x16_bf16 v[16:31], v[192:195], v[180:183], v[16:31]
	v_mfma_f32_32x32x16_bf16 v[0:15], v[200:203], v[180:183], v[0:15]
	s_add_u32 m0, s19, 0xc000
	s_nop 0
	global_load_lds_dwordx4 v[216:217], off
	v_lshl_add_u64 v[216:217], v[216:217], 0, s[4:5]
	s_waitcnt lgkmcnt(0)
	v_mfma_f32_32x32x16_bf16 v[112:127], v[184:187], v[152:155], v[112:127]
	ds_read_b128 v[192:195], v207
	ds_read_b128 v[168:171], v205
	v_mfma_f32_32x32x16_bf16 v[96:111], v[188:191], v[152:155], v[96:111]
	ds_read_b128 v[200:203], v207 offset:2048
	ds_read_b128 v[172:175], v205 offset:2048
	v_mfma_f32_32x32x16_bf16 v[80:95], v[184:187], v[156:159], v[80:95]
	ds_read_b128 v[176:179], v205 offset:4096
	ds_read_b128 v[180:183], v205 offset:6144
	v_mfma_f32_32x32x16_bf16 v[64:79], v[188:191], v[156:159], v[64:79]
	s_add_u32 m0, s19, 0xa000
	s_nop 0
	global_load_lds_dwordx4 v[214:215], off
	v_lshl_add_u64 v[214:215], v[214:215], 0, s[4:5]
	v_mfma_f32_32x32x16_bf16 v[48:63], v[184:187], v[160:163], v[48:63]
	v_mfma_f32_32x32x16_bf16 v[32:47], v[188:191], v[160:163], v[32:47]
	v_mfma_f32_32x32x16_bf16 v[16:31], v[184:187], v[164:167], v[16:31]
	v_mfma_f32_32x32x16_bf16 v[0:15], v[188:191], v[164:167], v[0:15]
	s_add_u32 m0, s19, 0xe000
	s_nop 0
	global_load_lds_dwordx4 v[218:219], off
	v_lshl_add_u64 v[218:219], v[218:219], 0, s[4:5]
	s_waitcnt lgkmcnt(0)
	s_waitcnt vmcnt(12)
	s_barrier
; #define G_LOADA(kt_) { _Pragma("unroll") for (int i = 0; i < 4; ++i) ra[i] = al(lrow + 64 * i, (kt_) * 64 + lck * 8); }
; #define G_LOADB(kt_) { _Pragma("unroll") for (int i = 0; i < 4; ++i) rb[i] = bl(lrow + 64 * i, (kt_) * 64 + lck * 8); }
; #define G_STOREA(buf_) { bf16_t* nA = sA + (buf_) * 256 * GLD; _Pragma("unroll") for (int i = 0; i < 4; ++i) *(u32x4*)(nA + (lrow + 64 * i) * GLD + lck * 8) = ra[i]; }
; #define G_STOREB(buf_) { bf16_t* nB = sB + (buf_) * 256 * GLD; _Pragma("unroll") for (int i = 0; i < 4; ++i) *(u32x4*)(nB + (lrow + 64 * i) * GLD + lck * 8) = rb[i]; }
; template <class AL, class BL, class EP>
; DI void gemm_tile256(AL al, BL bl, EP ep, int K, char* smem) {
;     ...
;   G_LOADA(0); G_LOADB(0);
;   __syncthreads();
;   G_STOREA(0); G_STOREB(0);
;   if (KT > 1) G_LOADB(1);
;   __syncthreads();
;   for (int kt = 0; kt < KT; kt += 2) {
;     G_STEP(0, kt);
;     if (kt + 1 >= KT) break;
;     G_STEP(1, kt + 1);
;   }
	s_waitcnt lgkmcnt(0)
	v_mfma_f32_32x32x16_bf16 v[112:127], v[192:195], v[168:171], v[112:127]
	ds_read_b128 v[184:187], v206 offset:32768
	ds_read_b128 v[152:155], v204 offset:32768
	v_mfma_f32_32x32x16_bf16 v[96:111], v[200:203], v[168:171], v[96:111]
	ds_read_b128 v[188:191], v206 offset:34816
	ds_read_b128 v[156:159], v204 offset:34816
	v_mfma_f32_32x32x16_bf16 v[80:95], v[192:195], v[172:175], v[80:95]
	ds_read_b128 v[160:163], v204 offset:36864
	ds_read_b128 v[164:167], v204 offset:38912
	v_mfma_f32_32x32x16_bf16 v[64:79], v[200:203], v[172:175], v[64:79]
	s_add_u32 m0, s19, 0x10000
	s_nop 0
	global_load_lds_dwordx4 v[212:213], off
	v_lshl_add_u64 v[212:213], v[212:213], 0, s[4:5]
	v_mfma_f32_32x32x16_bf16 v[48:63], v[192:195], v[176:179], v[48:63]
	v_mfma_f32_32x32x16_bf16 v[32:47], v[200:203], v[176:179], v[32:47]
	v_mfma_f32_32x32x16_bf16 v[16:31], v[192:195], v[180:183], v[16:31]
	v_mfma_f32_32x32x16_bf16 v[0:15], v[200:203], v[180:183], v[0:15]
	s_add_u32 m0, s19, 0x14000
	s_nop 0
	global_load_lds_dwordx4 v[216:217], off
	v_lshl_add_u64 v[216:217], v[216:217], 0, s[4:5]
	s_waitcnt lgkmcnt(0)
	v_mfma_f32_32x32x16_bf16 v[112:127], v[184:187], v[152:155], v[112:127]
	ds_read_b128 v[192:195], v207 offset:32768
	ds_read_b128 v[168:171], v205 offset:32768
	v_mfma_f32_32x32x16_bf16 v[96:111], v[188:191], v[152:155], v[96:111]
	ds_read_b128 v[200:203], v207 offset:34816
	ds_read_b128 v[172:175], v205 offset:34816
	v_mfma_f32_32x32x16_bf16 v[80:95], v[184:187], v[156:159], v[80:95]
	ds_read_b128 v[176:179], v205 offset:36864
	ds_read_b128 v[180:183], v205 offset:38912
	v_mfma_f32_32x32x16_bf16 v[64:79], v[188:191], v[156:159], v[64:79]
	s_add_u32 m0, s19, 0x12000
	s_nop 0
	global_load_lds_dwordx4 v[214:215], off
	v_lshl_add_u64 v[214:215], v[214:215], 0, s[4:5]
	v_mfma_f32_32x32x16_bf16 v[48:63], v[184:187], v[160:163], v[48:63]
	v_mfma_f32_32x32x16_bf16 v[32:47], v[188:191], v[160:163], v[32:47]
	v_mfma_f32_32x32x16_bf16 v[16:31], v[184:187], v[164:167], v[16:31]
	v_mfma_f32_32x32x16_bf16 v[0:15], v[188:191], v[164:167], v[0:15]
	s_add_u32 m0, s19, 0x16000
	s_nop 0
	global_load_lds_dwordx4 v[218:219], off
	v_lshl_add_u64 v[218:219], v[218:219], 0, s[4:5]
	s_waitcnt lgkmcnt(0)
	s_waitcnt vmcnt(12)
	s_barrier
	s_waitcnt lgkmcnt(0)
	v_mfma_f32_32x32x16_bf16 v[112:127], v[192:195], v[168:171], v[112:127]
	ds_read_b128 v[184:187], v210
	ds_read_b128 v[152:155], v208
	v_mfma_f32_32x32x16_bf16 v[96:111], v[200:203], v[168:171], v[96:111]
	ds_read_b128 v[188:191], v210 offset:2048
	ds_read_b128 v[156:159], v208 offset:2048
	v_mfma_f32_32x32x16_bf16 v[80:95], v[192:195], v[172:175], v[80:95]
	ds_read_b128 v[160:163], v208 offset:4096
	ds_read_b128 v[164:167], v208 offset:6144
	v_mfma_f32_32x32x16_bf16 v[64:79], v[200:203], v[172:175], v[64:79]
	s_add_u32 m0, s19, 0x18000
	s_nop 0
	global_load_lds_dwordx4 v[212:213], off
	v_lshl_add_u64 v[212:213], v[212:213], 0, s[4:5]
	v_mfma_f32_32x32x16_bf16 v[48:63], v[192:195], v[176:179], v[48:63]
	v_mfma_f32_32x32x16_bf16 v[32:47], v[200:203], v[176:179], v[32:47]
	v_mfma_f32_32x32x16_bf16 v[16:31], v[192:195], v[180:183], v[16:31]
	v_mfma_f32_32x32x16_bf16 v[0:15], v[200:203], v[180:183], v[0:15]
	s_add_u32 m0, s19, 0x1c000
	s_nop 0
	global_load_lds_dwordx4 v[216:217], off
	v_lshl_add_u64 v[216:217], v[216:217], 0, s[4:5]
	s_waitcnt lgkmcnt(0)
	v_mfma_f32_32x32x16_bf16 v[112:127], v[184:187], v[152:155], v[112:127]
	ds_read_b128 v[192:195], v211
	ds_read_b128 v[168:171], v209
	v_mfma_f32_32x32x16_bf16 v[96:111], v[188:191], v[152:155], v[96:111]
	ds_read_b128 v[200:203], v211 offset:2048
	ds_read_b128 v[172:175], v209 offset:2048
	v_mfma_f32_32x32x16_bf16 v[80:95], v[184:187], v[156:159], v[80:95]
	ds_read_b128 v[176:179], v209 offset:4096
	ds_read_b128 v[180:183], v209 offset:6144
	v_mfma_f32_32x32x16_bf16 v[64:79], v[188:191], v[156:159], v[64:79]
	s_add_u32 m0, s19, 0x1a000
	s_nop 0
	global_load_lds_dwordx4 v[214:215], off
	v_lshl_add_u64 v[214:215], v[214:215], 0, s[4:5]
	v_mfma_f32_32x32x16_bf16 v[48:63], v[184:187], v[160:163], v[48:63]
	v_mfma_f32_32x32x16_bf16 v[32:47], v[188:191], v[160:163], v[32:47]
	v_mfma_f32_32x32x16_bf16 v[16:31], v[184:187], v[164:167], v[16:31]
	v_mfma_f32_32x32x16_bf16 v[0:15], v[188:191], v[164:167], v[0:15]
	s_add_u32 m0, s19, 0x1e000
	s_nop 0
	global_load_lds_dwordx4 v[218:219], off
	v_lshl_add_u64 v[218:219], v[218:219], 0, s[4:5]
	s_waitcnt lgkmcnt(0)
	s_waitcnt vmcnt(12)
	s_barrier
	s_waitcnt lgkmcnt(0)
	v_mfma_f32_32x32x16_bf16 v[112:127], v[192:195], v[168:171], v[112:127]
	ds_read_b128 v[184:187], v198
	ds_read_b128 v[152:155], v132
	v_mfma_f32_32x32x16_bf16 v[96:111], v[200:203], v[168:171], v[96:111]
	ds_read_b128 v[188:191], v198 offset:2048
	ds_read_b128 v[156:159], v132 offset:2048
	v_mfma_f32_32x32x16_bf16 v[80:95], v[192:195], v[172:175], v[80:95]
	ds_read_b128 v[160:163], v132 offset:4096
	ds_read_b128 v[164:167], v132 offset:6144
	v_mfma_f32_32x32x16_bf16 v[64:79], v[200:203], v[172:175], v[64:79]
	s_add_u32 m0, s19, 0x20000
	s_nop 0
	global_load_lds_dwordx4 v[212:213], off
	v_lshl_add_u64 v[212:213], v[212:213], 0, s[4:5]
	v_mfma_f32_32x32x16_bf16 v[48:63], v[192:195], v[176:179], v[48:63]
	v_mfma_f32_32x32x16_bf16 v[32:47], v[200:203], v[176:179], v[32:47]
	v_mfma_f32_32x32x16_bf16 v[16:31], v[192:195], v[180:183], v[16:31]
	v_mfma_f32_32x32x16_bf16 v[0:15], v[200:203], v[180:183], v[0:15]
	s_add_u32 m0, s19, 0x24000
	s_nop 0
	global_load_lds_dwordx4 v[216:217], off
	v_lshl_add_u64 v[216:217], v[216:217], 0, s[4:5]
	s_sub_u32 s23, s23, 1
	s_cmp_lg_u32 s23, 0
	s_cbranch_scc1 .Lgk_ph4_loop
; #define G_LOADA(kt_) { _Pragma("unroll") for (int i = 0; i < 4; ++i) ra[i] = al(lrow + 64 * i, (kt_) * 64 + lck * 8); }
; #define G_LOADB(kt_) { _Pragma("unroll") for (int i = 0; i < 4; ++i) rb[i] = bl(lrow + 64 * i, (kt_) * 64 + lck * 8); }
; #define G_STOREA(buf_) { bf16_t* nA = sA + (buf_) * 256 * GLD; _Pragma("unroll") for (int i = 0; i < 4; ++i) *(u32x4*)(nA + (lrow + 64 * i) * GLD + lck * 8) = ra[i]; }
; #define G_STOREB(buf_) { bf16_t* nB = sB + (buf_) * 256 * GLD; _Pragma("unroll") for (int i = 0; i < 4; ++i) *(u32x4*)(nB + (lrow + 64 * i) * GLD + lck * 8) = rb[i]; }
; template <class AL, class BL, class EP>
; DI void gemm_tile256(AL al, BL bl, EP ep, int K, char* smem) {
;     ...
;   G_LOADA(0); G_LOADB(0);
;   __syncthreads();
;   G_STOREA(0); G_STOREB(0);
;   if (KT > 1) G_LOADB(1);
;   __syncthreads();
;   for (int kt = 0; kt < KT; kt += 2) {
;     G_STEP(0, kt);
;     if (kt + 1 >= KT) break;
;     G_STEP(1, kt + 1);
;   }
	s_waitcnt lgkmcnt(0)
	v_mfma_f32_32x32x16_bf16 v[112:127], v[184:187], v[152:155], v[112:127]
	ds_read_b128 v[192:195], v199
	ds_read_b128 v[168:171], v151
	v_mfma_f32_32x32x16_bf16 v[96:111], v[188:191], v[152:155], v[96:111]
	ds_read_b128 v[200:203], v199 offset:2048
	ds_read_b128 v[172:175], v151 offset:2048
	v_mfma_f32_32x32x16_bf16 v[80:95], v[184:187], v[156:159], v[80:95]
	ds_read_b128 v[176:179], v151 offset:4096
	ds_read_b128 v[180:183], v151 offset:6144
	v_mfma_f32_32x32x16_bf16 v[64:79], v[188:191], v[156:159], v[64:79]
	s_add_u32 m0, s19, 0x22000
	s_nop 0
	global_load_lds_dwordx4 v[214:215], off
	v_lshl_add_u64 v[214:215], v[214:215], 0, s[4:5]
	v_mfma_f32_32x32x16_bf16 v[48:63], v[184:187], v[160:163], v[48:63]
	v_mfma_f32_32x32x16_bf16 v[32:47], v[188:191], v[160:163], v[32:47]
	v_mfma_f32_32x32x16_bf16 v[16:31], v[184:187], v[164:167], v[16:31]
	v_mfma_f32_32x32x16_bf16 v[0:15], v[188:191], v[164:167], v[0:15]
	s_add_u32 m0, s19, 0x26000
	s_nop 0
	global_load_lds_dwordx4 v[218:219], off
	v_lshl_add_u64 v[218:219], v[218:219], 0, s[4:5]
	s_waitcnt lgkmcnt(0)
	s_waitcnt vmcnt(12)
	s_barrier
	s_waitcnt lgkmcnt(0)
	v_mfma_f32_32x32x16_bf16 v[112:127], v[192:195], v[168:171], v[112:127]
	ds_read_b128 v[184:187], v198 offset:32768
	ds_read_b128 v[152:155], v132 offset:32768
	v_mfma_f32_32x32x16_bf16 v[96:111], v[200:203], v[168:171], v[96:111]
	ds_read_b128 v[188:191], v198 offset:34816
	ds_read_b128 v[156:159], v132 offset:34816
	v_mfma_f32_32x32x16_bf16 v[80:95], v[192:195], v[172:175], v[80:95]
	ds_read_b128 v[160:163], v132 offset:36864
	ds_read_b128 v[164:167], v132 offset:38912
	v_mfma_f32_32x32x16_bf16 v[64:79], v[200:203], v[172:175], v[64:79]
	s_add_u32 m0, s19, 0x0
	s_nop 0
	global_load_lds_dwordx4 v[212:213], off
	v_lshl_add_u64 v[212:213], v[212:213], 0, s[4:5]
	v_mfma_f32_32x32x16_bf16 v[48:63], v[192:195], v[176:179], v[48:63]
	v_mfma_f32_32x32x16_bf16 v[32:47], v[200:203], v[176:179], v[32:47]
	v_mfma_f32_32x32x16_bf16 v[16:31], v[192:195], v[180:183], v[16:31]
	v_mfma_f32_32x32x16_bf16 v[0:15], v[200:203], v[180:183], v[0:15]
	s_add_u32 m0, s19, 0x4000
	s_nop 0
	global_load_lds_dwordx4 v[216:217], off
	v_lshl_add_u64 v[216:217], v[216:217], 0, s[4:5]
	s_waitcnt lgkmcnt(0)
	v_mfma_f32_32x32x16_bf16 v[112:127], v[184:187], v[152:155], v[112:127]
	ds_read_b128 v[192:195], v199 offset:32768
	ds_read_b128 v[168:171], v151 offset:32768
	v_mfma_f32_32x32x16_bf16 v[96:111], v[188:191], v[152:155], v[96:111]
	ds_read_b128 v[200:203], v199 offset:34816
	ds_read_b128 v[172:175], v151 offset:34816
	v_mfma_f32_32x32x16_bf16 v[80:95], v[184:187], v[156:159], v[80:95]
	ds_read_b128 v[176:179], v151 offset:36864
	ds_read_b128 v[180:183], v151 offset:38912
	v_mfma_f32_32x32x16_bf16 v[64:79], v[188:191], v[156:159], v[64:79]
	s_add_u32 m0, s19, 0x2000
	s_nop 0
	global_load_lds_dwordx4 v[214:215], off
	v_lshl_add_u64 v[214:215], v[214:215], 0, s[4:5]
	v_mfma_f32_32x32x16_bf16 v[48:63], v[184:187], v[160:163], v[48:63]
	v_mfma_f32_32x32x16_bf16 v[32:47], v[188:191], v[160:163], v[32:47]
	v_mfma_f32_32x32x16_bf16 v[16:31], v[184:187], v[164:167], v[16:31]
	v_mfma_f32_32x32x16_bf16 v[0:15], v[188:191], v[164:167], v[0:15]
	s_add_u32 m0, s19, 0x6000
	s_nop 0
	global_load_lds_dwordx4 v[218:219], off
	v_lshl_add_u64 v[218:219], v[218:219], 0, s[4:5]
	s_waitcnt lgkmcnt(0)
	s_waitcnt vmcnt(12)
	s_barrier
	s_waitcnt lgkmcnt(0)
	v_mfma_f32_32x32x16_bf16 v[112:127], v[192:195], v[168:171], v[112:127]
	ds_read_b128 v[184:187], v206
	ds_read_b128 v[152:155], v204
	v_mfma_f32_32x32x16_bf16 v[96:111], v[200:203], v[168:171], v[96:111]
	ds_read_b128 v[188:191], v206 offset:2048
	ds_read_b128 v[156:159], v204 offset:2048
	v_mfma_f32_32x32x16_bf16 v[80:95], v[192:195], v[172:175], v[80:95]
	ds_read_b128 v[160:163], v204 offset:4096
	ds_read_b128 v[164:167], v204 offset:6144
	v_mfma_f32_32x32x16_bf16 v[64:79], v[200:203], v[172:175], v[64:79]
	s_add_u32 m0, s19, 0x8000
	s_nop 0
	global_load_lds_dwordx4 v[212:213], off
	v_lshl_add_u64 v[212:213], v[212:213], 0, s[4:5]
	v_mfma_f32_32x32x16_bf16 v[48:63], v[192:195], v[176:179], v[48:63]
	v_mfma_f32_32x32x16_bf16 v[32:47], v[200:203], v[176:179], v[32:47]
	v_mfma_f32_32x32x16_bf16 v[16:31], v[192:195], v[180:183], v[16:31]
	v_mfma_f32_32x32x16_bf16 v[0:15], v[200:203], v[180:183], v[0:15]
	s_add_u32 m0, s19, 0xc000
	s_nop 0
	global_load_lds_dwordx4 v[216:217], off
	v_lshl_add_u64 v[216:217], v[216:217], 0, s[4:5]
	s_waitcnt lgkmcnt(0)
	v_mfma_f32_32x32x16_bf16 v[112:127], v[184:187], v[152:155], v[112:127]
	ds_read_b128 v[192:195], v207
	ds_read_b128 v[168:171], v205
	v_mfma_f32_32x32x16_bf16 v[96:111], v[188:191], v[152:155], v[96:111]
	ds_read_b128 v[200:203], v207 offset:2048
	ds_read_b128 v[172:175], v205 offset:2048
	v_mfma_f32_32x32x16_bf16 v[80:95], v[184:187], v[156:159], v[80:95]
	ds_read_b128 v[176:179], v205 offset:4096
	ds_read_b128 v[180:183], v205 offset:6144
	v_mfma_f32_32x32x16_bf16 v[64:79], v[188:191], v[156:159], v[64:79]
	s_add_u32 m0, s19, 0xa000
	s_nop 0
	global_load_lds_dwordx4 v[214:215], off
	v_lshl_add_u64 v[214:215], v[214:215], 0, s[4:5]
	v_mfma_f32_32x32x16_bf16 v[48:63], v[184:187], v[160:163], v[48:63]
	v_mfma_f32_32x32x16_bf16 v[32:47], v[188:191], v[160:163], v[32:47]
	v_mfma_f32_32x32x16_bf16 v[16:31], v[184:187], v[164:167], v[16:31]
	v_mfma_f32_32x32x16_bf16 v[0:15], v[188:191], v[164:167], v[0:15]
	s_add_u32 m0, s19, 0xe000
	s_nop 0
	global_load_lds_dwordx4 v[218:219], off
	v_lshl_add_u64 v[218:219], v[218:219], 0, s[4:5]
	s_waitcnt lgkmcnt(0)
	s_waitcnt vmcnt(12)
	s_barrier
; #define G_LOADA(kt_) { _Pragma("unroll") for (int i = 0; i < 4; ++i) ra[i] = al(lrow + 64 * i, (kt_) * 64 + lck * 8); }
; #define G_LOADB(kt_) { _Pragma("unroll") for (int i = 0; i < 4; ++i) rb[i] = bl(lrow + 64 * i, (kt_) * 64 + lck * 8); }
; #define G_STOREA(buf_) { bf16_t* nA = sA + (buf_) * 256 * GLD; _Pragma("unroll") for (int i = 0; i < 4; ++i) *(u32x4*)(nA + (lrow + 64 * i) * GLD + lck * 8) = ra[i]; }
; #define G_STOREB(buf_) { bf16_t* nB = sB + (buf_) * 256 * GLD; _Pragma("unroll") for (int i = 0; i < 4; ++i) *(u32x4*)(nB + (lrow + 64 * i) * GLD + lck * 8) = rb[i]; }
; template <class AL, class BL, class EP>
; DI void gemm_tile256(AL al, BL bl, EP ep, int K, char* smem) {
;     ...
;   G_LOADA(0); G_LOADB(0);
;   __syncthreads();
;   G_STOREA(0); G_STOREB(0);
;   if (KT > 1) G_LOADB(1);
;   __syncthreads();
;   for (int kt = 0; kt < KT; kt += 2) {
;     G_STEP(0, kt);
;     if (kt + 1 >= KT) break;
;     G_STEP(1, kt + 1);
;   }
	s_waitcnt lgkmcnt(0)
	v_mfma_f32_32x32x16_bf16 v[112:127], v[192:195], v[168:171], v[112:127]
	ds_read_b128 v[184:187], v206 offset:32768
	ds_read_b128 v[152:155], v204 offset:32768
	v_mfma_f32_32x32x16_bf16 v[96:111], v[200:203], v[168:171], v[96:111]
	ds_read_b128 v[188:191], v206 offset:34816
	ds_read_b128 v[156:159], v204 offset:34816
	v_mfma_f32_32x32x16_bf16 v[80:95], v[192:195], v[172:175], v[80:95]
	ds_read_b128 v[160:163], v204 offset:36864
	ds_read_b128 v[164:167], v204 offset:38912
	v_mfma_f32_32x32x16_bf16 v[64:79], v[200:203], v[172:175], v[64:79]
	v_mfma_f32_32x32x16_bf16 v[48:63], v[192:195], v[176:179], v[48:63]
	v_mfma_f32_32x32x16_bf16 v[32:47], v[200:203], v[176:179], v[32:47]
	v_mfma_f32_32x32x16_bf16 v[16:31], v[192:195], v[180:183], v[16:31]
	v_mfma_f32_32x32x16_bf16 v[0:15], v[200:203], v[180:183], v[0:15]
	s_waitcnt lgkmcnt(0)
	v_mfma_f32_32x32x16_bf16 v[112:127], v[184:187], v[152:155], v[112:127]
	ds_read_b128 v[192:195], v207 offset:32768
	ds_read_b128 v[168:171], v205 offset:32768
	v_mfma_f32_32x32x16_bf16 v[96:111], v[188:191], v[152:155], v[96:111]
	ds_read_b128 v[200:203], v207 offset:34816
	ds_read_b128 v[172:175], v205 offset:34816
	v_mfma_f32_32x32x16_bf16 v[80:95], v[184:187], v[156:159], v[80:95]
	ds_read_b128 v[176:179], v205 offset:36864
	ds_read_b128 v[180:183], v205 offset:38912
	v_mfma_f32_32x32x16_bf16 v[64:79], v[188:191], v[156:159], v[64:79]
	v_mfma_f32_32x32x16_bf16 v[48:63], v[184:187], v[160:163], v[48:63]
	v_mfma_f32_32x32x16_bf16 v[32:47], v[188:191], v[160:163], v[32:47]
	v_mfma_f32_32x32x16_bf16 v[16:31], v[184:187], v[164:167], v[16:31]
	v_mfma_f32_32x32x16_bf16 v[0:15], v[188:191], v[164:167], v[0:15]
	s_waitcnt lgkmcnt(0)
	s_waitcnt vmcnt(8)
	s_barrier
	s_waitcnt lgkmcnt(0)
	v_mfma_f32_32x32x16_bf16 v[112:127], v[192:195], v[168:171], v[112:127]
	ds_read_b128 v[184:187], v210
	ds_read_b128 v[152:155], v208
	v_mfma_f32_32x32x16_bf16 v[96:111], v[200:203], v[168:171], v[96:111]
	ds_read_b128 v[188:191], v210 offset:2048
	ds_read_b128 v[156:159], v208 offset:2048
	v_mfma_f32_32x32x16_bf16 v[80:95], v[192:195], v[172:175], v[80:95]
	ds_read_b128 v[160:163], v208 offset:4096
	ds_read_b128 v[164:167], v208 offset:6144
	v_mfma_f32_32x32x16_bf16 v[64:79], v[200:203], v[172:175], v[64:79]
	v_mfma_f32_32x32x16_bf16 v[48:63], v[192:195], v[176:179], v[48:63]
	v_mfma_f32_32x32x16_bf16 v[32:47], v[200:203], v[176:179], v[32:47]
	v_mfma_f32_32x32x16_bf16 v[16:31], v[192:195], v[180:183], v[16:31]
	v_mfma_f32_32x32x16_bf16 v[0:15], v[200:203], v[180:183], v[0:15]
	s_waitcnt lgkmcnt(0)
	v_mfma_f32_32x32x16_bf16 v[112:127], v[184:187], v[152:155], v[112:127]
	ds_read_b128 v[192:195], v211
	ds_read_b128 v[168:171], v209
	v_mfma_f32_32x32x16_bf16 v[96:111], v[188:191], v[152:155], v[96:111]
	ds_read_b128 v[200:203], v211 offset:2048
	ds_read_b128 v[172:175], v209 offset:2048
	v_mfma_f32_32x32x16_bf16 v[80:95], v[184:187], v[156:159], v[80:95]
	ds_read_b128 v[176:179], v209 offset:4096
	ds_read_b128 v[180:183], v209 offset:6144
	v_mfma_f32_32x32x16_bf16 v[64:79], v[188:191], v[156:159], v[64:79]
	v_mfma_f32_32x32x16_bf16 v[48:63], v[184:187], v[160:163], v[48:63]
	v_mfma_f32_32x32x16_bf16 v[32:47], v[188:191], v[160:163], v[32:47]
	v_mfma_f32_32x32x16_bf16 v[16:31], v[184:187], v[164:167], v[16:31]
	v_mfma_f32_32x32x16_bf16 v[0:15], v[188:191], v[164:167], v[0:15]
	s_waitcnt lgkmcnt(0)
	s_waitcnt vmcnt(4)
	s_barrier
	s_waitcnt lgkmcnt(0)
	v_mfma_f32_32x32x16_bf16 v[112:127], v[192:195], v[168:171], v[112:127]
	ds_read_b128 v[184:187], v198
	ds_read_b128 v[152:155], v132
	v_mfma_f32_32x32x16_bf16 v[96:111], v[200:203], v[168:171], v[96:111]
	ds_read_b128 v[188:191], v198 offset:2048
	ds_read_b128 v[156:159], v132 offset:2048
	v_mfma_f32_32x32x16_bf16 v[80:95], v[192:195], v[172:175], v[80:95]
	ds_read_b128 v[160:163], v132 offset:4096
	ds_read_b128 v[164:167], v132 offset:6144
	v_mfma_f32_32x32x16_bf16 v[64:79], v[200:203], v[172:175], v[64:79]
	v_mfma_f32_32x32x16_bf16 v[48:63], v[192:195], v[176:179], v[48:63]
	v_mfma_f32_32x32x16_bf16 v[32:47], v[200:203], v[176:179], v[32:47]
	v_mfma_f32_32x32x16_bf16 v[16:31], v[192:195], v[180:183], v[16:31]
	v_mfma_f32_32x32x16_bf16 v[0:15], v[200:203], v[180:183], v[0:15]
	s_waitcnt lgkmcnt(0)
	v_mfma_f32_32x32x16_bf16 v[112:127], v[184:187], v[152:155], v[112:127]
	ds_read_b128 v[192:195], v199
	ds_read_b128 v[168:171], v151
	v_mfma_f32_32x32x16_bf16 v[96:111], v[188:191], v[152:155], v[96:111]
	ds_read_b128 v[200:203], v199 offset:2048
	ds_read_b128 v[172:175], v151 offset:2048
	v_mfma_f32_32x32x16_bf16 v[80:95], v[184:187], v[156:159], v[80:95]
	ds_read_b128 v[176:179], v151 offset:4096
	ds_read_b128 v[180:183], v151 offset:6144
	v_mfma_f32_32x32x16_bf16 v[64:79], v[188:191], v[156:159], v[64:79]
	v_mfma_f32_32x32x16_bf16 v[48:63], v[184:187], v[160:163], v[48:63]
	v_mfma_f32_32x32x16_bf16 v[32:47], v[188:191], v[160:163], v[32:47]
	v_mfma_f32_32x32x16_bf16 v[16:31], v[184:187], v[164:167], v[16:31]
	v_mfma_f32_32x32x16_bf16 v[0:15], v[188:191], v[164:167], v[0:15]
	s_waitcnt lgkmcnt(0)
	s_waitcnt vmcnt(0)
	s_barrier
; DI unsigned pack2(float a, float b) { f2_t f = {a, b}; bf2_t r = __builtin_convertvector(f, bf2_t); return __builtin_bit_cast(unsigned, r); }
; template <class AL, class BL, class EP>
; DI void gemm_tile256(AL al, BL bl, EP ep, int K, char* smem) {
;     ...
;   if constexpr (EP::kBf16) {
;     bf16_t* sCb = (bf16_t*)smem;
; #pragma unroll
;     for (int i = 0; i < 4; ++i)
; #pragma unroll
;       for (int j = 0; j < 2; ++j)
; #pragma unroll
;         for (int g = 0; g < 4; ++g) {
;           u32x2 v = {pack2(acc[i][j][4 * g], acc[i][j][4 * g + 1]), pack2(acc[i][j][4 * g + 2], acc[i][j][4 * g + 3])};
;           *(u32x2*)(sCb + (128 * wm + 32 * i + r) * BLD + 64 * wn + 32 * j + 8 * g + 4 * h) = v;
;         }
;     __syncthreads();
	s_waitcnt lgkmcnt(0)
	v_mfma_f32_32x32x16_bf16 v[112:127], v[192:195], v[168:171], v[112:127]
	ds_read_b128 v[184:187], v198 offset:32768
	ds_read_b128 v[152:155], v132 offset:32768
	v_mfma_f32_32x32x16_bf16 v[96:111], v[200:203], v[168:171], v[96:111]
	ds_read_b128 v[188:191], v198 offset:34816
	ds_read_b128 v[156:159], v132 offset:34816
	v_mfma_f32_32x32x16_bf16 v[80:95], v[192:195], v[172:175], v[80:95]
	ds_read_b128 v[160:163], v132 offset:36864
	ds_read_b128 v[164:167], v132 offset:38912
	v_mfma_f32_32x32x16_bf16 v[64:79], v[200:203], v[172:175], v[64:79]
	v_mfma_f32_32x32x16_bf16 v[48:63], v[192:195], v[176:179], v[48:63]
	v_mfma_f32_32x32x16_bf16 v[32:47], v[200:203], v[176:179], v[32:47]
	v_mfma_f32_32x32x16_bf16 v[16:31], v[192:195], v[180:183], v[16:31]
	v_mfma_f32_32x32x16_bf16 v[0:15], v[200:203], v[180:183], v[0:15]
	s_waitcnt lgkmcnt(0)
	v_mfma_f32_32x32x16_bf16 v[112:127], v[184:187], v[152:155], v[112:127]
	ds_read_b128 v[192:195], v199 offset:32768
	ds_read_b128 v[168:171], v151 offset:32768
	v_mfma_f32_32x32x16_bf16 v[96:111], v[188:191], v[152:155], v[96:111]
	ds_read_b128 v[200:203], v199 offset:34816
	ds_read_b128 v[172:175], v151 offset:34816
	v_mfma_f32_32x32x16_bf16 v[80:95], v[184:187], v[156:159], v[80:95]
	ds_read_b128 v[176:179], v151 offset:36864
	ds_read_b128 v[180:183], v151 offset:38912
	v_mfma_f32_32x32x16_bf16 v[64:79], v[188:191], v[156:159], v[64:79]
	v_mfma_f32_32x32x16_bf16 v[48:63], v[184:187], v[160:163], v[48:63]
	v_mfma_f32_32x32x16_bf16 v[32:47], v[188:191], v[160:163], v[32:47]
	v_mfma_f32_32x32x16_bf16 v[16:31], v[184:187], v[164:167], v[16:31]
	v_mfma_f32_32x32x16_bf16 v[0:15], v[188:191], v[164:167], v[0:15]
	s_waitcnt lgkmcnt(0)
	s_waitcnt lgkmcnt(0)
	v_mfma_f32_32x32x16_bf16 v[112:127], v[192:195], v[168:171], v[112:127]
	v_mfma_f32_32x32x16_bf16 v[96:111], v[200:203], v[168:171], v[96:111]
	v_mfma_f32_32x32x16_bf16 v[80:95], v[192:195], v[172:175], v[80:95]
	v_mfma_f32_32x32x16_bf16 v[64:79], v[200:203], v[172:175], v[64:79]
	v_mfma_f32_32x32x16_bf16 v[48:63], v[192:195], v[176:179], v[48:63]
	v_mfma_f32_32x32x16_bf16 v[32:47], v[200:203], v[176:179], v[32:47]
	v_mfma_f32_32x32x16_bf16 v[16:31], v[192:195], v[180:183], v[16:31]
	v_mfma_f32_32x32x16_bf16 v[0:15], v[200:203], v[180:183], v[0:15]
	s_nop 15
	s_nop 3
	v_lshl_or_b32 v128, v128, 7, v150
	s_waitcnt lgkmcnt(4)
	v_mad_u64_u32 v[130:131], s[2:3], v133, s13, v[128:129]
	s_waitcnt lgkmcnt(0)
	s_barrier
	s_nop 8
	v_cvt_pk_bf16_f32 v112, v112, v113
	v_cvt_pk_bf16_f32 v113, v114, v115
	v_cvt_pk_bf16_f32 v114, v116, v117
	v_cvt_pk_bf16_f32 v115, v118, v119
	ds_write2_b64 v130, v[112:113], v[114:115] offset1:2
	v_cvt_pk_bf16_f32 v112, v120, v121
	v_cvt_pk_bf16_f32 v113, v122, v123
	v_cvt_pk_bf16_f32 v114, v124, v125
	s_nop 3
	v_cvt_pk_bf16_f32 v16, v16, v17
	v_cvt_pk_bf16_f32 v17, v18, v19
	v_cvt_pk_bf16_f32 v18, v20, v21
	v_add_u32_e32 v20, 0xc000, v130
	v_cvt_pk_bf16_f32 v19, v22, v23
	v_cvt_pk_bf16_f32 v115, v126, v127
	ds_write2_b64 v20, v[16:17], v[18:19] offset0:192 offset1:194
	v_cvt_pk_bf16_f32 v0, v0, v1
	v_cvt_pk_bf16_f32 v1, v2, v3
	v_cvt_pk_bf16_f32 v2, v4, v5
	v_cvt_pk_bf16_f32 v3, v6, v7
	ds_write2_b64 v20, v[0:1], v[2:3] offset0:200 offset1:202
	v_cvt_pk_bf16_f32 v0, v8, v9
	v_cvt_pk_bf16_f32 v1, v10, v11
	s_nop 3
	v_cvt_pk_bf16_f32 v96, v96, v97
	v_cvt_pk_bf16_f32 v97, v98, v99
	v_cvt_pk_bf16_f32 v98, v100, v101
	v_cvt_pk_bf16_f32 v99, v102, v103
	v_cvt_pk_bf16_f32 v2, v12, v13
	v_cvt_pk_bf16_f32 v3, v14, v15
	ds_write2_b64 v130, v[96:97], v[98:99] offset0:8 offset1:10
	v_cvt_pk_bf16_f32 v80, v80, v81
	v_cvt_pk_bf16_f32 v81, v82, v83
	v_cvt_pk_bf16_f32 v82, v84, v85
	v_cvt_pk_bf16_f32 v83, v86, v87
	v_add_u32_e32 v84, 0x4000, v130
	v_cvt_pk_bf16_f32 v96, v104, v105
	v_cvt_pk_bf16_f32 v97, v106, v107
	s_nop 3
	v_cvt_pk_bf16_f32 v64, v64, v65
	v_cvt_pk_bf16_f32 v65, v66, v67
	v_cvt_pk_bf16_f32 v66, v68, v69
	v_cvt_pk_bf16_f32 v67, v70, v71
	v_cvt_pk_bf16_f32 v98, v108, v109
	v_cvt_pk_bf16_f32 v99, v110, v111
	ds_write2_b64 v84, v[80:81], v[82:83] offset0:64 offset1:66
	v_cvt_pk_bf16_f32 v48, v48, v49
	v_cvt_pk_bf16_f32 v49, v50, v51
	v_cvt_pk_bf16_f32 v50, v52, v53
	v_cvt_pk_bf16_f32 v51, v54, v55
	v_add_u32_e32 v52, 0x8000, v130
	v_cvt_pk_bf16_f32 v80, v88, v89
	v_cvt_pk_bf16_f32 v81, v90, v91
	s_nop 4
	v_cvt_pk_bf16_f32 v32, v32, v33
	v_cvt_pk_bf16_f32 v33, v34, v35
	v_cvt_pk_bf16_f32 v34, v36, v37
	v_cvt_pk_bf16_f32 v35, v38, v39
	v_cvt_pk_bf16_f32 v82, v92, v93
	v_cvt_pk_bf16_f32 v83, v94, v95
	ds_write2_b64 v84, v[64:65], v[66:67] offset0:72 offset1:74
	v_cvt_pk_bf16_f32 v64, v72, v73
	v_cvt_pk_bf16_f32 v65, v74, v75
	v_cvt_pk_bf16_f32 v66, v76, v77
	v_cvt_pk_bf16_f32 v67, v78, v79
	ds_write2_b64 v52, v[48:49], v[50:51] offset0:128 offset1:130
	v_cvt_pk_bf16_f32 v48, v56, v57
	v_cvt_pk_bf16_f32 v49, v58, v59
	v_cvt_pk_bf16_f32 v50, v60, v61
	v_cvt_pk_bf16_f32 v51, v62, v63
	ds_write2_b64 v52, v[32:33], v[34:35] offset0:136 offset1:138
	v_cvt_pk_bf16_f32 v32, v40, v41
	v_cvt_pk_bf16_f32 v33, v42, v43
	v_cvt_pk_bf16_f32 v34, v44, v45
	v_cvt_pk_bf16_f32 v35, v46, v47
	v_cvt_pk_bf16_f32 v16, v24, v25
	v_cvt_pk_bf16_f32 v17, v26, v27
	v_cvt_pk_bf16_f32 v18, v28, v29
	v_cvt_pk_bf16_f32 v19, v30, v31
	ds_write2_b64 v20, v[0:1], v[2:3] offset0:204 offset1:206
	v_mov_b32_e32 v2, v196
	ds_write2_b64 v130, v[112:113], v[114:115] offset0:4 offset1:6
	ds_write2_b64 v130, v[96:97], v[98:99] offset0:12 offset1:14
	ds_write2_b64 v84, v[80:81], v[82:83] offset0:68 offset1:70
	ds_write2_b64 v84, v[64:65], v[66:67] offset0:76 offset1:78
	ds_write2_b64 v52, v[48:49], v[50:51] offset0:132 offset1:134
	ds_write2_b64 v52, v[32:33], v[34:35] offset0:140 offset1:142
	ds_write2_b64 v20, v[16:17], v[18:19] offset0:196 offset1:198
	s_waitcnt lgkmcnt(0)
	s_barrier
; DI int tid512() { int t = threadIdx_x_raw(); asm volatile("" : "+v"(t)); return t; }
;   DI void operator()(const bf16_t* sCb) const {
;     for (int id = tid512(); id < 8192; id += 512) {
;       int row = id >> 5, c8 = (id & 31) * 8, n = n0 + c8;
;       if (n < N) *(u32x4*)(dst + (size_t)(m0 + row) * ld + n) = *(const u32x4*)(sCb + row * BLD + c8);
	s_nop 0
	v_cmp_gt_i32_e32 vcc, s14, v2
	s_and_saveexec_b64 s[2:3], vcc
	s_cbranch_execz .LBB0_444
	v_lshlrev_b32_e32 v3, 3, v2
	v_and_b32_e32 v1, 0xf8, v3
	v_or_b32_e32 v0, s17, v1
	v_cmp_gt_i32_e32 vcc, s15, v0
	s_and_saveexec_b64 s[6:7], vcc
	s_cbranch_execz .Lep_done_444
; DI int tid512() { int t = threadIdx_x_raw(); asm volatile("" : "+v"(t)); return t; }
;   DI void operator()(const bf16_t* sCb) const {
;     for (int id = tid512(); id < 8192; id += 512) {
;       int row = id >> 5, c8 = (id & 31) * 8, n = n0 + c8;
;       if (n < N) *(u32x4*)(dst + (size_t)(m0 + row) * ld + n) = *(const u32x4*)(sCb + row * BLD + c8);
;     }
;   }
	v_ashrrev_i32_e32 v8, 5, v2
	v_mul_lo_u32 v4, v8, s13
	v_lshl_add_u32 v1, v1, 1, v4
	v_add_u32_e32 v10, 0x10800, v1
	ds_read_b128 v[64:67], v1
	ds_read_b128 v[68:71], v1 offset:8448
	ds_read_b128 v[72:75], v1 offset:16896
	ds_read_b128 v[76:79], v1 offset:25344
	ds_read_b128 v[80:83], v1 offset:33792
	ds_read_b128 v[84:87], v1 offset:42240
	ds_read_b128 v[88:91], v1 offset:50688
	ds_read_b128 v[92:95], v1 offset:59136
	ds_read_b128 v[96:99], v10
	ds_read_b128 v[100:103], v10 offset:8448
	ds_read_b128 v[104:107], v10 offset:16896
	ds_read_b128 v[108:111], v10 offset:25344
	ds_read_b128 v[112:115], v10 offset:33792
	ds_read_b128 v[116:119], v10 offset:42240
	ds_read_b128 v[120:123], v10 offset:50688
	ds_read_b128 v[124:127], v10 offset:59136
	v_and_b32_e32 v1, 0xf8, v3
	v_or_b32_e32 v0, s17, v1
	v_ashrrev_i32_e32 v8, 5, v2
	v_add_u32_e32 v8, s18, v8
	v_ashrrev_i32_e32 v9, 31, v8
	v_lshlrev_b64 v[8:9], 11, v[8:9]
	v_lshl_add_u64 v[8:9], s[8:9], 0, v[8:9]
	v_ashrrev_i32_e32 v1, 31, v0
	v_lshl_add_u64 v[0:1], v[0:1], 1, v[8:9]
	s_waitcnt lgkmcnt(15)
	global_store_dwordx4 v[0:1], v[64:67], off
	v_add_u32_e32 v2, 0x200, v2
	v_and_b32_e32 v1, 0xf8, v3
	v_or_b32_e32 v0, s17, v1
	v_ashrrev_i32_e32 v8, 5, v2
	v_add_u32_e32 v8, s18, v8
	v_ashrrev_i32_e32 v9, 31, v8
	v_lshlrev_b64 v[8:9], 11, v[8:9]
	v_lshl_add_u64 v[8:9], s[8:9], 0, v[8:9]
	v_ashrrev_i32_e32 v1, 31, v0
	v_lshl_add_u64 v[0:1], v[0:1], 1, v[8:9]
	s_waitcnt lgkmcnt(14)
	global_store_dwordx4 v[0:1], v[68:71], off
	v_add_u32_e32 v2, 0x200, v2
	v_and_b32_e32 v1, 0xf8, v3
	v_or_b32_e32 v0, s17, v1
	v_ashrrev_i32_e32 v8, 5, v2
	v_add_u32_e32 v8, s18, v8
	v_ashrrev_i32_e32 v9, 31, v8
	v_lshlrev_b64 v[8:9], 11, v[8:9]
	v_lshl_add_u64 v[8:9], s[8:9], 0, v[8:9]
	v_ashrrev_i32_e32 v1, 31, v0
	v_lshl_add_u64 v[0:1], v[0:1], 1, v[8:9]
	s_waitcnt lgkmcnt(13)
	global_store_dwordx4 v[0:1], v[72:75], off
	v_add_u32_e32 v2, 0x200, v2
	v_and_b32_e32 v1, 0xf8, v3
	v_or_b32_e32 v0, s17, v1
	v_ashrrev_i32_e32 v8, 5, v2
	v_add_u32_e32 v8, s18, v8
	v_ashrrev_i32_e32 v9, 31, v8
	v_lshlrev_b64 v[8:9], 11, v[8:9]
	v_lshl_add_u64 v[8:9], s[8:9], 0, v[8:9]
	v_ashrrev_i32_e32 v1, 31, v0
	v_lshl_add_u64 v[0:1], v[0:1], 1, v[8:9]
	s_waitcnt lgkmcnt(12)
	global_store_dwordx4 v[0:1], v[76:79], off
	v_add_u32_e32 v2, 0x200, v2
	v_and_b32_e32 v1, 0xf8, v3
	v_or_b32_e32 v0, s17, v1
	v_ashrrev_i32_e32 v8, 5, v2
	v_add_u32_e32 v8, s18, v8
	v_ashrrev_i32_e32 v9, 31, v8
	v_lshlrev_b64 v[8:9], 11, v[8:9]
	v_lshl_add_u64 v[8:9], s[8:9], 0, v[8:9]
	v_ashrrev_i32_e32 v1, 31, v0
	v_lshl_add_u64 v[0:1], v[0:1], 1, v[8:9]
	s_waitcnt lgkmcnt(11)
	global_store_dwordx4 v[0:1], v[80:83], off
	v_add_u32_e32 v2, 0x200, v2
	v_and_b32_e32 v1, 0xf8, v3
	v_or_b32_e32 v0, s17, v1
	v_ashrrev_i32_e32 v8, 5, v2
	v_add_u32_e32 v8, s18, v8
	v_ashrrev_i32_e32 v9, 31, v8
	v_lshlrev_b64 v[8:9], 11, v[8:9]
	v_lshl_add_u64 v[8:9], s[8:9], 0, v[8:9]
	v_ashrrev_i32_e32 v1, 31, v0
	v_lshl_add_u64 v[0:1], v[0:1], 1, v[8:9]
	s_waitcnt lgkmcnt(10)
	global_store_dwordx4 v[0:1], v[84:87], off
	v_add_u32_e32 v2, 0x200, v2
	v_and_b32_e32 v1, 0xf8, v3
	v_or_b32_e32 v0, s17, v1
	v_ashrrev_i32_e32 v8, 5, v2
	v_add_u32_e32 v8, s18, v8
	v_ashrrev_i32_e32 v9, 31, v8
	v_lshlrev_b64 v[8:9], 11, v[8:9]
	v_lshl_add_u64 v[8:9], s[8:9], 0, v[8:9]
	v_ashrrev_i32_e32 v1, 31, v0
	v_lshl_add_u64 v[0:1], v[0:1], 1, v[8:9]
	s_waitcnt lgkmcnt(9)
	global_store_dwordx4 v[0:1], v[88:91], off
	v_add_u32_e32 v2, 0x200, v2
	v_and_b32_e32 v1, 0xf8, v3
	v_or_b32_e32 v0, s17, v1
	v_ashrrev_i32_e32 v8, 5, v2
	v_add_u32_e32 v8, s18, v8
	v_ashrrev_i32_e32 v9, 31, v8
	v_lshlrev_b64 v[8:9], 11, v[8:9]
	v_lshl_add_u64 v[8:9], s[8:9], 0, v[8:9]
	v_ashrrev_i32_e32 v1, 31, v0
	v_lshl_add_u64 v[0:1], v[0:1], 1, v[8:9]
	s_waitcnt lgkmcnt(8)
	global_store_dwordx4 v[0:1], v[92:95], off
	v_add_u32_e32 v2, 0x200, v2
	v_and_b32_e32 v1, 0xf8, v3
	v_or_b32_e32 v0, s17, v1
	v_ashrrev_i32_e32 v8, 5, v2
	v_add_u32_e32 v8, s18, v8
	v_ashrrev_i32_e32 v9, 31, v8
	v_lshlrev_b64 v[8:9], 11, v[8:9]
	v_lshl_add_u64 v[8:9], s[8:9], 0, v[8:9]
	v_ashrrev_i32_e32 v1, 31, v0
	v_lshl_add_u64 v[0:1], v[0:1], 1, v[8:9]
	s_waitcnt lgkmcnt(7)
	global_store_dwordx4 v[0:1], v[96:99], off
	v_add_u32_e32 v2, 0x200, v2
	v_and_b32_e32 v1, 0xf8, v3
	v_or_b32_e32 v0, s17, v1
	v_ashrrev_i32_e32 v8, 5, v2
	v_add_u32_e32 v8, s18, v8
	v_ashrrev_i32_e32 v9, 31, v8
	v_lshlrev_b64 v[8:9], 11, v[8:9]
	v_lshl_add_u64 v[8:9], s[8:9], 0, v[8:9]
	v_ashrrev_i32_e32 v1, 31, v0
	v_lshl_add_u64 v[0:1], v[0:1], 1, v[8:9]
	s_waitcnt lgkmcnt(6)
	global_store_dwordx4 v[0:1], v[100:103], off
	v_add_u32_e32 v2, 0x200, v2
	v_and_b32_e32 v1, 0xf8, v3
	v_or_b32_e32 v0, s17, v1
	v_ashrrev_i32_e32 v8, 5, v2
	v_add_u32_e32 v8, s18, v8
	v_ashrrev_i32_e32 v9, 31, v8
	v_lshlrev_b64 v[8:9], 11, v[8:9]
	v_lshl_add_u64 v[8:9], s[8:9], 0, v[8:9]
	v_ashrrev_i32_e32 v1, 31, v0
	v_lshl_add_u64 v[0:1], v[0:1], 1, v[8:9]
	s_waitcnt lgkmcnt(5)
	global_store_dwordx4 v[0:1], v[104:107], off
	v_add_u32_e32 v2, 0x200, v2
	v_and_b32_e32 v1, 0xf8, v3
	v_or_b32_e32 v0, s17, v1
	v_ashrrev_i32_e32 v8, 5, v2
	v_add_u32_e32 v8, s18, v8
	v_ashrrev_i32_e32 v9, 31, v8
	v_lshlrev_b64 v[8:9], 11, v[8:9]
	v_lshl_add_u64 v[8:9], s[8:9], 0, v[8:9]
	v_ashrrev_i32_e32 v1, 31, v0
	v_lshl_add_u64 v[0:1], v[0:1], 1, v[8:9]
	s_waitcnt lgkmcnt(4)
	global_store_dwordx4 v[0:1], v[108:111], off
	v_add_u32_e32 v2, 0x200, v2
	v_and_b32_e32 v1, 0xf8, v3
	v_or_b32_e32 v0, s17, v1
	v_ashrrev_i32_e32 v8, 5, v2
	v_add_u32_e32 v8, s18, v8
	v_ashrrev_i32_e32 v9, 31, v8
	v_lshlrev_b64 v[8:9], 11, v[8:9]
	v_lshl_add_u64 v[8:9], s[8:9], 0, v[8:9]
	v_ashrrev_i32_e32 v1, 31, v0
	v_lshl_add_u64 v[0:1], v[0:1], 1, v[8:9]
	s_waitcnt lgkmcnt(3)
	global_store_dwordx4 v[0:1], v[112:115], off
	v_add_u32_e32 v2, 0x200, v2
	v_and_b32_e32 v1, 0xf8, v3
	v_or_b32_e32 v0, s17, v1
	v_ashrrev_i32_e32 v8, 5, v2
	v_add_u32_e32 v8, s18, v8
	v_ashrrev_i32_e32 v9, 31, v8
	v_lshlrev_b64 v[8:9], 11, v[8:9]
	v_lshl_add_u64 v[8:9], s[8:9], 0, v[8:9]
	v_ashrrev_i32_e32 v1, 31, v0
	v_lshl_add_u64 v[0:1], v[0:1], 1, v[8:9]
	s_waitcnt lgkmcnt(2)
	global_store_dwordx4 v[0:1], v[116:119], off
	v_add_u32_e32 v2, 0x200, v2
	v_and_b32_e32 v1, 0xf8, v3
	v_or_b32_e32 v0, s17, v1
	v_ashrrev_i32_e32 v8, 5, v2
	v_add_u32_e32 v8, s18, v8
	v_ashrrev_i32_e32 v9, 31, v8
	v_lshlrev_b64 v[8:9], 11, v[8:9]
	v_lshl_add_u64 v[8:9], s[8:9], 0, v[8:9]
	v_ashrrev_i32_e32 v1, 31, v0
	v_lshl_add_u64 v[0:1], v[0:1], 1, v[8:9]
	s_waitcnt lgkmcnt(1)
	global_store_dwordx4 v[0:1], v[120:123], off
	v_add_u32_e32 v2, 0x200, v2
	v_and_b32_e32 v1, 0xf8, v3
	v_or_b32_e32 v0, s17, v1
	v_ashrrev_i32_e32 v8, 5, v2
	v_add_u32_e32 v8, s18, v8
	v_ashrrev_i32_e32 v9, 31, v8
	v_lshlrev_b64 v[8:9], 11, v[8:9]
	v_lshl_add_u64 v[8:9], s[8:9], 0, v[8:9]
	v_ashrrev_i32_e32 v1, 31, v0
	v_lshl_add_u64 v[0:1], v[0:1], 1, v[8:9]
	s_waitcnt lgkmcnt(0)
	global_store_dwordx4 v[0:1], v[124:127], off
.Lep_done_444:
	s_or_b64 exec, exec, s[6:7]
	s_branch .LBB0_444

; DI unsigned pack2(float a, float b) { f2_t f = {a, b}; bf2_t r = __builtin_convertvector(f, bf2_t); return __builtin_bit_cast(unsigned, r); }
; DI int tid512() { int t = threadIdx_x_raw(); asm volatile("" : "+v"(t)); return t; }
; template <class AL, class BL, class EP>
; DI void gemm_tile256(AL al, BL bl, EP ep, int K, char* smem) {
;     ...
;   if constexpr (EP::kBf16) {
;     bf16_t* sCb = (bf16_t*)smem;
; #pragma unroll
;     for (int i = 0; i < 4; ++i)
; #pragma unroll
;       for (int j = 0; j < 2; ++j)
; #pragma unroll
;         for (int g = 0; g < 4; ++g) {
;           u32x2 v = {pack2(acc[i][j][4 * g], acc[i][j][4 * g + 1]), pack2(acc[i][j][4 * g + 2], acc[i][j][4 * g + 3])};
;           *(u32x2*)(sCb + (128 * wm + 32 * i + r) * BLD + 64 * wn + 32 * j + 8 * g + 4 * h) = v;
;         }
;     __syncthreads();
;   DI void operator()(const bf16_t* sCb) const {
;     for (int id = tid512(); id < 8192; id += 512) {
;       int row = id >> 5, c8 = (id & 31) * 8, n = n0 + c8;
;       if (n < N) *(u32x4*)(dst + (size_t)(m0 + row) * ld + n) = *(const u32x4*)(sCb + row * BLD + c8);
.LBB0_666:
	v_lshl_or_b32 v128, v198, 7, v200
	v_mad_u64_u32 v[128:129], s[0:1], v199, s21, v[128:129]
	s_nop 7
	v_cvt_pk_bf16_f32 v16, v16, v17
	v_cvt_pk_bf16_f32 v17, v18, v19
	v_cvt_pk_bf16_f32 v18, v20, v21
	v_add_u32_e32 v20, 0xc000, v128
	v_cvt_pk_bf16_f32 v0, v0, v1
	v_cvt_pk_bf16_f32 v1, v2, v3
	v_cvt_pk_bf16_f32 v2, v4, v5
	v_cvt_pk_bf16_f32 v3, v6, v7
	v_cvt_pk_bf16_f32 v112, v112, v113
	v_cvt_pk_bf16_f32 v113, v114, v115
	v_cvt_pk_bf16_f32 v114, v116, v117
	v_cvt_pk_bf16_f32 v115, v118, v119
	v_cvt_pk_bf16_f32 v96, v96, v97
	v_cvt_pk_bf16_f32 v97, v98, v99
	v_cvt_pk_bf16_f32 v98, v100, v101
	v_cvt_pk_bf16_f32 v99, v102, v103
	v_cvt_pk_bf16_f32 v80, v80, v81
	v_cvt_pk_bf16_f32 v81, v82, v83
	v_cvt_pk_bf16_f32 v82, v84, v85
	v_cvt_pk_bf16_f32 v83, v86, v87
	v_add_u32_e32 v84, 0x4000, v128
	v_cvt_pk_bf16_f32 v64, v64, v65
	v_cvt_pk_bf16_f32 v65, v66, v67
	v_cvt_pk_bf16_f32 v66, v68, v69
	v_cvt_pk_bf16_f32 v67, v70, v71
	v_cvt_pk_bf16_f32 v48, v48, v49
	v_cvt_pk_bf16_f32 v49, v50, v51
	v_cvt_pk_bf16_f32 v50, v52, v53
	v_cvt_pk_bf16_f32 v51, v54, v55
	v_add_u32_e32 v52, 0x8000, v128
	v_cvt_pk_bf16_f32 v32, v32, v33
	v_cvt_pk_bf16_f32 v33, v34, v35
	v_cvt_pk_bf16_f32 v34, v36, v37
	v_cvt_pk_bf16_f32 v35, v38, v39
	v_cvt_pk_bf16_f32 v19, v22, v23
	ds_write2_b64 v20, v[0:1], v[2:3] offset0:200 offset1:202
	v_cvt_pk_bf16_f32 v0, v8, v9
	v_cvt_pk_bf16_f32 v1, v10, v11
	v_cvt_pk_bf16_f32 v2, v12, v13
	v_cvt_pk_bf16_f32 v3, v14, v15
	ds_write2_b64 v128, v[112:113], v[114:115] offset1:2
	v_cvt_pk_bf16_f32 v112, v120, v121
	v_cvt_pk_bf16_f32 v113, v122, v123
	v_cvt_pk_bf16_f32 v114, v124, v125
	v_cvt_pk_bf16_f32 v115, v126, v127
	ds_write2_b64 v128, v[96:97], v[98:99] offset0:8 offset1:10
	v_cvt_pk_bf16_f32 v96, v104, v105
	v_cvt_pk_bf16_f32 v97, v106, v107
	v_cvt_pk_bf16_f32 v98, v108, v109
	v_cvt_pk_bf16_f32 v99, v110, v111
	ds_write2_b64 v84, v[80:81], v[82:83] offset0:64 offset1:66
	v_cvt_pk_bf16_f32 v80, v88, v89
	v_cvt_pk_bf16_f32 v81, v90, v91
	v_cvt_pk_bf16_f32 v82, v92, v93
	v_cvt_pk_bf16_f32 v83, v94, v95
	ds_write2_b64 v84, v[64:65], v[66:67] offset0:72 offset1:74
	v_cvt_pk_bf16_f32 v64, v72, v73
	v_cvt_pk_bf16_f32 v65, v74, v75
	v_cvt_pk_bf16_f32 v66, v76, v77
	v_cvt_pk_bf16_f32 v67, v78, v79
	ds_write2_b64 v52, v[48:49], v[50:51] offset0:128 offset1:130
	v_cvt_pk_bf16_f32 v48, v56, v57
	v_cvt_pk_bf16_f32 v49, v58, v59
	v_cvt_pk_bf16_f32 v50, v60, v61
	v_cvt_pk_bf16_f32 v51, v62, v63
	ds_write2_b64 v52, v[32:33], v[34:35] offset0:136 offset1:138
	v_cvt_pk_bf16_f32 v32, v40, v41
	v_cvt_pk_bf16_f32 v33, v42, v43
	v_cvt_pk_bf16_f32 v34, v44, v45
	v_cvt_pk_bf16_f32 v35, v46, v47
	ds_write2_b64 v20, v[16:17], v[18:19] offset0:192 offset1:194
	v_cvt_pk_bf16_f32 v16, v24, v25
	v_cvt_pk_bf16_f32 v17, v26, v27
	v_cvt_pk_bf16_f32 v18, v28, v29
	v_cvt_pk_bf16_f32 v19, v30, v31
	ds_write2_b64 v20, v[0:1], v[2:3] offset0:204 offset1:206
	v_mov_b32_e32 v2, v196
	ds_write2_b64 v128, v[112:113], v[114:115] offset0:4 offset1:6
	ds_write2_b64 v128, v[96:97], v[98:99] offset0:12 offset1:14
	ds_write2_b64 v84, v[80:81], v[82:83] offset0:68 offset1:70
	ds_write2_b64 v84, v[64:65], v[66:67] offset0:76 offset1:78
	ds_write2_b64 v52, v[48:49], v[50:51] offset0:132 offset1:134
	ds_write2_b64 v52, v[32:33], v[34:35] offset0:140 offset1:142
	ds_write2_b64 v20, v[16:17], v[18:19] offset0:196 offset1:198
	s_waitcnt lgkmcnt(0)
	s_barrier
	s_nop 0
	v_cmp_gt_i32_e32 vcc, s23, v2
	s_and_saveexec_b64 s[0:1], vcc
	s_cbranch_execz .LBB0_671
	v_lshlrev_b32_e32 v3, 3, v2
	v_and_b32_e32 v1, 0xf8, v3
	v_or_b32_e32 v0, s26, v1
	v_cmp_gt_i32_e32 vcc, s24, v0
	s_and_saveexec_b64 s[14:15], vcc
	s_cbranch_execz .Lep_done_671
; DI int tid512() { int t = threadIdx_x_raw(); asm volatile("" : "+v"(t)); return t; }
;   DI void operator()(const bf16_t* sCb) const {
;     for (int id = tid512(); id < 8192; id += 512) {
;       int row = id >> 5, c8 = (id & 31) * 8, n = n0 + c8;
;       if (n < N) *(u32x4*)(dst + (size_t)(m0 + row) * ld + n) = *(const u32x4*)(sCb + row * BLD + c8);
;     }
;   }
	v_ashrrev_i32_e32 v8, 5, v2
	v_mul_lo_u32 v4, v8, s21
	v_lshl_add_u32 v1, v1, 1, v4
	v_add_u32_e32 v10, 0x10800, v1
	ds_read_b128 v[64:67], v1
	ds_read_b128 v[68:71], v1 offset:8448
	ds_read_b128 v[72:75], v1 offset:16896
	ds_read_b128 v[76:79], v1 offset:25344
	ds_read_b128 v[80:83], v1 offset:33792
	ds_read_b128 v[84:87], v1 offset:42240
	ds_read_b128 v[88:91], v1 offset:50688
	ds_read_b128 v[92:95], v1 offset:59136
	ds_read_b128 v[96:99], v10
	ds_read_b128 v[100:103], v10 offset:8448
	ds_read_b128 v[104:107], v10 offset:16896
	ds_read_b128 v[108:111], v10 offset:25344
	ds_read_b128 v[112:115], v10 offset:33792
	ds_read_b128 v[116:119], v10 offset:42240
	ds_read_b128 v[120:123], v10 offset:50688
	ds_read_b128 v[124:127], v10 offset:59136
	v_and_b32_e32 v1, 0xf8, v3
	v_or_b32_e32 v0, s26, v1
	v_ashrrev_i32_e32 v8, 5, v2
	v_add_u32_e32 v8, s27, v8
	v_ashrrev_i32_e32 v9, 31, v8
	v_lshlrev_b64 v[8:9], 11, v[8:9]
	v_lshl_add_u64 v[8:9], s[8:9], 0, v[8:9]
	v_ashrrev_i32_e32 v1, 31, v0
	v_lshl_add_u64 v[0:1], v[0:1], 1, v[8:9]
	s_waitcnt lgkmcnt(15)
	global_store_dwordx4 v[0:1], v[64:67], off
	v_add_u32_e32 v2, 0x200, v2
	v_and_b32_e32 v1, 0xf8, v3
	v_or_b32_e32 v0, s26, v1
	v_ashrrev_i32_e32 v8, 5, v2
	v_add_u32_e32 v8, s27, v8
	v_ashrrev_i32_e32 v9, 31, v8
	v_lshlrev_b64 v[8:9], 11, v[8:9]
	v_lshl_add_u64 v[8:9], s[8:9], 0, v[8:9]
	v_ashrrev_i32_e32 v1, 31, v0
	v_lshl_add_u64 v[0:1], v[0:1], 1, v[8:9]
	s_waitcnt lgkmcnt(14)
	global_store_dwordx4 v[0:1], v[68:71], off
	v_add_u32_e32 v2, 0x200, v2
	v_and_b32_e32 v1, 0xf8, v3
	v_or_b32_e32 v0, s26, v1
	v_ashrrev_i32_e32 v8, 5, v2
	v_add_u32_e32 v8, s27, v8
	v_ashrrev_i32_e32 v9, 31, v8
	v_lshlrev_b64 v[8:9], 11, v[8:9]
	v_lshl_add_u64 v[8:9], s[8:9], 0, v[8:9]
	v_ashrrev_i32_e32 v1, 31, v0
	v_lshl_add_u64 v[0:1], v[0:1], 1, v[8:9]
	s_waitcnt lgkmcnt(13)
	global_store_dwordx4 v[0:1], v[72:75], off
	v_add_u32_e32 v2, 0x200, v2
	v_and_b32_e32 v1, 0xf8, v3
	v_or_b32_e32 v0, s26, v1
	v_ashrrev_i32_e32 v8, 5, v2
	v_add_u32_e32 v8, s27, v8
	v_ashrrev_i32_e32 v9, 31, v8
	v_lshlrev_b64 v[8:9], 11, v[8:9]
	v_lshl_add_u64 v[8:9], s[8:9], 0, v[8:9]
	v_ashrrev_i32_e32 v1, 31, v0
	v_lshl_add_u64 v[0:1], v[0:1], 1, v[8:9]
	s_waitcnt lgkmcnt(12)
	global_store_dwordx4 v[0:1], v[76:79], off
	v_add_u32_e32 v2, 0x200, v2
	v_and_b32_e32 v1, 0xf8, v3
	v_or_b32_e32 v0, s26, v1
	v_ashrrev_i32_e32 v8, 5, v2
	v_add_u32_e32 v8, s27, v8
	v_ashrrev_i32_e32 v9, 31, v8
	v_lshlrev_b64 v[8:9], 11, v[8:9]
	v_lshl_add_u64 v[8:9], s[8:9], 0, v[8:9]
	v_ashrrev_i32_e32 v1, 31, v0
	v_lshl_add_u64 v[0:1], v[0:1], 1, v[8:9]
	s_waitcnt lgkmcnt(11)
	global_store_dwordx4 v[0:1], v[80:83], off
	v_add_u32_e32 v2, 0x200, v2
	v_and_b32_e32 v1, 0xf8, v3
	v_or_b32_e32 v0, s26, v1
	v_ashrrev_i32_e32 v8, 5, v2
	v_add_u32_e32 v8, s27, v8
	v_ashrrev_i32_e32 v9, 31, v8
	v_lshlrev_b64 v[8:9], 11, v[8:9]
	v_lshl_add_u64 v[8:9], s[8:9], 0, v[8:9]
	v_ashrrev_i32_e32 v1, 31, v0
	v_lshl_add_u64 v[0:1], v[0:1], 1, v[8:9]
	s_waitcnt lgkmcnt(10)
	global_store_dwordx4 v[0:1], v[84:87], off
	v_add_u32_e32 v2, 0x200, v2
	v_and_b32_e32 v1, 0xf8, v3
	v_or_b32_e32 v0, s26, v1
	v_ashrrev_i32_e32 v8, 5, v2
	v_add_u32_e32 v8, s27, v8
	v_ashrrev_i32_e32 v9, 31, v8
	v_lshlrev_b64 v[8:9], 11, v[8:9]
	v_lshl_add_u64 v[8:9], s[8:9], 0, v[8:9]
	v_ashrrev_i32_e32 v1, 31, v0
	v_lshl_add_u64 v[0:1], v[0:1], 1, v[8:9]
	s_waitcnt lgkmcnt(9)
	global_store_dwordx4 v[0:1], v[88:91], off
	v_add_u32_e32 v2, 0x200, v2
	v_and_b32_e32 v1, 0xf8, v3
	v_or_b32_e32 v0, s26, v1
	v_ashrrev_i32_e32 v8, 5, v2
	v_add_u32_e32 v8, s27, v8
	v_ashrrev_i32_e32 v9, 31, v8
	v_lshlrev_b64 v[8:9], 11, v[8:9]
	v_lshl_add_u64 v[8:9], s[8:9], 0, v[8:9]
	v_ashrrev_i32_e32 v1, 31, v0
	v_lshl_add_u64 v[0:1], v[0:1], 1, v[8:9]
	s_waitcnt lgkmcnt(8)
	global_store_dwordx4 v[0:1], v[92:95], off
	v_add_u32_e32 v2, 0x200, v2
	v_and_b32_e32 v1, 0xf8, v3
	v_or_b32_e32 v0, s26, v1
	v_ashrrev_i32_e32 v8, 5, v2
	v_add_u32_e32 v8, s27, v8
	v_ashrrev_i32_e32 v9, 31, v8
	v_lshlrev_b64 v[8:9], 11, v[8:9]
	v_lshl_add_u64 v[8:9], s[8:9], 0, v[8:9]
	v_ashrrev_i32_e32 v1, 31, v0
	v_lshl_add_u64 v[0:1], v[0:1], 1, v[8:9]
	s_waitcnt lgkmcnt(7)
	global_store_dwordx4 v[0:1], v[96:99], off
	v_add_u32_e32 v2, 0x200, v2
	v_and_b32_e32 v1, 0xf8, v3
	v_or_b32_e32 v0, s26, v1
	v_ashrrev_i32_e32 v8, 5, v2
	v_add_u32_e32 v8, s27, v8
	v_ashrrev_i32_e32 v9, 31, v8
	v_lshlrev_b64 v[8:9], 11, v[8:9]
	v_lshl_add_u64 v[8:9], s[8:9], 0, v[8:9]
	v_ashrrev_i32_e32 v1, 31, v0
	v_lshl_add_u64 v[0:1], v[0:1], 1, v[8:9]
	s_waitcnt lgkmcnt(6)
	global_store_dwordx4 v[0:1], v[100:103], off
	v_add_u32_e32 v2, 0x200, v2
	v_and_b32_e32 v1, 0xf8, v3
	v_or_b32_e32 v0, s26, v1
	v_ashrrev_i32_e32 v8, 5, v2
	v_add_u32_e32 v8, s27, v8
	v_ashrrev_i32_e32 v9, 31, v8
	v_lshlrev_b64 v[8:9], 11, v[8:9]
	v_lshl_add_u64 v[8:9], s[8:9], 0, v[8:9]
	v_ashrrev_i32_e32 v1, 31, v0
	v_lshl_add_u64 v[0:1], v[0:1], 1, v[8:9]
	s_waitcnt lgkmcnt(5)
	global_store_dwordx4 v[0:1], v[104:107], off
	v_add_u32_e32 v2, 0x200, v2
	v_and_b32_e32 v1, 0xf8, v3
	v_or_b32_e32 v0, s26, v1
	v_ashrrev_i32_e32 v8, 5, v2
	v_add_u32_e32 v8, s27, v8
	v_ashrrev_i32_e32 v9, 31, v8
	v_lshlrev_b64 v[8:9], 11, v[8:9]
	v_lshl_add_u64 v[8:9], s[8:9], 0, v[8:9]
	v_ashrrev_i32_e32 v1, 31, v0
	v_lshl_add_u64 v[0:1], v[0:1], 1, v[8:9]
	s_waitcnt lgkmcnt(4)
	global_store_dwordx4 v[0:1], v[108:111], off
	v_add_u32_e32 v2, 0x200, v2
	v_and_b32_e32 v1, 0xf8, v3
	v_or_b32_e32 v0, s26, v1
	v_ashrrev_i32_e32 v8, 5, v2
	v_add_u32_e32 v8, s27, v8
	v_ashrrev_i32_e32 v9, 31, v8
	v_lshlrev_b64 v[8:9], 11, v[8:9]
	v_lshl_add_u64 v[8:9], s[8:9], 0, v[8:9]
	v_ashrrev_i32_e32 v1, 31, v0
	v_lshl_add_u64 v[0:1], v[0:1], 1, v[8:9]
	s_waitcnt lgkmcnt(3)
	global_store_dwordx4 v[0:1], v[112:115], off
	v_add_u32_e32 v2, 0x200, v2
	v_and_b32_e32 v1, 0xf8, v3
	v_or_b32_e32 v0, s26, v1
	v_ashrrev_i32_e32 v8, 5, v2
	v_add_u32_e32 v8, s27, v8
	v_ashrrev_i32_e32 v9, 31, v8
	v_lshlrev_b64 v[8:9], 11, v[8:9]
	v_lshl_add_u64 v[8:9], s[8:9], 0, v[8:9]
	v_ashrrev_i32_e32 v1, 31, v0
	v_lshl_add_u64 v[0:1], v[0:1], 1, v[8:9]
	s_waitcnt lgkmcnt(2)
	global_store_dwordx4 v[0:1], v[116:119], off
	v_add_u32_e32 v2, 0x200, v2
	v_and_b32_e32 v1, 0xf8, v3
	v_or_b32_e32 v0, s26, v1
	v_ashrrev_i32_e32 v8, 5, v2
	v_add_u32_e32 v8, s27, v8
	v_ashrrev_i32_e32 v9, 31, v8
	v_lshlrev_b64 v[8:9], 11, v[8:9]
	v_lshl_add_u64 v[8:9], s[8:9], 0, v[8:9]
	v_ashrrev_i32_e32 v1, 31, v0
	v_lshl_add_u64 v[0:1], v[0:1], 1, v[8:9]
	s_waitcnt lgkmcnt(1)
	global_store_dwordx4 v[0:1], v[120:123], off
	v_add_u32_e32 v2, 0x200, v2
	v_and_b32_e32 v1, 0xf8, v3
	v_or_b32_e32 v0, s26, v1
	v_ashrrev_i32_e32 v8, 5, v2
	v_add_u32_e32 v8, s27, v8
	v_ashrrev_i32_e32 v9, 31, v8
	v_lshlrev_b64 v[8:9], 11, v[8:9]
	v_lshl_add_u64 v[8:9], s[8:9], 0, v[8:9]
	v_ashrrev_i32_e32 v1, 31, v0
	v_lshl_add_u64 v[0:1], v[0:1], 1, v[8:9]
	s_waitcnt lgkmcnt(0)
	global_store_dwordx4 v[0:1], v[124:127], off
.Lep_done_671:
	s_or_b64 exec, exec, s[14:15]
	s_branch .LBB0_671

; DI int tid512() { int t = threadIdx_x_raw(); asm volatile("" : "+v"(t)); return t; }
;   DI void operator()(bf16_t* sCb) const {
;     ...
;       if (nt >= 4 && nt < 12) {
;         bf16_t* tp = (bf16_t*)(ws + (nt < 8 ? OFF_RKT : OFF_RVT));
;         int hh = (nt - 4) & 3;
;         for (int id = tid512(); id < 128 * 32; id += 512) {
;           int col = id & 127, rch = id >> 7;
;           unsigned short e[8];
; #pragma unroll
;           for (int j = 0; j < 8; ++j) e[j] = base[(rch * 8 + j) * BLD + col];
;           u32x4 o = {(unsigned)e[0] | ((unsigned)e[1] << 16), (unsigned)e[2] | ((unsigned)e[3] << 16), (unsigned)e[4] | ((unsigned)e[5] << 16), (unsigned)e[6] | ((unsigned)e[7] << 16)};
;           *(u32x4*)(tp + ((size_t)(b * 4 + hh) * 128 + col) * 4096 + s0 + rch * 8) = o;
;         }
.LBB0_793:
	v_mov_b32_e32 v1, v196
	s_nop 0
	v_cmp_gt_i32_e32 vcc, s50, v1
	s_and_saveexec_b64 s[26:27], vcc
	s_cbranch_execz .LBB0_772
	s_and_b32 s28, s57, 3
	s_or_b32 s28, s28, s53
	s_ashr_i32 s29, s28, 31
	s_lshl_b64 s[28:29], s[28:29], 20
	s_add_u32 s28, s55, s28
	s_addc_u32 s29, s56, s29
	v_and_b32_e32 v2, 7, v196
	v_bfe_u32 v3, v196, 3, 5
	v_lshrrev_b32_e32 v4, 8, v196
	v_lshl_or_b32 v2, v4, 3, v2
	v_mul_u32_u24_e32 v0, 0x1080, v3
	v_lshl_add_u32 v0, v2, 1, v0
	v_add_u32_e32 v0, s58, v0
	v_lshlrev_b32_e32 v128, 13, v2
	v_lshl_add_u32 v128, v3, 4, v128
	v_lshl_add_u64 v[2:3], s[28:29], 0, v[128:129]
	s_mov_b32 s30, 0x20000
	s_mov_b32 s31, 0
	ds_read_u16 v10, v0
	ds_read_u16 v11, v0 offset:528
	ds_read_u16 v12, v0 offset:1056
	ds_read_u16 v13, v0 offset:1584
	ds_read_u16 v14, v0 offset:2112
	ds_read_u16 v15, v0 offset:2640
	ds_read_u16 v16, v0 offset:3168
	ds_read_u16 v17, v0 offset:3696
	v_add_u32_e32 v0, 32, v0
	ds_read_u16 v18, v0
	ds_read_u16 v19, v0 offset:528
	ds_read_u16 v20, v0 offset:1056
	ds_read_u16 v21, v0 offset:1584
	ds_read_u16 v22, v0 offset:2112
	ds_read_u16 v23, v0 offset:2640
	ds_read_u16 v24, v0 offset:3168
	ds_read_u16 v25, v0 offset:3696
	s_waitcnt lgkmcnt(8)
	v_perm_b32 v4, v11, v10, s51
	v_perm_b32 v5, v13, v12, s51
	v_perm_b32 v6, v15, v14, s51
	v_perm_b32 v7, v17, v16, s51
	global_store_dwordx4 v[2:3], v[4:7], off
	v_lshl_add_u64 v[2:3], v[2:3], 0, s[30:31]
	v_add_u32_e32 v0, 32, v0
	ds_read_u16 v10, v0
	ds_read_u16 v11, v0 offset:528
	ds_read_u16 v12, v0 offset:1056
	ds_read_u16 v13, v0 offset:1584
	ds_read_u16 v14, v0 offset:2112
	ds_read_u16 v15, v0 offset:2640
	ds_read_u16 v16, v0 offset:3168
	ds_read_u16 v17, v0 offset:3696
	s_waitcnt lgkmcnt(8)
	v_perm_b32 v4, v19, v18, s51
	v_perm_b32 v5, v21, v20, s51
	v_perm_b32 v6, v23, v22, s51
	v_perm_b32 v7, v25, v24, s51
	global_store_dwordx4 v[2:3], v[4:7], off
	v_lshl_add_u64 v[2:3], v[2:3], 0, s[30:31]
	v_add_u32_e32 v0, 32, v0
	ds_read_u16 v18, v0
	ds_read_u16 v19, v0 offset:528
	ds_read_u16 v20, v0 offset:1056
	ds_read_u16 v21, v0 offset:1584
	ds_read_u16 v22, v0 offset:2112
	ds_read_u16 v23, v0 offset:2640
	ds_read_u16 v24, v0 offset:3168
	ds_read_u16 v25, v0 offset:3696
	s_waitcnt lgkmcnt(8)
	v_perm_b32 v4, v11, v10, s51
	v_perm_b32 v5, v13, v12, s51
	v_perm_b32 v6, v15, v14, s51
	v_perm_b32 v7, v17, v16, s51
	global_store_dwordx4 v[2:3], v[4:7], off
	v_lshl_add_u64 v[2:3], v[2:3], 0, s[30:31]
	v_add_u32_e32 v0, 32, v0
	ds_read_u16 v10, v0
	ds_read_u16 v11, v0 offset:528
	ds_read_u16 v12, v0 offset:1056
	ds_read_u16 v13, v0 offset:1584
	ds_read_u16 v14, v0 offset:2112
	ds_read_u16 v15, v0 offset:2640
	ds_read_u16 v16, v0 offset:3168
	ds_read_u16 v17, v0 offset:3696
	s_waitcnt lgkmcnt(8)
	v_perm_b32 v4, v19, v18, s51
	v_perm_b32 v5, v21, v20, s51
	v_perm_b32 v6, v23, v22, s51
	v_perm_b32 v7, v25, v24, s51
	global_store_dwordx4 v[2:3], v[4:7], off
	v_lshl_add_u64 v[2:3], v[2:3], 0, s[30:31]
	v_add_u32_e32 v0, 32, v0
	ds_read_u16 v18, v0
	ds_read_u16 v19, v0 offset:528
	ds_read_u16 v20, v0 offset:1056
	ds_read_u16 v21, v0 offset:1584
	ds_read_u16 v22, v0 offset:2112
	ds_read_u16 v23, v0 offset:2640
	ds_read_u16 v24, v0 offset:3168
	ds_read_u16 v25, v0 offset:3696
	s_waitcnt lgkmcnt(8)
	v_perm_b32 v4, v11, v10, s51
	v_perm_b32 v5, v13, v12, s51
	v_perm_b32 v6, v15, v14, s51
	v_perm_b32 v7, v17, v16, s51
	global_store_dwordx4 v[2:3], v[4:7], off
	v_lshl_add_u64 v[2:3], v[2:3], 0, s[30:31]
	v_add_u32_e32 v0, 32, v0
	ds_read_u16 v10, v0
	ds_read_u16 v11, v0 offset:528
	ds_read_u16 v12, v0 offset:1056
	ds_read_u16 v13, v0 offset:1584
	ds_read_u16 v14, v0 offset:2112
	ds_read_u16 v15, v0 offset:2640
	ds_read_u16 v16, v0 offset:3168
	ds_read_u16 v17, v0 offset:3696
	s_waitcnt lgkmcnt(8)
	v_perm_b32 v4, v19, v18, s51
	v_perm_b32 v5, v21, v20, s51
	v_perm_b32 v6, v23, v22, s51
	v_perm_b32 v7, v25, v24, s51
	global_store_dwordx4 v[2:3], v[4:7], off
	v_lshl_add_u64 v[2:3], v[2:3], 0, s[30:31]
	v_add_u32_e32 v0, 32, v0
	ds_read_u16 v18, v0
	ds_read_u16 v19, v0 offset:528
	ds_read_u16 v20, v0 offset:1056
	ds_read_u16 v21, v0 offset:1584
	ds_read_u16 v22, v0 offset:2112
	ds_read_u16 v23, v0 offset:2640
	ds_read_u16 v24, v0 offset:3168
	ds_read_u16 v25, v0 offset:3696
	s_waitcnt lgkmcnt(8)
	v_perm_b32 v4, v11, v10, s51
	v_perm_b32 v5, v13, v12, s51
	v_perm_b32 v6, v15, v14, s51
	v_perm_b32 v7, v17, v16, s51
	global_store_dwordx4 v[2:3], v[4:7], off
	v_lshl_add_u64 v[2:3], v[2:3], 0, s[30:31]
	s_waitcnt lgkmcnt(0)
	v_perm_b32 v4, v19, v18, s51
	v_perm_b32 v5, v21, v20, s51
	v_perm_b32 v6, v23, v22, s51
	v_perm_b32 v7, v25, v24, s51
	global_store_dwordx4 v[2:3], v[4:7], off
	s_branch .LBB0_772

; DI int tidx() { return tid512() & 255; }
; DI float log_sigmoid(float x) { return fminf(x, 0.f) - log1pf(expf(-fabsf(x))); }
; DI void retention_out_unit(const Params& p, int unit, char* smem) {
;   const int tid = tidx(), lane = tid & 63, w = tid >> 6, r = lane & 31, h = lane >> 5;
;   const int n = unit & 31, bh = unit >> 5, hh = bh & 3, b = bh >> 2;
;   const size_t tok0 = (size_t)b * 4096 + n * 128;
;   bf16_t* sT = (bf16_t*)smem;
;   const float lgf = log_sigmoid(p.c_decay_f[hh]) * LOG2E, lgb = log_sigmoid(p.c_decay_b[hh]) * LOG2E;
;   const bf16_t* qp = (const bf16_t*)(p.ws + OFF_RQ) + (tok0 + 32 * w + r) * 512 + hh * 128 + 8 * h;
;   int cq = 32 * w + r;
;   asm volatile("" : "+v"(cq));
;   stage_tile128(sT, (const bf16_t*)(p.ws + OFF_RK) + tok0 * 512 + hh * 128, 512, false);
.LBB0_993:
	s_and_b64 vcc, exec, s[2:3]
	s_cbranch_vccz .LBB0_986
	s_ashr_i32 s22, s0, 5
	s_and_b32 s4, s22, 3
	s_lshl_b32 s1, s4, 2
	v_readlane_b32 s52, v247, 34
	v_mov_b32_e32 v0, v196
	v_mov_b32_e32 v2, s1
	v_readlane_b32 s54, v247, 36
	v_readlane_b32 s55, v247, 37
	s_ashr_i32 s2, s0, 7
	s_lshl_b32 s1, s0, 7
	s_ashr_i32 s3, s2, 31
	s_and_b32 s1, s1, 0xf80
	s_nop 0
	global_load_dword v14, v2, s[54:55]
	s_lshl_b64 s[2:3], s[2:3], 12
	v_readlane_b32 s56, v247, 38
	v_readlane_b32 s57, v247, 39
	v_readlane_b32 s60, v247, 42
	s_or_b32 s2, s2, s1
	s_lshl_b32 s60, s4, 7
	s_lshl_b32 s4, s4, 8
	v_and_b32_e32 v64, 31, v0
	global_load_dword v35, v2, s[56:57]
	s_lshl_b64 s[54:55], s[2:3], 10
	v_bfe_u32 v146, v0, 5, 1
	v_lshrrev_b32_e32 v0, 1, v0
	s_add_u32 s23, s18, s54
	v_mov_b32_e32 v4, v196
	v_and_or_b32 v132, v0, s74, v64
	s_addc_u32 s55, s19, s55
	v_or_b32_e32 v34, s2, v132
	s_add_u32 s54, s23, s4
	v_lshlrev_b32_e32 v0, 4, v4
	v_bfe_u32 v52, v4, 4, 4
	v_mov_b32_e32 v33, v129
	v_and_b32_e32 v32, 0xf0, v0
	v_lshlrev_b32_e32 v24, 10, v52
	s_addc_u32 s55, s55, 0
	v_mov_b32_e32 v1, v129
	v_or_b32_e32 v0, 0x4000, v24
	v_lshl_add_u64 v[26:27], s[54:55], 0, v[32:33]
	v_mov_b32_e32 v3, v129
	v_or_b32_e32 v2, 0x8000, v24
	v_lshl_add_u64 v[8:9], v[26:27], 0, v[0:1]
	v_lshl_add_u64 v[10:11], v[26:27], 0, v[2:3]
	v_mov_b32_e32 v25, v129
	v_mov_b32_e32 v5, v129
	v_or_b32_e32 v4, 0xc000, v24
	v_lshl_add_u64 v[6:7], v[26:27], 0, v[24:25]
	s_waitcnt vmcnt(63) expcnt(7) lgkmcnt(15)
	s_barrier
	v_lshl_add_u64 v[12:13], v[26:27], 0, v[4:5]
	v_or_b32_e32 v28, 0x18000, v24
	v_mov_b32_e32 v29, v129
	v_lshl_add_u64 v[28:29], v[26:27], 0, v[28:29]
	v_lshlrev_b32_e32 v128, 4, v146
	s_waitcnt vmcnt(11)
	v_mad_i32_i24 v100, v146, -4, -1
	v_mad_i32_i24 v101, v146, -4, -2
	v_mad_i32_i24 v102, v146, -4, -3
	v_mad_i32_i24 v103, v146, -4, -8
	s_waitcnt vmcnt(10)
	v_mad_i32_i24 v104, v146, -4, -9
	v_mad_i32_i24 v99, v146, -4, -10
	v_mad_i32_i24 v91, v146, -4, -11
	v_mad_i32_i24 v92, v146, -4, -16
	v_mad_i32_i24 v93, v146, -4, v139
	v_mad_i32_i24 v94, v146, -4, v140
	v_mad_i32_i24 v97, v146, -4, v141
	v_mad_i32_i24 v90, v146, -4, v142
	v_mad_i32_i24 v95, v146, -4, v143
	v_mad_i32_i24 v98, v146, -4, v144
	v_mad_i32_i24 v96, v146, -4, v145
	v_subrev_u32_e32 v87, 32, v132
	s_ashr_i32 s23, s22, 31
	s_lshl_b64 s[22:23], s[22:23], 20
	v_readlane_b32 s53, v247, 35
	v_readlane_b32 s58, v247, 40
	v_readlane_b32 s59, v247, 41
	v_readlane_b32 s44, v246, 17
	v_readlane_b32 s58, v246, 31
	v_readlane_b32 s59, v246, 32
	v_readlane_b32 s61, v247, 43
	v_readlane_b32 s62, v247, 44
	v_readlane_b32 s63, v247, 45
	v_readlane_b32 s64, v247, 46
	v_readlane_b32 s65, v247, 47
	v_readlane_b32 s66, v247, 48
	v_readlane_b32 s67, v247, 49
	v_readlane_b32 s45, v246, 18
	v_readlane_b32 s46, v246, 19
	v_readlane_b32 s47, v246, 20
	s_waitcnt vmcnt(1)
	v_mul_f32_e64 v0, |v14|, s42
	v_fma_f32 v1, |v14|, s42, -v0
	v_rndne_f32_e32 v2, v0
	v_fma_f32 v1, |v14|, s43, v1
	v_sub_f32_e32 v0, v0, v2
	v_add_f32_e32 v0, v0, v1
	v_cvt_i32_f32_e32 v15, v2
	v_exp_f32_e32 v16, v0
	global_load_dwordx4 v[0:3], v[6:7], off
	s_nop 0
	global_load_dwordx4 v[4:7], v[8:9], off
	v_max_f32_e32 v8, v14, v14
	v_min_f32_e32 v33, 0, v8
	v_ldexp_f32 v8, v16, v15
	v_cmp_ngt_f32_e64 vcc, |v14|, s10
	v_readlane_b32 s48, v246, 21
	v_readlane_b32 s49, v246, 22
	v_cndmask_b32_e32 v8, 0, v8, vcc
	v_cmp_nlt_f32_e64 vcc, |v14|, s11
	v_readlane_b32 s50, v246, 23
	v_readlane_b32 s51, v246, 24
	v_cndmask_b32_e32 v53, v138, v8, vcc
	v_add_f32_e32 v14, 1.0, v53
	v_add_f32_e32 v15, -1.0, v14
	v_frexp_mant_f32_e32 v16, v14
	v_cvt_f64_f32_e32 v[8:9], v14
	v_sub_f32_e32 v17, v15, v14
	v_frexp_exp_i32_f64_e32 v8, v[8:9]
	v_cmp_gt_f32_e32 vcc, s69, v16
	v_sub_f32_e32 v15, v53, v15
	v_add_f32_e32 v9, 1.0, v17
	v_subbrev_co_u32_e32 v8, vcc, 0, v8, vcc
	v_add_f32_e32 v9, v15, v9
	v_sub_u32_e32 v15, 0, v8
	v_cvt_f32_i32_e32 v36, v8
	v_ldexp_f32 v8, v14, v15
	v_ldexp_f32 v9, v9, v15
	v_add_f32_e32 v14, -1.0, v8
	v_add_f32_e32 v15, 1.0, v8
	v_add_f32_e32 v16, 1.0, v14
	v_add_f32_e32 v17, -1.0, v15
	v_sub_f32_e32 v16, v8, v16
	v_sub_f32_e32 v8, v8, v17
	v_add_f32_e32 v8, v9, v8
	v_add_f32_e32 v18, v15, v8
	v_rcp_f32_e32 v19, v18
	v_add_f32_e32 v16, v9, v16
	v_add_f32_e32 v9, v14, v16
	v_sub_f32_e32 v14, v14, v9
	v_mul_f32_e32 v22, v9, v19
	v_sub_f32_e32 v15, v15, v18
	v_add_f32_e32 v21, v16, v14
	v_mul_f32_e32 v14, v18, v22
	v_add_f32_e32 v20, v8, v15
	v_fma_f32 v16, v22, v18, -v14
	v_fmac_f32_e32 v16, v22, v20
	v_add_f32_e32 v8, v14, v16
	v_sub_f32_e32 v15, v9, v8
	v_mov_b32_e32 v17, v8
	v_pk_add_f32 v[8:9], v[8:9], v[14:15] neg_lo:[0,1] neg_hi:[0,1]
	v_cmp_neq_f32_e32 vcc, s40, v53
	v_pk_add_f32 v[8:9], v[8:9], v[16:17] neg_lo:[0,1] neg_hi:[0,1]
	v_readlane_b32 s52, v246, 25
	v_add_f32_e32 v9, v21, v9
	v_add_f32_e32 v8, v8, v9
	v_add_f32_e32 v9, v15, v8
	v_mul_f32_e32 v17, v19, v9
	v_mul_f32_e32 v14, v18, v17
	v_sub_f32_e32 v15, v15, v9
	v_add_f32_e32 v23, v22, v17
	v_fma_f32 v16, v17, v18, -v14
	v_add_f32_e32 v21, v8, v15
	v_sub_f32_e32 v8, v23, v22
	v_fmac_f32_e32 v16, v17, v20
	v_sub_f32_e32 v18, v17, v8
	v_add_f32_e32 v8, v14, v16
	v_sub_f32_e32 v15, v9, v8
	v_mov_b32_e32 v17, v8
	v_pk_add_f32 v[8:9], v[8:9], v[14:15] neg_lo:[0,1] neg_hi:[0,1]
	v_readlane_b32 s53, v246, 26
	v_pk_add_f32 v[8:9], v[8:9], v[16:17] neg_lo:[0,1] neg_hi:[0,1]
	v_mov_b32_e32 v17, v129
	v_add_f32_e32 v9, v21, v9
	v_add_f32_e32 v8, v8, v9
	v_add_f32_e32 v8, v15, v8
	v_mul_f32_e32 v8, v19, v8
	v_add_f32_e32 v8, v18, v8
	v_add_f32_e32 v9, v23, v8
	v_mul_f32_e32 v14, v9, v9
	v_fmamk_f32 v16, v14, 0x3e9b6dac, v136
	v_sub_f32_e32 v15, v9, v23
	v_fmaak_f32 v131, v14, v16, 0x3f2aaada
; DI int tidx() { return tid512() & 255; }
; DI float log_sigmoid(float x) { return fminf(x, 0.f) - log1pf(expf(-fabsf(x))); }
; DI void stage_tile128(bf16_t* sT, const bf16_t* __restrict__ src, size_t ld, bool perm) {
;   const int tid = tidx();
;   __syncthreads();
; #pragma unroll
;   for (int hlf = 0; hlf < 2; ++hlf) {
;     u32x4 regs[4];
; #pragma unroll
;     for (int i = 0; i < 4; ++i) { int id = tid + 256 * (4 * hlf + i); int row = id >> 4, ck = id & 15; regs[i] = ldg16(src + (size_t)row * ld + ck * 8); }
; #pragma unroll
;     for (int i = 0; i < 4; ++i) {
;       int id = tid + 256 * (4 * hlf + i); int row = id >> 4, ck = id & 15;
;       if (!perm) *(u32x4*)(sT + row * 136 + ck * 8) = regs[i];
;       else {
;         int g = ck >> 1, odd = ck & 1;
;         u32x2 lo = {regs[i][0], regs[i][1]}, hi = {regs[i][2], regs[i][3]};
;         *(u32x2*)(sT + row * 136 + g * 16 + (odd ? 4 : 0)) = lo;
;         *(u32x2*)(sT + row * 136 + g * 16 + (odd ? 12 : 8)) = hi;
;       }
;     }
;   }
;   __syncthreads();
; }
; DI void load_qf8(const bf16_t* __restrict__ qp, u32x4* qf) {
; #pragma unroll
;   for (int ds = 0; ds < 8; ++ds) qf[ds] = ldg16(qp + 16 * ds);
; }
; DI void retention_out_unit(const Params& p, int unit, char* smem) {
;   const int tid = tidx(), lane = tid & 63, w = tid >> 6, r = lane & 31, h = lane >> 5;
;   const int n = unit & 31, bh = unit >> 5, hh = bh & 3, b = bh >> 2;
;   const size_t tok0 = (size_t)b * 4096 + n * 128;
;   bf16_t* sT = (bf16_t*)smem;
;   const float lgf = log_sigmoid(p.c_decay_f[hh]) * LOG2E, lgb = log_sigmoid(p.c_decay_b[hh]) * LOG2E;
;   const bf16_t* qp = (const bf16_t*)(p.ws + OFF_RQ) + (tok0 + 32 * w + r) * 512 + hh * 128 + 8 * h;
;   int cq = 32 * w + r;
;   asm volatile("" : "+v"(cq));
;   stage_tile128(sT, (const bf16_t*)(p.ws + OFF_RK) + tok0 * 512 + hh * 128, 512, false);
;   u32x4 pf[8];
;   {
;     u32x4 qf[8];
;     load_qf8(qp, qf);
	v_or_b32_e32 v16, 0x10000, v24
	v_or_b32_e32 v18, 0x14000, v24
	v_mov_b32_e32 v19, v129
	v_or_b32_e32 v24, 0x1c000, v24
	v_sub_f32_e32 v8, v8, v15
	v_lshl_add_u64 v[16:17], v[26:27], 0, v[16:17]
	v_lshl_add_u64 v[20:21], v[26:27], 0, v[18:19]
	v_lshl_add_u64 v[30:31], v[26:27], 0, v[24:25]
	v_ldexp_f32 v39, v9, 1
	v_mul_f32_e32 v37, v9, v14
	v_ldexp_f32 v42, v8, 1
	global_load_dwordx4 v[8:11], v[10:11], off
	s_nop 0
	global_load_dwordx4 v[12:15], v[12:13], off
	s_nop 0
	global_load_dwordx4 v[16:19], v[16:17], off
	s_nop 0
	global_load_dwordx4 v[20:23], v[20:21], off
	s_nop 0
	global_load_dwordx4 v[24:27], v[28:29], off
	s_nop 0
	global_load_dwordx4 v[28:31], v[30:31], off
	v_pk_mul_f32 v[40:41], v[36:37], v[130:131]
	v_readlane_b32 s54, v246, 27
	v_fma_f32 v38, v36, s70, -v40
	v_fmac_f32_e32 v38, 0xb102e308, v36
	v_pk_add_f32 v[36:37], v[40:41], v[38:39]
	v_readlane_b32 s55, v246, 28
	v_sub_f32_e32 v39, v37, v39
	v_sub_f32_e32 v39, v41, v39
	v_add_f32_e32 v43, v42, v39
	v_mov_b32_e32 v42, v40
	v_pk_add_f32 v[40:41], v[36:37], v[40:41] neg_lo:[0,1] neg_hi:[0,1]
	v_pk_add_f32 v[44:45], v[36:37], v[42:43]
	v_mov_b32_e32 v39, v36
	v_mov_b32_e32 v41, v45
	v_pk_add_f32 v[46:47], v[38:39], v[40:41] neg_lo:[0,1] neg_hi:[0,1]
	v_pk_add_f32 v[38:39], v[38:39], v[40:41]
	v_mov_b32_e32 v50, v37
	v_pk_add_f32 v[40:41], v[38:39], v[36:37] op_sel:[1,0] op_sel_hi:[0,1] neg_lo:[0,1] neg_hi:[0,1]
	v_pk_add_f32 v[48:49], v[44:45], v[40:41] op_sel_hi:[1,0] neg_lo:[0,1] neg_hi:[0,1]
	v_mov_b32_e32 v44, v45
	v_mov_b32_e32 v45, v39
	v_mov_b32_e32 v51, v40
	v_pk_add_f32 v[40:41], v[44:45], v[50:51] neg_lo:[0,1] neg_hi:[0,1]
	v_mov_b32_e32 v42, v43
	v_mov_b32_e32 v43, v36
	v_pk_add_f32 v[36:37], v[42:43], v[40:41] neg_lo:[0,1] neg_hi:[0,1]
	v_mov_b32_e32 v48, v46
	v_pk_add_f32 v[40:41], v[48:49], v[36:37]
	v_mov_b32_e32 v47, v39
	v_pk_add_f32 v[42:43], v[40:41], v[40:41] op_sel:[0,1] op_sel_hi:[1,0]
	v_readlane_b32 s56, v246, 29
	v_pk_add_f32 v[38:39], v[38:39], v[42:43] op_sel:[1,0] op_sel_hi:[0,1]
	v_mov_b32_e32 v41, v38
	v_pk_add_f32 v[44:45], v[40:41], v[46:47] neg_lo:[0,1] neg_hi:[0,1]
	v_mov_b32_e32 v37, v42
	v_sub_f32_e32 v39, v40, v44
	v_pk_add_f32 v[36:37], v[36:37], v[44:45] neg_lo:[0,1] neg_hi:[0,1]
	v_sub_f32_e32 v39, v46, v39
	v_add_f32_e32 v36, v36, v39
	v_add_f32_e32 v36, v36, v37
	v_add_f32_e32 v36, v38, v36
	v_cndmask_b32_e32 v36, v138, v36, vcc
	v_cmp_lt_f32_e64 vcc, |v53|, s71
	v_readlane_b32 s57, v246, 30
	s_nop 0
	v_cndmask_b32_e32 v36, v36, v53, vcc
	v_sub_f32_e32 v33, v33, v36
	s_waitcnt vmcnt(8)
	v_mul_f32_e64 v36, |v35|, s42
	v_fma_f32 v37, |v35|, s42, -v36
	v_rndne_f32_e32 v38, v36
	v_fma_f32 v37, |v35|, s43, v37
	v_sub_f32_e32 v36, v36, v38
	v_add_f32_e32 v36, v36, v37
	v_exp_f32_e32 v36, v36
	v_cvt_i32_f32_e32 v37, v38
	v_mul_f32_e32 v88, 0x3fb8aa3b, v33
	v_max_f32_e32 v33, v35, v35
	v_min_f32_e32 v70, 0, v33
	v_ldexp_f32 v33, v36, v37
	v_cmp_ngt_f32_e64 vcc, |v35|, s10
	s_nop 1
	v_cndmask_b32_e32 v33, 0, v33, vcc
	v_cmp_nlt_f32_e64 vcc, |v35|, s11
	s_nop 1
	v_cndmask_b32_e32 v71, v138, v33, vcc
	v_add_f32_e32 v33, 1.0, v71
	v_add_f32_e32 v35, -1.0, v33
	v_sub_f32_e32 v36, v35, v33
	v_add_f32_e32 v36, 1.0, v36
	v_sub_f32_e32 v35, v71, v35
	v_add_f32_e32 v36, v35, v36
	v_mov_b32_e32 v35, s3
	v_lshlrev_b64 v[34:35], 10, v[34:35]
	v_lshl_add_u64 v[34:35], s[72:73], 0, v[34:35]
	v_lshl_add_u64 v[34:35], v[34:35], 0, s[4:5]
	v_lshl_add_u64 v[134:135], v[34:35], 0, v[128:129]
	v_mul_u32_u24_e32 v34, 0x110, v52
	v_add3_u32 v32, s24, v32, v34
	s_waitcnt vmcnt(7)
	ds_write_b128 v32, v[0:3]
	s_waitcnt vmcnt(6)
	ds_write_b128 v32, v[4:7] offset:4352
	s_waitcnt vmcnt(5)
	ds_write_b128 v32, v[8:11] offset:8704
	s_waitcnt vmcnt(4)
	ds_write_b128 v32, v[12:15] offset:13056
	s_waitcnt vmcnt(3)
	ds_write_b128 v32, v[16:19] offset:17408
	s_waitcnt vmcnt(2)
	ds_write_b128 v32, v[20:23] offset:21760
	s_waitcnt vmcnt(1)
	ds_write_b128 v32, v[24:27] offset:26112
	s_waitcnt vmcnt(0)
	ds_write_b128 v32, v[28:31] offset:30464
	s_waitcnt lgkmcnt(0)
	s_barrier
	global_load_dwordx4 v[60:63], v[134:135], off
	global_load_dwordx4 v[56:59], v[134:135], off offset:32
	global_load_dwordx4 v[52:55], v[134:135], off offset:64
	global_load_dwordx4 v[48:51], v[134:135], off offset:96
	v_frexp_mant_f32_e32 v37, v33
	v_cvt_f64_f32_e32 v[0:1], v33
	v_frexp_exp_i32_f64_e32 v0, v[0:1]
	v_cmp_gt_f32_e32 vcc, s69, v37
	global_load_dwordx4 v[44:47], v[134:135], off offset:128
	global_load_dwordx4 v[40:43], v[134:135], off offset:160
	v_subbrev_co_u32_e32 v8, vcc, 0, v0, vcc
	v_sub_u32_e32 v0, 0, v8
	v_ldexp_f32 v1, v33, v0
	v_add_f32_e32 v2, -1.0, v1
	v_add_f32_e32 v4, 1.0, v1
	v_add_f32_e32 v3, 1.0, v2
	v_add_f32_e32 v5, -1.0, v4
	v_ldexp_f32 v0, v36, v0
	v_sub_f32_e32 v3, v1, v3
	v_sub_f32_e32 v1, v1, v5
	v_add_f32_e32 v3, v0, v3
	v_add_f32_e32 v0, v0, v1
	v_add_f32_e32 v9, v4, v0
	v_rcp_f32_e32 v11, v9
	v_sub_f32_e32 v1, v4, v9
	v_add_f32_e32 v10, v0, v1
	v_add_f32_e32 v1, v2, v3
	v_mul_f32_e32 v13, v1, v11
	v_sub_f32_e32 v0, v2, v1
	v_mul_f32_e32 v2, v9, v13
	v_fma_f32 v4, v13, v9, -v2
	v_fmac_f32_e32 v4, v13, v10
	v_add_f32_e32 v12, v3, v0
	v_add_f32_e32 v0, v2, v4
	v_sub_f32_e32 v3, v1, v0
	global_load_dwordx4 v[36:39], v[134:135], off offset:192
	global_load_dwordx4 v[32:35], v[134:135], off offset:224
	v_pk_add_f32 v[6:7], v[0:1], v[2:3] neg_lo:[0,1] neg_hi:[0,1]
	v_mov_b32_e32 v5, v0
	v_pk_add_f32 v[0:1], v[6:7], v[4:5] neg_lo:[0,1] neg_hi:[0,1]
	v_cmp_neq_f32_e32 vcc, s40, v71
	v_add_f32_e32 v1, v12, v1
	v_add_f32_e32 v0, v0, v1
	v_add_f32_e32 v1, v3, v0
	v_mul_f32_e32 v12, v11, v1
	v_mul_f32_e32 v2, v9, v12
	v_fma_f32 v4, v12, v9, -v2
	v_fmac_f32_e32 v4, v12, v10
	v_sub_f32_e32 v3, v3, v1
	v_add_f32_e32 v9, v0, v3
	v_add_f32_e32 v0, v2, v4
	v_sub_f32_e32 v3, v1, v0
	v_pk_add_f32 v[6:7], v[0:1], v[2:3] neg_lo:[0,1] neg_hi:[0,1]
	v_mov_b32_e32 v5, v0
	v_pk_add_f32 v[0:1], v[6:7], v[4:5] neg_lo:[0,1] neg_hi:[0,1]
	v_cvt_f32_i32_e32 v4, v8
	v_add_f32_e32 v1, v9, v1
	v_add_f32_e32 v0, v0, v1
	v_add_f32_e32 v1, v13, v12
	v_add_f32_e32 v0, v3, v0
	v_sub_f32_e32 v2, v1, v13
	v_mul_f32_e32 v0, v11, v0
	v_sub_f32_e32 v2, v12, v2
	v_add_f32_e32 v0, v2, v0
	v_add_f32_e32 v5, v1, v0
	v_sub_f32_e32 v1, v5, v1
	v_mul_f32_e32 v6, v5, v5
	v_sub_f32_e32 v7, v0, v1
	v_mul_u32_u24_e32 v0, 0x110, v64
	v_fmamk_f32 v2, v6, 0x3e9b6dac, v136
	v_add3_u32 v133, s24, v128, v0
	v_fmaak_f32 v131, v6, v2, 0x3f2aaada
	ds_read_b128 v[0:3], v133
	ds_read_b128 v[16:19], v133 offset:32
	v_ldexp_f32 v25, v5, 1
	v_mul_f32_e32 v5, v5, v6
	v_pk_mul_f32 v[20:21], v[4:5], v[130:131]
	v_ldexp_f32 v22, v7, 1
	v_fma_f32 v24, v4, s70, -v20
	v_fmac_f32_e32 v24, 0xb102e308, v4
	s_waitcnt vmcnt(7) lgkmcnt(1)
; #define MFMA32(a, b, c) __builtin_amdgcn_mfma_f32_32x32x16_bf16(__builtin_bit_cast(bf16x8, (a)), __builtin_bit_cast(bf16x8, (b)), (c), 0, 0, 0)
; DI unsigned pack2(float a, float b) { f2_t f = {a, b}; bf2_t r = __builtin_convertvector(f, bf2_t); return __builtin_bit_cast(unsigned, r); }
; DI float ex2(float x) { return __builtin_amdgcn_exp2f(x); }
; DI int crow(int reg, int h) { return (reg & 3) + 8 * (reg >> 2) + 4 * h; }
; DI void retention_out_unit(const Params& p, int unit, char* smem) {
;     ...
; #pragma unroll
;     for (int mb = 0; mb < 4; ++mb) {
;       f32x16 s;
; #pragma unroll
;       for (int q = 0; q < 16; ++q) s[q] = 0.f;
;       const bf16_t* cK = sT + (32 * mb + r) * 136 + 8 * h;
; #pragma unroll
;       for (int ds = 0; ds < 8; ++ds) { u32x4 k = *(const u32x4*)(cK + 16 * ds); s = MFMA32(k, qf[ds], s); }
; #pragma unroll
;       for (int q = 0; q < 16; ++q) {
;         int m = 32 * mb + crow(q, h);
;         int diff = cq - m;
;         float dec = (diff >= 0) ? ex2((float)diff * lgf) : ex2((float)(-diff) * lgb);
;         s[q] *= dec;
;       }
; #pragma unroll
;       for (int sx = 0; sx < 2; ++sx) {
;         pf[2 * mb + sx][0] = pack2(s[8 * sx], s[8 * sx + 1]); pf[2 * mb + sx][1] = pack2(s[8 * sx + 2], s[8 * sx + 3]);
;         pf[2 * mb + sx][2] = pack2(s[8 * sx + 4], s[8 * sx + 5]); pf[2 * mb + sx][3] = pack2(s[8 * sx + 6], s[8 * sx + 7]);
;       }
	v_mfma_f32_32x32x16_bf16 v[0:15], v[0:3], v[60:63], 0
	v_add_f32_e64 v26, v20, v24
	v_add_f32_e64 v27, v21, v25
	v_mov_b32_e32 v28, v20
	v_sub_f32_e32 v23, v27, v25
	v_sub_f32_e32 v23, v21, v23
	v_add_f32_e32 v29, v22, v23
	v_pk_add_f32 v[30:31], v[26:27], v[20:21] neg_lo:[0,1] neg_hi:[0,1]
	ds_read_b128 v[20:23], v133 offset:64
	s_waitcnt vmcnt(6) lgkmcnt(1)
	v_mfma_f32_32x32x16_bf16 v[0:15], v[16:19], v[56:59], v[0:15]
	ds_read_b128 v[16:19], v133 offset:96
	v_add_f32_e64 v64, v26, v28
	v_add_f32_e64 v65, v27, v29
	v_mov_b32_e32 v25, v26
	v_mov_b32_e32 v31, v65
	v_pk_add_f32 v[66:67], v[24:25], v[30:31] neg_lo:[0,1] neg_hi:[0,1]
	v_pk_add_f32 v[24:25], v[24:25], v[30:31]
	s_add_u32 s4, s27, s22
	s_waitcnt vmcnt(5) lgkmcnt(1)
	v_mfma_f32_32x32x16_bf16 v[0:15], v[20:23], v[52:55], v[0:15]
	v_add_f32_e64 v30, v25, -v26
	v_add_f32_e64 v31, v24, -v27
	v_mov_b32_e32 v20, v65
	v_mov_b32_e32 v21, v25
	v_mov_b32_e32 v22, v27
	v_mov_b32_e32 v23, v30
	v_pk_add_f32 v[68:69], v[64:65], v[30:31] op_sel_hi:[1,0] neg_lo:[0,1] neg_hi:[0,1]
	v_pk_add_f32 v[30:31], v[20:21], v[22:23] neg_lo:[0,1] neg_hi:[0,1]
	ds_read_b128 v[20:23], v133 offset:128
	s_waitcnt vmcnt(4) lgkmcnt(1)
	v_mfma_f32_32x32x16_bf16 v[0:15], v[16:19], v[48:51], v[0:15]
	v_mov_b32_e32 v16, v29
	v_mov_b32_e32 v17, v26
	v_add_f32_e64 v26, v16, -v30
	v_add_f32_e64 v27, v17, -v31
	ds_read_b128 v[16:19], v133 offset:160
	v_mov_b32_e32 v68, v66
	v_pk_add_f32 v[28:29], v[68:69], v[26:27]
	v_mov_b32_e32 v67, v25
	s_waitcnt vmcnt(3) lgkmcnt(1)
	v_mfma_f32_32x32x16_bf16 v[0:15], v[20:23], v[44:47], v[0:15]
	v_add_f32_e64 v30, v28, v29
	v_add_f32_e64 v31, v29, v28
	s_addc_u32 s23, s28, s23
	v_pk_add_f32 v[24:25], v[24:25], v[30:31] op_sel:[1,0] op_sel_hi:[0,1]
	v_mov_b32_e32 v29, v24
	v_pk_add_f32 v[20:21], v[28:29], v[66:67] neg_lo:[0,1] neg_hi:[0,1]
	v_mov_b32_e32 v27, v30
	v_pk_add_f32 v[26:27], v[26:27], v[20:21] neg_lo:[0,1] neg_hi:[0,1]
	v_sub_f32_e32 v25, v28, v20
	ds_read_b128 v[20:23], v133 offset:192
	s_waitcnt vmcnt(2) lgkmcnt(1)
	v_mfma_f32_32x32x16_bf16 v[0:15], v[16:19], v[40:43], v[0:15]
	v_sub_f32_e32 v16, v66, v25
	v_add_f32_e32 v16, v26, v16
	v_add_f32_e32 v16, v16, v27
	v_add_f32_e32 v16, v24, v16
	v_cndmask_b32_e32 v24, v138, v16, vcc
	ds_read_b128 v[16:19], v133 offset:224
	v_cmp_lt_f32_e64 vcc, |v71|, s71
	s_waitcnt vmcnt(1) lgkmcnt(1)
	v_mfma_f32_32x32x16_bf16 v[0:15], v[20:23], v[36:39], v[0:15]
	s_lshl_b32 s1, s1, 1
	v_cndmask_b32_e32 v20, v24, v71, vcc
	v_sub_f32_e32 v20, v70, v20
	v_mul_f32_e32 v89, 0x3fb8aa3b, v20
	v_mad_i32_i24 v20, v146, -4, v132
	v_sub_u32_e32 v21, 0, v20
	v_max_i32_e32 v21, v20, v21
	s_waitcnt vmcnt(0) lgkmcnt(0)
	v_mfma_f32_32x32x16_bf16 v[0:15], v[16:19], v[32:35], v[0:15]
	v_add_u32_e32 v17, v100, v132
	v_sub_u32_e32 v18, 0, v17
	v_max_i32_e32 v18, v17, v18
	v_cvt_f32_u32_e32 v21, v21
	v_cvt_f32_u32_e32 v18, v18
	v_cmp_gt_i32_e32 vcc, 0, v20
	ds_read_b128 v[64:67], v133 offset:8736
	s_add_u32 s22, s4, s1
	v_cndmask_b32_e32 v16, v88, v89, vcc
	v_cmp_gt_i32_e32 vcc, 0, v17
	v_mul_f32_e32 v16, v16, v21
	v_exp_f32_e32 v16, v16
	v_cndmask_b32_e32 v17, v88, v89, vcc
	v_mul_f32_e32 v17, v17, v18
	v_exp_f32_e32 v17, v17
	v_add_u32_e32 v18, v101, v132
	v_sub_u32_e32 v19, 0, v18
	v_max_i32_e32 v19, v18, v19
	v_pk_mul_f32 v[0:1], v[0:1], v[16:17]
	v_add_u32_e32 v17, v102, v132
	v_cmp_gt_i32_e32 vcc, 0, v18
	v_sub_u32_e32 v18, 0, v17
	v_max_i32_e32 v18, v17, v18
	v_cvt_f32_u32_e32 v19, v19
	v_cvt_f32_u32_e32 v18, v18
	v_cndmask_b32_e32 v16, v88, v89, vcc
	v_cmp_gt_i32_e32 vcc, 0, v17
	v_mul_f32_e32 v16, v16, v19
	v_exp_f32_e32 v16, v16
	v_cndmask_b32_e32 v17, v88, v89, vcc
	v_mul_f32_e32 v17, v17, v18
	v_exp_f32_e32 v17, v17
	v_add_u32_e32 v18, v103, v132
	v_sub_u32_e32 v19, 0, v18
	v_max_i32_e32 v19, v18, v19
	v_pk_mul_f32 v[68:69], v[2:3], v[16:17]
	v_add_u32_e32 v3, v104, v132
	v_sub_u32_e32 v16, 0, v3
	v_max_i32_e32 v16, v3, v16
	v_cvt_f32_u32_e32 v19, v19
	v_cvt_f32_u32_e32 v16, v16
	v_cmp_gt_i32_e32 vcc, 0, v18
	s_addc_u32 s23, s23, 0
	s_ashr_i32 s1, s0, 31
	v_cndmask_b32_e32 v2, v88, v89, vcc
	v_cmp_gt_i32_e32 vcc, 0, v3
	v_mul_f32_e32 v2, v2, v19
	v_exp_f32_e32 v2, v2
	v_cndmask_b32_e32 v3, v88, v89, vcc
	v_mul_f32_e32 v3, v3, v16
	v_exp_f32_e32 v3, v3
	v_add_u32_e32 v16, v99, v132
	v_sub_u32_e32 v17, 0, v16
	v_max_i32_e32 v17, v16, v17
	v_pk_mul_f32 v[70:71], v[4:5], v[2:3]
	v_add_u32_e32 v3, v91, v132
	v_sub_u32_e32 v4, 0, v3
	v_max_i32_e32 v4, v3, v4
	v_cvt_f32_u32_e32 v17, v17
	v_cvt_f32_u32_e32 v4, v4
	v_cmp_gt_i32_e32 vcc, 0, v16
	s_nop 1
	v_cndmask_b32_e32 v2, v88, v89, vcc
	v_cmp_gt_i32_e32 vcc, 0, v3
	v_mul_f32_e32 v2, v2, v17
	v_exp_f32_e32 v2, v2
	v_cndmask_b32_e32 v3, v88, v89, vcc
	v_mul_f32_e32 v3, v3, v4
	v_exp_f32_e32 v3, v3
	v_add_u32_e32 v4, v92, v132
	v_sub_u32_e32 v5, 0, v4
	v_max_i32_e32 v5, v4, v5
	v_pk_mul_f32 v[6:7], v[6:7], v[2:3]
	v_add_u32_e32 v3, v93, v132
	v_cvt_f32_u32_e32 v5, v5
	v_cmp_gt_i32_e32 vcc, 0, v4
	v_sub_u32_e32 v4, 0, v3
	v_max_i32_e32 v4, v3, v4
	v_cvt_f32_u32_e32 v4, v4
	v_cndmask_b32_e32 v2, v88, v89, vcc
	v_mul_f32_e32 v2, v2, v5
	v_cmp_gt_i32_e32 vcc, 0, v3
	v_exp_f32_e32 v72, v2
	v_add_u32_e32 v3, v94, v132
	v_cndmask_b32_e32 v2, v88, v89, vcc
	v_mul_f32_e32 v2, v2, v4
	v_sub_u32_e32 v4, 0, v3
	v_max_i32_e32 v4, v3, v4
	v_cvt_f32_u32_e32 v4, v4
	v_cmp_gt_i32_e32 vcc, 0, v3
	v_exp_f32_e32 v73, v2
	v_add_u32_e32 v3, v97, v132
	v_cndmask_b32_e32 v2, v88, v89, vcc
	v_mul_f32_e32 v2, v2, v4
	v_sub_u32_e32 v4, 0, v3
	v_max_i32_e32 v4, v3, v4
	v_cvt_f32_u32_e32 v4, v4
	v_cmp_gt_i32_e32 vcc, 0, v3
	v_exp_f32_e32 v74, v2
	v_add_u32_e32 v17, v90, v132
	v_cndmask_b32_e32 v2, v88, v89, vcc
	v_mul_f32_e32 v16, v2, v4
	v_sub_u32_e32 v2, 0, v17
	v_max_i32_e32 v18, v17, v2
	ds_read_b128 v[2:5], v133 offset:8704
	v_cvt_f32_u32_e32 v18, v18
	v_cmp_gt_i32_e32 vcc, 0, v17
	v_exp_f32_e32 v75, v16
	v_pk_mul_f32 v[8:9], v[8:9], v[72:73]
	v_cndmask_b32_e32 v16, v88, v89, vcc
	v_mul_f32_e32 v16, v16, v18
	v_exp_f32_e32 v76, v16
	s_waitcnt lgkmcnt(0)
; #define MFMA32(a, b, c) __builtin_amdgcn_mfma_f32_32x32x16_bf16(__builtin_bit_cast(bf16x8, (a)), __builtin_bit_cast(bf16x8, (b)), (c), 0, 0, 0)
; DI unsigned pack2(float a, float b) { f2_t f = {a, b}; bf2_t r = __builtin_convertvector(f, bf2_t); return __builtin_bit_cast(unsigned, r); }
; DI float ex2(float x) { return __builtin_amdgcn_exp2f(x); }
; DI int crow(int reg, int h) { return (reg & 3) + 8 * (reg >> 2) + 4 * h; }
; DI void retention_out_unit(const Params& p, int unit, char* smem) {
;     ...
; #pragma unroll
;     for (int mb = 0; mb < 4; ++mb) {
;       f32x16 s;
; #pragma unroll
;       for (int q = 0; q < 16; ++q) s[q] = 0.f;
;       const bf16_t* cK = sT + (32 * mb + r) * 136 + 8 * h;
; #pragma unroll
;       for (int ds = 0; ds < 8; ++ds) { u32x4 k = *(const u32x4*)(cK + 16 * ds); s = MFMA32(k, qf[ds], s); }
; #pragma unroll
;       for (int q = 0; q < 16; ++q) {
;         int m = 32 * mb + crow(q, h);
;         int diff = cq - m;
;         float dec = (diff >= 0) ? ex2((float)diff * lgf) : ex2((float)(-diff) * lgb);
;         s[q] *= dec;
;       }
; #pragma unroll
;       for (int sx = 0; sx < 2; ++sx) {
;         pf[2 * mb + sx][0] = pack2(s[8 * sx], s[8 * sx + 1]); pf[2 * mb + sx][1] = pack2(s[8 * sx + 2], s[8 * sx + 3]);
;         pf[2 * mb + sx][2] = pack2(s[8 * sx + 4], s[8 * sx + 5]); pf[2 * mb + sx][3] = pack2(s[8 * sx + 6], s[8 * sx + 7]);
;       }
	v_mfma_f32_32x32x16_bf16 v[16:31], v[2:5], v[60:63], 0
	v_add_u32_e32 v2, v95, v132
	v_sub_u32_e32 v3, 0, v2
	v_max_i32_e32 v3, v2, v3
	v_cvt_f32_u32_e32 v77, v3
	v_cmp_gt_i32_e32 vcc, 0, v2
	ds_read_b128 v[2:5], v133 offset:8768
	v_pk_mul_f32 v[10:11], v[10:11], v[74:75]
	v_mfma_f32_32x32x16_bf16 v[16:31], v[64:67], v[56:59], v[16:31]
	v_cndmask_b32_e32 v78, v88, v89, vcc
	v_mul_f32_e32 v77, v78, v77
	v_add_u32_e32 v78, v98, v132
	v_sub_u32_e32 v64, 0, v78
	v_max_i32_e32 v64, v78, v64
	v_cvt_f32_u32_e32 v79, v64
	ds_read_b128 v[64:67], v133 offset:8800
	s_waitcnt lgkmcnt(1)
	v_mfma_f32_32x32x16_bf16 v[16:31], v[2:5], v[52:55], v[16:31]
	v_cmp_gt_i32_e32 vcc, 0, v78
	v_exp_f32_e32 v77, v77
	s_nop 0
	v_cndmask_b32_e32 v2, v88, v89, vcc
	v_mul_f32_e32 v2, v2, v79
	v_exp_f32_e32 v78, v2
	ds_read_b128 v[2:5], v133 offset:8832
	s_waitcnt lgkmcnt(1)
	v_mfma_f32_32x32x16_bf16 v[16:31], v[64:67], v[48:51], v[16:31]
	v_add_u32_e32 v64, v96, v132
	v_sub_u32_e32 v65, 0, v64
	v_max_i32_e32 v65, v64, v65
	v_cvt_f32_u32_e32 v79, v65
	v_cmp_gt_i32_e32 vcc, 0, v64
	ds_read_b128 v[64:67], v133 offset:8864
	v_pk_mul_f32 v[12:13], v[12:13], v[76:77]
	s_waitcnt lgkmcnt(1)
	v_mfma_f32_32x32x16_bf16 v[16:31], v[2:5], v[44:47], v[16:31]
	v_cndmask_b32_e32 v80, v88, v89, vcc
	v_mul_f32_e32 v2, v80, v79
	v_exp_f32_e32 v79, v2
	ds_read_b128 v[2:5], v133 offset:8896
	v_pk_mul_f32 v[14:15], v[14:15], v[78:79]
	s_waitcnt lgkmcnt(1)
	v_mfma_f32_32x32x16_bf16 v[16:31], v[64:67], v[40:43], v[16:31]
	v_cvt_pk_bf16_f32 v64, v0, v1
	v_mad_i32_i24 v0, v146, -4, v87
	v_sub_u32_e32 v1, 0, v0
	v_cvt_pk_bf16_f32 v65, v68, v69
	v_cvt_pk_bf16_f32 v67, v6, v7
	v_cvt_pk_bf16_f32 v68, v8, v9
	ds_read_b128 v[6:9], v133 offset:8928
	v_max_i32_e32 v1, v0, v1
	s_waitcnt lgkmcnt(1)
	v_mfma_f32_32x32x16_bf16 v[16:31], v[2:5], v[36:39], v[16:31]
	v_cvt_f32_u32_e32 v1, v1
	v_cmp_gt_i32_e32 vcc, 0, v0
	v_cvt_pk_bf16_f32 v66, v70, v71
	v_cvt_pk_bf16_f32 v69, v10, v11
	v_cndmask_b32_e32 v0, v88, v89, vcc
	v_mul_f32_e32 v0, v0, v1
	v_add_u32_e32 v1, v87, v100
	v_sub_u32_e32 v2, 0, v1
	v_max_i32_e32 v2, v1, v2
	v_cvt_f32_u32_e32 v2, v2
	s_waitcnt lgkmcnt(0)
	v_mfma_f32_32x32x16_bf16 v[16:31], v[6:9], v[32:35], v[16:31]
	v_cmp_gt_i32_e32 vcc, 0, v1
	v_exp_f32_e32 v0, v0
	v_cvt_pk_bf16_f32 v70, v12, v13
	v_cndmask_b32_e32 v1, v88, v89, vcc
	v_mul_f32_e32 v1, v1, v2
	v_exp_f32_e32 v1, v1
	v_add_u32_e32 v2, v87, v101
	v_sub_u32_e32 v3, 0, v2
	v_max_i32_e32 v3, v2, v3
	s_nop 2
	v_pk_mul_f32 v[72:73], v[16:17], v[0:1]
	v_add_u32_e32 v1, v87, v102
	v_cmp_gt_i32_e32 vcc, 0, v2
	v_sub_u32_e32 v2, 0, v1
	v_max_i32_e32 v2, v1, v2
	v_cvt_f32_u32_e32 v3, v3
	v_cvt_f32_u32_e32 v2, v2
	v_cndmask_b32_e32 v0, v88, v89, vcc
	v_cmp_gt_i32_e32 vcc, 0, v1
	v_mul_f32_e32 v0, v0, v3
	v_exp_f32_e32 v0, v0
	v_cndmask_b32_e32 v1, v88, v89, vcc
	v_mul_f32_e32 v1, v1, v2
	v_exp_f32_e32 v1, v1
	v_add_u32_e32 v2, v87, v103
	v_sub_u32_e32 v3, 0, v2
	v_max_i32_e32 v3, v2, v3
	v_pk_mul_f32 v[74:75], v[18:19], v[0:1]
	v_add_u32_e32 v1, v87, v104
	v_cmp_gt_i32_e32 vcc, 0, v2
	v_sub_u32_e32 v2, 0, v1
	v_max_i32_e32 v2, v1, v2
	v_cvt_f32_u32_e32 v3, v3
	v_cvt_f32_u32_e32 v2, v2
	v_cndmask_b32_e32 v0, v88, v89, vcc
	v_cmp_gt_i32_e32 vcc, 0, v1
	v_mul_f32_e32 v0, v0, v3
	v_exp_f32_e32 v0, v0
	v_cndmask_b32_e32 v1, v88, v89, vcc
	v_mul_f32_e32 v1, v1, v2
	v_exp_f32_e32 v1, v1
	v_add_u32_e32 v2, v87, v99
	v_sub_u32_e32 v3, 0, v2
	v_max_i32_e32 v3, v2, v3
	v_pk_mul_f32 v[76:77], v[20:21], v[0:1]
	v_add_u32_e32 v1, v87, v91
	v_cmp_gt_i32_e32 vcc, 0, v2
	v_sub_u32_e32 v2, 0, v1
	v_max_i32_e32 v2, v1, v2
	v_cvt_f32_u32_e32 v3, v3
	v_cvt_f32_u32_e32 v2, v2
	v_cndmask_b32_e32 v0, v88, v89, vcc
	v_cmp_gt_i32_e32 vcc, 0, v1
	v_mul_f32_e32 v0, v0, v3
	v_exp_f32_e32 v0, v0
	v_cndmask_b32_e32 v1, v88, v89, vcc
	v_mul_f32_e32 v1, v1, v2
	v_exp_f32_e32 v1, v1
	v_add_u32_e32 v2, v87, v92
	v_sub_u32_e32 v3, 0, v2
	v_max_i32_e32 v3, v2, v3
	v_pk_mul_f32 v[78:79], v[22:23], v[0:1]
	v_add_u32_e32 v1, v87, v93
	v_cvt_f32_u32_e32 v3, v3
	v_cmp_gt_i32_e32 vcc, 0, v2
	v_sub_u32_e32 v2, 0, v1
	v_max_i32_e32 v2, v1, v2
	v_cvt_f32_u32_e32 v2, v2
	v_cndmask_b32_e32 v0, v88, v89, vcc
	v_mul_f32_e32 v0, v0, v3
	v_cmp_gt_i32_e32 vcc, 0, v1
	v_exp_f32_e32 v80, v0
	v_add_u32_e32 v1, v87, v94
	v_cndmask_b32_e32 v0, v88, v89, vcc
	v_mul_f32_e32 v0, v0, v2
	v_sub_u32_e32 v2, 0, v1
	v_max_i32_e32 v2, v1, v2
	v_cvt_f32_u32_e32 v2, v2
	v_cmp_gt_i32_e32 vcc, 0, v1
	v_exp_f32_e32 v81, v0
	v_add_u32_e32 v1, v87, v97
	v_cndmask_b32_e32 v0, v88, v89, vcc
	v_mul_f32_e32 v0, v0, v2
	v_sub_u32_e32 v2, 0, v1
	v_max_i32_e32 v2, v1, v2
	v_cvt_f32_u32_e32 v2, v2
	v_cmp_gt_i32_e32 vcc, 0, v1
	v_exp_f32_e32 v82, v0
	v_cvt_pk_bf16_f32 v71, v14, v15
	v_cndmask_b32_e32 v0, v88, v89, vcc
	v_mul_f32_e32 v4, v0, v2
	ds_read_b128 v[0:3], v133 offset:17408
	v_exp_f32_e32 v83, v4
	v_add_u32_e32 v4, v87, v90
	v_sub_u32_e32 v5, 0, v4
	v_max_i32_e32 v5, v4, v5
	v_cvt_f32_u32_e32 v84, v5
	v_cmp_gt_i32_e32 vcc, 0, v4
	ds_read_b128 v[4:7], v133 offset:17440
	s_waitcnt lgkmcnt(1)
	v_mfma_f32_32x32x16_bf16 v[8:23], v[0:3], v[60:63], 0
	v_cndmask_b32_e32 v85, v88, v89, vcc
	v_mul_f32_e32 v0, v85, v84
	v_add_u32_e32 v85, v87, v95
	v_exp_f32_e32 v84, v0
	v_sub_u32_e32 v0, 0, v85
	v_max_i32_e32 v0, v85, v0
	v_cvt_f32_u32_e32 v86, v0
	ds_read_b128 v[0:3], v133 offset:17472
	s_waitcnt lgkmcnt(1)
	v_mfma_f32_32x32x16_bf16 v[8:23], v[4:7], v[56:59], v[8:23]
	v_cmp_gt_i32_e32 vcc, 0, v85
	v_mul_f32_e64 v24, v24, v80
	v_mul_f32_e64 v25, v25, v81
	v_mul_f32_e64 v26, v26, v82
	v_mul_f32_e64 v27, v27, v83
	v_cndmask_b32_e32 v4, v88, v89, vcc
	v_mul_f32_e32 v85, v4, v86
	v_add_u32_e32 v86, v87, v98
	v_sub_u32_e32 v4, 0, v86
	v_max_i32_e32 v105, v86, v4
	ds_read_b128 v[4:7], v133 offset:17504
	s_waitcnt lgkmcnt(1)
; #define MFMA32(a, b, c) __builtin_amdgcn_mfma_f32_32x32x16_bf16(__builtin_bit_cast(bf16x8, (a)), __builtin_bit_cast(bf16x8, (b)), (c), 0, 0, 0)
; DI unsigned pack2(float a, float b) { f2_t f = {a, b}; bf2_t r = __builtin_convertvector(f, bf2_t); return __builtin_bit_cast(unsigned, r); }
; DI float ex2(float x) { return __builtin_amdgcn_exp2f(x); }
; DI int crow(int reg, int h) { return (reg & 3) + 8 * (reg >> 2) + 4 * h; }
; DI void retention_out_unit(const Params& p, int unit, char* smem) {
;     ...
; #pragma unroll
;     for (int mb = 0; mb < 4; ++mb) {
;       f32x16 s;
; #pragma unroll
;       for (int q = 0; q < 16; ++q) s[q] = 0.f;
;       const bf16_t* cK = sT + (32 * mb + r) * 136 + 8 * h;
; #pragma unroll
;       for (int ds = 0; ds < 8; ++ds) { u32x4 k = *(const u32x4*)(cK + 16 * ds); s = MFMA32(k, qf[ds], s); }
; #pragma unroll
;       for (int q = 0; q < 16; ++q) {
;         int m = 32 * mb + crow(q, h);
;         int diff = cq - m;
;         float dec = (diff >= 0) ? ex2((float)diff * lgf) : ex2((float)(-diff) * lgb);
;         s[q] *= dec;
;       }
; #pragma unroll
;       for (int sx = 0; sx < 2; ++sx) {
;         pf[2 * mb + sx][0] = pack2(s[8 * sx], s[8 * sx + 1]); pf[2 * mb + sx][1] = pack2(s[8 * sx + 2], s[8 * sx + 3]);
;         pf[2 * mb + sx][2] = pack2(s[8 * sx + 4], s[8 * sx + 5]); pf[2 * mb + sx][3] = pack2(s[8 * sx + 6], s[8 * sx + 7]);
;       }
	v_mfma_f32_32x32x16_bf16 v[8:23], v[0:3], v[52:55], v[8:23]
	v_cvt_f32_u32_e32 v0, v105
	v_cmp_gt_i32_e32 vcc, 0, v86
	v_exp_f32_e32 v85, v85
	v_cvt_pk_bf16_f32 v72, v72, v73
	v_cndmask_b32_e32 v1, v88, v89, vcc
	v_mul_f32_e32 v0, v1, v0
	v_exp_f32_e32 v86, v0
	ds_read_b128 v[0:3], v133 offset:17536
	s_waitcnt lgkmcnt(1)
	v_mfma_f32_32x32x16_bf16 v[8:23], v[4:7], v[48:51], v[8:23]
	v_add_u32_e32 v4, v87, v96
	v_sub_u32_e32 v5, 0, v4
	v_max_i32_e32 v5, v4, v5
	v_cvt_f32_u32_e32 v87, v5
	v_cmp_gt_i32_e32 vcc, 0, v4
	ds_read_b128 v[4:7], v133 offset:17568
	v_pk_mul_f32 v[28:29], v[28:29], v[84:85]
	s_waitcnt lgkmcnt(1)
	v_mfma_f32_32x32x16_bf16 v[8:23], v[0:3], v[44:47], v[8:23]
	v_cndmask_b32_e32 v105, v88, v89, vcc
	v_mul_f32_e32 v0, v105, v87
	v_exp_f32_e32 v87, v0
	ds_read_b128 v[0:3], v133 offset:17600
	v_subrev_u32_e32 v105, 64, v132
	v_cvt_pk_bf16_f32 v73, v74, v75
	v_pk_mul_f32 v[30:31], v[30:31], v[86:87]
	s_waitcnt lgkmcnt(1)
	v_mfma_f32_32x32x16_bf16 v[8:23], v[4:7], v[40:43], v[8:23]
	ds_read_b128 v[4:7], v133 offset:17632
	v_cvt_pk_bf16_f32 v74, v76, v77
	v_cvt_pk_bf16_f32 v76, v24, v25
	v_cvt_pk_bf16_f32 v77, v26, v27
	ds_read_b128 v[24:27], v133 offset:26144
	v_cvt_pk_bf16_f32 v75, v78, v79
	v_cvt_pk_bf16_f32 v78, v28, v29
	s_waitcnt lgkmcnt(2)
	v_mfma_f32_32x32x16_bf16 v[8:23], v[0:3], v[36:39], v[8:23]
	v_mad_i32_i24 v0, v146, -4, v105
	v_sub_u32_e32 v1, 0, v0
	v_max_i32_e32 v1, v0, v1
	v_cvt_f32_u32_e32 v1, v1
	v_cmp_gt_i32_e32 vcc, 0, v0
	v_cvt_pk_bf16_f32 v79, v30, v31
	s_nop 0
	v_cndmask_b32_e32 v0, v88, v89, vcc
	v_mul_f32_e32 v0, v0, v1
	v_add_u32_e32 v1, v105, v100
	v_sub_u32_e32 v2, 0, v1
	v_max_i32_e32 v2, v1, v2
	v_cvt_f32_u32_e32 v2, v2
	s_waitcnt lgkmcnt(1)
	v_mfma_f32_32x32x16_bf16 v[8:23], v[4:7], v[32:35], v[8:23]
	v_cmp_gt_i32_e32 vcc, 0, v1
	v_exp_f32_e32 v0, v0
	s_nop 0
	v_cndmask_b32_e32 v1, v88, v89, vcc
	v_mul_f32_e32 v1, v1, v2
	v_exp_f32_e32 v1, v1
	v_add_u32_e32 v2, v105, v101
	v_sub_u32_e32 v3, 0, v2
	v_max_i32_e32 v3, v2, v3
	s_nop 2
	v_pk_mul_f32 v[80:81], v[0:1], v[8:9]
	v_add_u32_e32 v1, v105, v102
	v_cmp_gt_i32_e32 vcc, 0, v2
	v_sub_u32_e32 v2, 0, v1
	v_max_i32_e32 v2, v1, v2
	v_cvt_f32_u32_e32 v3, v3
	v_cvt_f32_u32_e32 v2, v2
	v_cndmask_b32_e32 v0, v88, v89, vcc
	v_cmp_gt_i32_e32 vcc, 0, v1
	v_mul_f32_e32 v0, v0, v3
	v_exp_f32_e32 v0, v0
	v_cndmask_b32_e32 v1, v88, v89, vcc
	v_mul_f32_e32 v1, v1, v2
	v_exp_f32_e32 v1, v1
	v_add_u32_e32 v2, v105, v103
	v_sub_u32_e32 v3, 0, v2
	v_max_i32_e32 v3, v2, v3
	v_pk_mul_f32 v[82:83], v[0:1], v[10:11]
	v_add_u32_e32 v1, v105, v104
	v_cmp_gt_i32_e32 vcc, 0, v2
	v_sub_u32_e32 v2, 0, v1
	v_max_i32_e32 v2, v1, v2
	v_cvt_f32_u32_e32 v3, v3
	v_cvt_f32_u32_e32 v2, v2
	v_cndmask_b32_e32 v0, v88, v89, vcc
	v_cmp_gt_i32_e32 vcc, 0, v1
	v_mul_f32_e32 v0, v0, v3
	v_exp_f32_e32 v0, v0
	v_cndmask_b32_e32 v1, v88, v89, vcc
	v_mul_f32_e32 v1, v1, v2
	v_exp_f32_e32 v1, v1
	v_add_u32_e32 v2, v105, v99
	v_sub_u32_e32 v3, 0, v2
	v_max_i32_e32 v3, v2, v3
	v_pk_mul_f32 v[84:85], v[0:1], v[12:13]
	v_add_u32_e32 v1, v105, v91
	v_cmp_gt_i32_e32 vcc, 0, v2
	v_sub_u32_e32 v2, 0, v1
	v_max_i32_e32 v2, v1, v2
	v_cvt_f32_u32_e32 v3, v3
	v_cvt_f32_u32_e32 v2, v2
	v_cndmask_b32_e32 v0, v88, v89, vcc
	v_cmp_gt_i32_e32 vcc, 0, v1
	v_mul_f32_e32 v0, v0, v3
	v_exp_f32_e32 v0, v0
	v_cndmask_b32_e32 v1, v88, v89, vcc
	v_mul_f32_e32 v1, v1, v2
	v_exp_f32_e32 v1, v1
	v_add_u32_e32 v2, v105, v92
	v_sub_u32_e32 v3, 0, v2
	v_max_i32_e32 v3, v2, v3
	v_pk_mul_f32 v[86:87], v[0:1], v[14:15]
	v_add_u32_e32 v1, v105, v93
	v_cvt_f32_u32_e32 v3, v3
	v_cmp_gt_i32_e32 vcc, 0, v2
	v_sub_u32_e32 v2, 0, v1
	v_max_i32_e32 v2, v1, v2
	v_cvt_f32_u32_e32 v2, v2
	v_cndmask_b32_e32 v0, v88, v89, vcc
	v_mul_f32_e32 v0, v0, v3
	v_cmp_gt_i32_e32 vcc, 0, v1
	v_exp_f32_e32 v106, v0
	v_add_u32_e32 v1, v105, v94
	v_cndmask_b32_e32 v0, v88, v89, vcc
	v_mul_f32_e32 v0, v0, v2
	v_sub_u32_e32 v2, 0, v1
	v_max_i32_e32 v2, v1, v2
	v_cvt_f32_u32_e32 v2, v2
	v_cmp_gt_i32_e32 vcc, 0, v1
	v_exp_f32_e32 v107, v0
	v_add_u32_e32 v1, v105, v97
	v_cndmask_b32_e32 v0, v88, v89, vcc
	v_mul_f32_e32 v0, v0, v2
	v_sub_u32_e32 v2, 0, v1
	v_max_i32_e32 v2, v1, v2
	v_cvt_f32_u32_e32 v2, v2
	v_cmp_gt_i32_e32 vcc, 0, v1
	v_exp_f32_e32 v108, v0
	v_cvt_pk_bf16_f32 v80, v80, v81
	v_cndmask_b32_e32 v0, v88, v89, vcc
	v_mul_f32_e32 v4, v0, v2
	ds_read_b128 v[0:3], v133 offset:26112
	v_exp_f32_e32 v109, v4
	v_add_u32_e32 v4, v105, v90
	v_sub_u32_e32 v5, 0, v4
	v_max_i32_e32 v5, v4, v5
	v_cvt_f32_u32_e32 v28, v5
	v_cmp_gt_i32_e32 vcc, 0, v4
	s_waitcnt lgkmcnt(0)
	v_mfma_f32_32x32x16_bf16 v[0:15], v[0:3], v[60:63], 0
	v_cndmask_b32_e32 v29, v88, v89, vcc
	v_mul_f32_e32 v28, v29, v28
	v_add_u32_e32 v61, v105, v95
	v_exp_f32_e32 v60, v28
	v_sub_u32_e32 v28, 0, v61
	v_max_i32_e32 v28, v61, v28
	v_cvt_f32_u32_e32 v62, v28
	ds_read_b128 v[28:31], v133 offset:26176
	v_mfma_f32_32x32x16_bf16 v[0:15], v[24:27], v[56:59], v[0:15]
	v_cmp_gt_i32_e32 vcc, 0, v61
	v_add_u32_e32 v57, v105, v98
	v_cvt_pk_bf16_f32 v81, v82, v83
	v_cndmask_b32_e32 v24, v88, v89, vcc
	v_mul_f32_e32 v56, v24, v62
	v_sub_u32_e32 v24, 0, v57
	v_max_i32_e32 v58, v57, v24
	ds_read_b128 v[24:27], v133 offset:26208
	s_waitcnt lgkmcnt(1)
	v_mfma_f32_32x32x16_bf16 v[0:15], v[28:31], v[52:55], v[0:15]
	v_cvt_f32_u32_e32 v28, v58
	v_cmp_gt_i32_e32 vcc, 0, v57
	v_exp_f32_e32 v61, v56
	v_cvt_pk_bf16_f32 v83, v86, v87
	v_cndmask_b32_e32 v29, v88, v89, vcc
	v_mul_f32_e32 v28, v29, v28
	v_exp_f32_e32 v52, v28
	ds_read_b128 v[28:31], v133 offset:26240
	s_waitcnt lgkmcnt(1)
; DI unsigned pack2(float a, float b) { f2_t f = {a, b}; bf2_t r = __builtin_convertvector(f, bf2_t); return __builtin_bit_cast(unsigned, r); }
; DI float ex2(float x) { return __builtin_amdgcn_exp2f(x); }
; DI int tidx() { return tid512() & 255; }
; DI int crow(int reg, int h) { return (reg & 3) + 8 * (reg >> 2) + 4 * h; }
; DI void stage_tile128(bf16_t* sT, const bf16_t* __restrict__ src, size_t ld, bool perm) {
;   const int tid = tidx();
;   __syncthreads();
; #pragma unroll
;   for (int hlf = 0; hlf < 2; ++hlf) {
;     u32x4 regs[4];
; #pragma unroll
;     for (int i = 0; i < 4; ++i) { int id = tid + 256 * (4 * hlf + i); int row = id >> 4, ck = id & 15; regs[i] = ldg16(src + (size_t)row * ld + ck * 8); }
; #pragma unroll
;     for (int i = 0; i < 4; ++i) {
;       int id = tid + 256 * (4 * hlf + i); int row = id >> 4, ck = id & 15;
;       if (!perm) *(u32x4*)(sT + row * 136 + ck * 8) = regs[i];
;       else {
;         int g = ck >> 1, odd = ck & 1;
;         u32x2 lo = {regs[i][0], regs[i][1]}, hi = {regs[i][2], regs[i][3]};
;         *(u32x2*)(sT + row * 136 + g * 16 + (odd ? 4 : 0)) = lo;
;         *(u32x2*)(sT + row * 136 + g * 16 + (odd ? 12 : 8)) = hi;
;       }
;     }
;   }
;   __syncthreads();
; }
; DI void retention_out_unit(const Params& p, int unit, char* smem) {
;     ...
; #pragma unroll
;       for (int q = 0; q < 16; ++q) {
;         int m = 32 * mb + crow(q, h);
;         int diff = cq - m;
;         float dec = (diff >= 0) ? ex2((float)diff * lgf) : ex2((float)(-diff) * lgb);
;         s[q] *= dec;
;       }
; #pragma unroll
;       for (int sx = 0; sx < 2; ++sx) {
;         pf[2 * mb + sx][0] = pack2(s[8 * sx], s[8 * sx + 1]); pf[2 * mb + sx][1] = pack2(s[8 * sx + 2], s[8 * sx + 3]);
;         pf[2 * mb + sx][2] = pack2(s[8 * sx + 4], s[8 * sx + 5]); pf[2 * mb + sx][3] = pack2(s[8 * sx + 6], s[8 * sx + 7]);
;       }
;     }
;   }
;   stage_tile128(sT, (const bf16_t*)(p.ws + OFF_RVT) + (size_t)bh * 128 * 4096 + n * 128, 4096, true);
	v_mfma_f32_32x32x16_bf16 v[0:15], v[24:27], v[48:51], v[0:15]
	v_add_u32_e32 v24, v105, v96
	v_sub_u32_e32 v25, 0, v24
	v_max_i32_e32 v25, v24, v25
	v_cvt_f32_u32_e32 v48, v25
	v_cmp_gt_i32_e32 vcc, 0, v24
	ds_read_b128 v[24:27], v133 offset:26272
	v_add_u32_e32 v105, 0xffffffa0, v132
	s_waitcnt lgkmcnt(1)
	v_mfma_f32_32x32x16_bf16 v[0:15], v[28:31], v[44:47], v[0:15]
	v_cndmask_b32_e32 v49, v88, v89, vcc
	v_mul_f32_e32 v28, v49, v48
	v_exp_f32_e32 v53, v28
	v_pk_mul_f32 v[28:29], v[106:107], v[16:17]
	v_pk_mul_f32 v[30:31], v[108:109], v[18:19]
	ds_read_b128 v[16:19], v133 offset:26304
	v_pk_mul_f32 v[44:45], v[60:61], v[20:21]
	s_waitcnt lgkmcnt(1)
	v_mfma_f32_32x32x16_bf16 v[0:15], v[24:27], v[40:43], v[0:15]
	v_mul_f32_e64 v46, v52, v22
	v_mul_f32_e64 v47, v53, v23
	ds_read_b128 v[20:23], v133 offset:26336
	v_mov_b32_e32 v48, v196
	s_waitcnt lgkmcnt(0)
	v_lshlrev_b32_e32 v49, 4, v48
	v_and_b32_e32 v128, 0xf0, v49
	v_mfma_f32_32x32x16_bf16 v[0:15], v[16:19], v[36:39], v[0:15]
	v_mad_i32_i24 v16, v146, -4, v105
	v_sub_u32_e32 v17, 0, v16
	v_max_i32_e32 v17, v16, v17
	v_cvt_f32_u32_e32 v17, v17
	v_cmp_gt_i32_e32 vcc, 0, v16
	v_bfe_u32 v50, v48, 4, 4
	v_lshl_add_u64 v[40:41], s[22:23], 0, v[128:129]
	v_cndmask_b32_e32 v16, v88, v89, vcc
	v_mul_f32_e32 v16, v16, v17
	v_add_u32_e32 v17, v105, v100
	v_sub_u32_e32 v18, 0, v17
	v_max_i32_e32 v18, v17, v18
	v_cvt_f32_u32_e32 v18, v18
	v_cmp_gt_i32_e32 vcc, 0, v17
	v_mfma_f32_32x32x16_bf16 v[0:15], v[20:23], v[32:35], v[0:15]
	v_exp_f32_e32 v20, v16
	v_cndmask_b32_e32 v16, v88, v89, vcc
	v_add_u32_e32 v17, v105, v101
	v_mul_f32_e32 v16, v16, v18
	v_sub_u32_e32 v18, 0, v17
	v_max_i32_e32 v18, v17, v18
	v_cvt_f32_u32_e32 v18, v18
	v_cmp_gt_i32_e32 vcc, 0, v17
	v_exp_f32_e32 v21, v16
	v_add_u32_e32 v17, v105, v102
	v_cndmask_b32_e32 v16, v88, v89, vcc
	v_mul_f32_e32 v16, v16, v18
	v_sub_u32_e32 v18, 0, v17
	v_max_i32_e32 v18, v17, v18
	v_cvt_f32_u32_e32 v18, v18
	v_cmp_gt_i32_e32 vcc, 0, v17
	v_exp_f32_e32 v22, v16
	v_add_u32_e32 v17, v105, v103
	v_cndmask_b32_e32 v16, v88, v89, vcc
	v_mul_f32_e32 v16, v16, v18
	v_sub_u32_e32 v18, 0, v17
	v_max_i32_e32 v18, v17, v18
	v_cvt_f32_u32_e32 v18, v18
	v_cmp_gt_i32_e32 vcc, 0, v17
	v_exp_f32_e32 v23, v16
	v_add_u32_e32 v17, v105, v104
	v_cndmask_b32_e32 v16, v88, v89, vcc
	v_mul_f32_e32 v16, v16, v18
	v_sub_u32_e32 v18, 0, v17
	v_max_i32_e32 v18, v17, v18
	v_cvt_f32_u32_e32 v18, v18
	v_cmp_gt_i32_e32 vcc, 0, v17
	v_exp_f32_e32 v24, v16
	v_lshlrev_b32_e32 v128, 13, v50
	v_cndmask_b32_e32 v16, v88, v89, vcc
	v_mul_f32_e32 v16, v16, v18
	v_exp_f32_e32 v25, v16
	v_lshl_add_u64 v[16:17], v[40:41], 0, v[128:129]
	s_barrier
	global_load_dwordx4 v[16:19], v[16:17], off
	v_cvt_pk_bf16_f32 v86, v44, v45
	v_pk_mul_f32 v[44:45], v[20:21], v[0:1]
	v_or_b32_e32 v0, 0x20000, v128
	v_mov_b32_e32 v1, v129
	v_lshl_add_u64 v[0:1], v[40:41], 0, v[0:1]
	v_cvt_pk_bf16_f32 v87, v46, v47
	v_pk_mul_f32 v[46:47], v[22:23], v[2:3]
	global_load_dwordx4 v[0:3], v[0:1], off
	v_pk_mul_f32 v[100:101], v[24:25], v[4:5]
	v_or_b32_e32 v4, 0x40000, v128
	v_mov_b32_e32 v5, v129
	v_lshl_add_u64 v[4:5], v[40:41], 0, v[4:5]
	global_load_dwordx4 v[20:23], v[4:5], off
	v_or_b32_e32 v4, 0x60000, v128
	v_mov_b32_e32 v5, v129
	v_lshl_add_u64 v[4:5], v[40:41], 0, v[4:5]
	v_add_u32_e32 v42, v105, v99
	global_load_dwordx4 v[24:27], v[4:5], off
	v_or_b32_e32 v4, 0x80000, v128
	v_mov_b32_e32 v5, v129
	v_cvt_pk_bf16_f32 v82, v84, v85
	v_cvt_pk_bf16_f32 v84, v28, v29
	v_sub_u32_e32 v28, 0, v42
	v_lshl_add_u64 v[4:5], v[40:41], 0, v[4:5]
	v_cvt_pk_bf16_f32 v85, v30, v31
	v_max_i32_e32 v32, v42, v28
	global_load_dwordx4 v[28:31], v[4:5], off
	v_or_b32_e32 v4, 0xa0000, v128
	v_mov_b32_e32 v5, v129
	v_cvt_f32_u32_e32 v43, v32
	v_lshl_add_u64 v[4:5], v[40:41], 0, v[4:5]
	global_load_dwordx4 v[32:35], v[4:5], off
	v_or_b32_e32 v4, 0xc0000, v128
	v_mov_b32_e32 v5, v129
	v_lshl_add_u64 v[4:5], v[40:41], 0, v[4:5]
	v_cmp_gt_i32_e32 vcc, 0, v42
	global_load_dwordx4 v[36:39], v[4:5], off
	v_or_b32_e32 v128, 0xe0000, v128
	v_cndmask_b32_e32 v4, v88, v89, vcc
	v_mul_f32_e32 v51, v4, v43
	v_lshl_add_u64 v[4:5], v[40:41], 0, v[128:129]
	global_load_dwordx4 v[40:43], v[4:5], off
	v_add_u32_e32 v5, v105, v91
	v_sub_u32_e32 v4, 0, v5
	v_max_i32_e32 v4, v5, v4
	v_cvt_f32_u32_e32 v52, v4
	v_cmp_gt_i32_e32 vcc, 0, v5
	v_exp_f32_e32 v4, v51
	v_add_u32_e32 v51, v105, v92
	v_cndmask_b32_e32 v5, v88, v89, vcc
	v_mul_f32_e32 v5, v5, v52
	v_exp_f32_e32 v5, v5
	v_sub_u32_e32 v52, 0, v51
	v_max_i32_e32 v52, v51, v52
	v_cvt_f32_u32_e32 v52, v52
	v_pk_mul_f32 v[102:103], v[4:5], v[6:7]
	v_add_u32_e32 v5, v105, v93
	v_sub_u32_e32 v6, 0, v5
	v_max_i32_e32 v6, v5, v6
	v_cvt_f32_u32_e32 v6, v6
	v_cmp_gt_i32_e32 vcc, 0, v51
	v_cvt_pk_bf16_f32 v91, v46, v47
	v_cvt_pk_bf16_f32 v92, v100, v101
	v_cndmask_b32_e32 v4, v88, v89, vcc
	v_cmp_gt_i32_e32 vcc, 0, v5
	v_mul_f32_e32 v4, v4, v52
	v_exp_f32_e32 v4, v4
	v_cndmask_b32_e32 v5, v88, v89, vcc
	v_mul_f32_e32 v5, v5, v6
	v_add_u32_e32 v6, v105, v94
	v_sub_u32_e32 v7, 0, v6
	v_exp_f32_e32 v5, v5
	v_max_i32_e32 v7, v6, v7
	v_cvt_f32_u32_e32 v7, v7
	v_cmp_gt_i32_e32 vcc, 0, v6
	v_pk_mul_f32 v[8:9], v[4:5], v[8:9]
	v_add_u32_e32 v5, v105, v97
	v_cndmask_b32_e32 v4, v88, v89, vcc
	v_mul_f32_e32 v4, v4, v7
	v_and_b32_e32 v7, 1, v48
	v_and_b32_e32 v48, 0xe0, v49
	v_mul_u32_u24_e32 v49, 0x110, v50
	v_add3_u32 v48, s24, v48, v49
	v_lshlrev_b32_e32 v49, 3, v7
	v_cmp_eq_u32_e32 vcc, 0, v7
	v_add_u32_e32 v50, v48, v49
	s_waitcnt vmcnt(7)
	ds_write_b64 v50, v[16:17]
	v_cndmask_b32_e64 v7, 24, 16, vcc
	v_add_u32_e32 v16, v48, v7
	ds_write_b64 v16, v[18:19]
	v_add_u32_e32 v16, 0x1100, v48
	v_add_u32_e32 v17, v16, v49
	s_waitcnt vmcnt(6)
	ds_write_b64 v17, v[0:1]
	v_add_u32_e32 v0, v16, v7
	ds_write_b64 v0, v[2:3]
	v_add_u32_e32 v0, 0x2200, v48
	v_add_u32_e32 v1, v0, v49
	v_add_u32_e32 v0, v0, v7
	s_waitcnt vmcnt(5)
	ds_write_b64 v0, v[22:23]
	v_add_u32_e32 v0, 0x3300, v48
	ds_write_b64 v1, v[20:21]
	v_add_u32_e32 v1, v0, v49
	v_add_u32_e32 v0, v0, v7
	s_waitcnt vmcnt(4)
	ds_write_b64 v0, v[26:27]
	v_add_u32_e32 v0, 0x4400, v48
	ds_write_b64 v1, v[24:25]
	v_add_u32_e32 v1, v0, v49
	v_add_u32_e32 v0, v0, v7
	s_waitcnt vmcnt(3)
	ds_write_b64 v0, v[30:31]
	v_add_u32_e32 v0, 0x5500, v48
	ds_write_b64 v1, v[28:29]
	v_add_u32_e32 v1, v0, v49
	v_add_u32_e32 v0, v0, v7
	s_waitcnt vmcnt(2)
	ds_write_b64 v0, v[34:35]
	v_add_u32_e32 v0, 0x6600, v48
	ds_write_b64 v1, v[32:33]
	v_add_u32_e32 v1, v0, v49
	v_add_u32_e32 v0, v0, v7
	s_waitcnt vmcnt(1)
	ds_write_b64 v0, v[38:39]
	v_add_u32_e32 v0, 0x7700, v48
	ds_write_b64 v1, v[36:37]
	v_add_u32_e32 v1, v0, v49
	v_add_u32_e32 v0, v0, v7
	s_waitcnt vmcnt(0)
	ds_write_b64 v1, v[40:41]
	ds_write_b64 v0, v[42:43]
	s_waitcnt lgkmcnt(0)
	s_barrier
; #define MFMA32(a, b, c) __builtin_amdgcn_mfma_f32_32x32x16_bf16(__builtin_bit_cast(bf16x8, (a)), __builtin_bit_cast(bf16x8, (b)), (c), 0, 0, 0)
; DI float ex2(float x) { return __builtin_amdgcn_exp2f(x); }
; DI void retention_out_unit(const Params& p, int unit, char* smem) {
;     ...
;   f32x16 o[4];
; #pragma unroll
;   for (int eb = 0; eb < 4; ++eb) {
; #pragma unroll
;     for (int q = 0; q < 16; ++q) o[eb][q] = 0.f;
;     const bf16_t* cV = sT + (32 * eb + r) * 136 + 8 * h;
; #pragma unroll
;     for (int ks = 0; ks < 8; ++ks) { u32x4 v = *(const u32x4*)(cV + 16 * ks); o[eb] = MFMA32(v, pf[ks], o[eb]); }
;   }
; #pragma unroll 1
;   for (int dir = 0; dir < 2; ++dir) {
;     stage_tile128(sT, (const bf16_t*)(p.ws + (dir ? OFF_KVB : OFF_KVF)) + (size_t)unit * 16384, 128, false);
;     u32x4 qf[8];
;     load_qf8(qp, qf);
;     const float xi = dir ? ex2((float)(128 - cq) * lgb) : ex2((float)(cq + 1) * lgf);
	ds_read_b128 v[0:3], v133
	v_sub_u32_e32 v6, 0, v5
	v_max_i32_e32 v6, v5, v6
	v_cvt_f32_u32_e32 v6, v6
	v_cmp_gt_i32_e32 vcc, 0, v5
	v_exp_f32_e32 v16, v4
	v_cvt_pk_bf16_f32 v93, v102, v103
	v_cndmask_b32_e32 v4, v88, v89, vcc
	v_mul_f32_e32 v4, v4, v6
	v_exp_f32_e32 v17, v4
	ds_read_b128 v[4:7], v133 offset:32
	s_waitcnt lgkmcnt(1)
	v_mfma_f32_32x32x16_bf16 v[48:63], v[0:3], v[64:67], 0
	v_add_u32_e32 v0, v105, v90
	v_sub_u32_e32 v1, 0, v0
	v_max_i32_e32 v1, v0, v1
	v_cvt_f32_u32_e32 v18, v1
	v_cmp_gt_i32_e32 vcc, 0, v0
	ds_read_b128 v[0:3], v133 offset:64
	v_cvt_pk_bf16_f32 v90, v44, v45
	s_waitcnt lgkmcnt(1)
	v_mfma_f32_32x32x16_bf16 v[48:63], v[4:7], v[68:71], v[48:63]
	v_cndmask_b32_e32 v19, v88, v89, vcc
	v_mul_f32_e32 v4, v19, v18
	v_add_u32_e32 v19, v105, v95
	v_exp_f32_e32 v18, v4
	v_sub_u32_e32 v4, 0, v19
	v_max_i32_e32 v4, v19, v4
	v_cvt_f32_u32_e32 v20, v4
	ds_read_b128 v[4:7], v133 offset:96
	s_waitcnt lgkmcnt(1)
	v_mfma_f32_32x32x16_bf16 v[48:63], v[0:3], v[72:75], v[48:63]
	v_cmp_gt_i32_e32 vcc, 0, v19
	v_cvt_pk_bf16_f32 v94, v8, v9
	s_lshl_b64 s[22:23], s[0:1], 15
	v_cndmask_b32_e32 v0, v88, v89, vcc
	v_mul_f32_e32 v19, v0, v20
	v_add_u32_e32 v20, v105, v98
	v_sub_u32_e32 v0, 0, v20
	v_max_i32_e32 v21, v20, v0
	ds_read_b128 v[0:3], v133 offset:128
	s_waitcnt lgkmcnt(1)
	v_mfma_f32_32x32x16_bf16 v[48:63], v[4:7], v[76:79], v[48:63]
	v_cvt_f32_u32_e32 v4, v21
	v_cmp_gt_i32_e32 vcc, 0, v20
	v_exp_f32_e32 v19, v19
	s_add_u32 s1, s58, s22
	v_cndmask_b32_e32 v5, v88, v89, vcc
	v_mul_f32_e32 v4, v5, v4
	v_exp_f32_e32 v20, v4
	ds_read_b128 v[4:7], v133 offset:160
	s_waitcnt lgkmcnt(1)
	v_mfma_f32_32x32x16_bf16 v[48:63], v[0:3], v[80:83], v[48:63]
	v_add_u32_e32 v0, v105, v96
	v_sub_u32_e32 v1, 0, v0
	v_max_i32_e32 v1, v0, v1
	v_cvt_f32_u32_e32 v21, v1
	v_cmp_gt_i32_e32 vcc, 0, v0
	ds_read_b128 v[0:3], v133 offset:192
	s_addc_u32 s4, s59, s23
	s_waitcnt lgkmcnt(1)
	v_mfma_f32_32x32x16_bf16 v[48:63], v[4:7], v[84:87], v[48:63]
	v_cndmask_b32_e32 v22, v88, v89, vcc
	v_mul_f32_e32 v4, v22, v21
	v_exp_f32_e32 v21, v4
	ds_read_b128 v[4:7], v133 offset:224
	s_mov_b64 s[22:23], -1
	s_waitcnt lgkmcnt(1)
	v_mfma_f32_32x32x16_bf16 v[48:63], v[0:3], v[90:93], v[48:63]
	v_mul_f32_e64 v0, v16, v10
	v_mul_f32_e64 v1, v17, v11
	v_mul_f32_e64 v2, v18, v12
	v_mul_f32_e64 v3, v19, v13
	v_mul_f32_e64 v10, v20, v14
	v_mul_f32_e64 v11, v21, v15
	v_cvt_pk_bf16_f32 v95, v0, v1
	v_cvt_pk_bf16_f32 v96, v2, v3
	v_cvt_pk_bf16_f32 v97, v10, v11
	s_waitcnt lgkmcnt(0)
	s_nop 0
	v_mfma_f32_32x32x16_bf16 v[48:63], v[4:7], v[94:97], v[48:63]
	ds_read_b128 v[0:3], v133 offset:8704
	ds_read_b128 v[4:7], v133 offset:8736
	s_waitcnt lgkmcnt(1)
	v_mfma_f32_32x32x16_bf16 v[32:47], v[0:3], v[64:67], 0
	s_waitcnt lgkmcnt(0)
	v_mfma_f32_32x32x16_bf16 v[32:47], v[4:7], v[68:71], v[32:47]
	ds_read_b128 v[0:3], v133 offset:8768
	ds_read_b128 v[4:7], v133 offset:8800
	s_waitcnt lgkmcnt(1)
	v_mfma_f32_32x32x16_bf16 v[32:47], v[0:3], v[72:75], v[32:47]
	s_waitcnt lgkmcnt(0)
	v_mfma_f32_32x32x16_bf16 v[32:47], v[4:7], v[76:79], v[32:47]
	ds_read_b128 v[0:3], v133 offset:8832
	ds_read_b128 v[4:7], v133 offset:8864
	s_waitcnt lgkmcnt(1)
	v_mfma_f32_32x32x16_bf16 v[32:47], v[0:3], v[80:83], v[32:47]
	s_waitcnt lgkmcnt(0)
	v_mfma_f32_32x32x16_bf16 v[32:47], v[4:7], v[84:87], v[32:47]
	ds_read_b128 v[0:3], v133 offset:8896
	ds_read_b128 v[4:7], v133 offset:8928
	s_waitcnt lgkmcnt(1)
	v_mfma_f32_32x32x16_bf16 v[32:47], v[0:3], v[90:93], v[32:47]
	s_waitcnt lgkmcnt(0)
	v_mfma_f32_32x32x16_bf16 v[32:47], v[4:7], v[94:97], v[32:47]
	ds_read_b128 v[0:3], v133 offset:17408
	ds_read_b128 v[4:7], v133 offset:17440
	s_waitcnt lgkmcnt(1)
	v_mfma_f32_32x32x16_bf16 v[16:31], v[0:3], v[64:67], 0
	s_waitcnt lgkmcnt(0)
	v_mfma_f32_32x32x16_bf16 v[16:31], v[4:7], v[68:71], v[16:31]
	ds_read_b128 v[0:3], v133 offset:17472
	ds_read_b128 v[4:7], v133 offset:17504
	s_waitcnt lgkmcnt(1)
	v_mfma_f32_32x32x16_bf16 v[16:31], v[0:3], v[72:75], v[16:31]
	s_waitcnt lgkmcnt(0)
	v_mfma_f32_32x32x16_bf16 v[16:31], v[4:7], v[76:79], v[16:31]
	ds_read_b128 v[0:3], v133 offset:17536
	ds_read_b128 v[4:7], v133 offset:17568
	s_waitcnt lgkmcnt(1)
	v_mfma_f32_32x32x16_bf16 v[16:31], v[0:3], v[80:83], v[16:31]
	s_waitcnt lgkmcnt(0)
	v_mfma_f32_32x32x16_bf16 v[16:31], v[4:7], v[84:87], v[16:31]
	ds_read_b128 v[0:3], v133 offset:17600
	ds_read_b128 v[4:7], v133 offset:17632
	s_waitcnt lgkmcnt(1)
	v_mfma_f32_32x32x16_bf16 v[16:31], v[0:3], v[90:93], v[16:31]
	ds_read_b128 v[0:3], v133 offset:26112
	ds_read_b128 v[98:101], v133 offset:26144
	s_waitcnt lgkmcnt(2)
	v_mfma_f32_32x32x16_bf16 v[16:31], v[4:7], v[94:97], v[16:31]
	s_waitcnt lgkmcnt(1)
	v_mfma_f32_32x32x16_bf16 v[0:15], v[0:3], v[64:67], 0
	s_waitcnt lgkmcnt(0)
	v_mfma_f32_32x32x16_bf16 v[0:15], v[98:101], v[68:71], v[0:15]
	ds_read_b128 v[64:67], v133 offset:26176
	ds_read_b128 v[68:71], v133 offset:26208
	s_waitcnt lgkmcnt(1)
	v_mfma_f32_32x32x16_bf16 v[0:15], v[64:67], v[72:75], v[0:15]
	s_waitcnt lgkmcnt(0)
	v_mfma_f32_32x32x16_bf16 v[0:15], v[68:71], v[76:79], v[0:15]
	ds_read_b128 v[64:67], v133 offset:26240
	ds_read_b128 v[68:71], v133 offset:26272
	s_waitcnt lgkmcnt(1)
	v_mfma_f32_32x32x16_bf16 v[0:15], v[64:67], v[80:83], v[0:15]
	s_waitcnt lgkmcnt(0)
	v_mfma_f32_32x32x16_bf16 v[0:15], v[68:71], v[84:87], v[0:15]
	ds_read_b128 v[64:67], v133 offset:26304
	ds_read_b128 v[68:71], v133 offset:26336
	s_waitcnt lgkmcnt(1)
	v_mfma_f32_32x32x16_bf16 v[0:15], v[64:67], v[90:93], v[0:15]
	v_sub_u32_e32 v64, 0x80, v132
	v_cvt_f32_i32_e32 v64, v64
	v_add_u32_e32 v65, 1, v132
	v_cvt_f32_i32_e32 v65, v65
	v_mul_f32_e32 v64, v89, v64
	v_exp_f32_e32 v131, v64
	s_waitcnt lgkmcnt(0)
	v_mfma_f32_32x32x16_bf16 v[0:15], v[68:71], v[94:97], v[0:15]
	v_mul_f32_e32 v64, v88, v65
	v_exp_f32_e32 v147, v64
	global_load_dwordx4 v[200:203], v[134:135], off
	global_load_dwordx4 v[204:207], v[134:135], off offset:32
	global_load_dwordx4 v[208:211], v[134:135], off offset:64
	global_load_dwordx4 v[212:215], v[134:135], off offset:96
	global_load_dwordx4 v[216:219], v[134:135], off offset:128
	global_load_dwordx4 v[220:223], v[134:135], off offset:160
	global_load_dwordx4 v[224:227], v[134:135], off offset:192
	global_load_dwordx4 v[228:231], v[134:135], off offset:224
; #define MFMA32(a, b, c) __builtin_amdgcn_mfma_f32_32x32x16_bf16(__builtin_bit_cast(bf16x8, (a)), __builtin_bit_cast(bf16x8, (b)), (c), 0, 0, 0)
; DI float ex2(float x) { return __builtin_amdgcn_exp2f(x); }
; DI int tidx() { return tid512() & 255; }
; DI void stage_tile128(bf16_t* sT, const bf16_t* __restrict__ src, size_t ld, bool perm) {
;   const int tid = tidx();
;   __syncthreads();
; #pragma unroll
;   for (int hlf = 0; hlf < 2; ++hlf) {
;     u32x4 regs[4];
; #pragma unroll
;     for (int i = 0; i < 4; ++i) { int id = tid + 256 * (4 * hlf + i); int row = id >> 4, ck = id & 15; regs[i] = ldg16(src + (size_t)row * ld + ck * 8); }
; #pragma unroll
;     for (int i = 0; i < 4; ++i) {
;       int id = tid + 256 * (4 * hlf + i); int row = id >> 4, ck = id & 15;
;       if (!perm) *(u32x4*)(sT + row * 136 + ck * 8) = regs[i];
;       else {
;         int g = ck >> 1, odd = ck & 1;
;         u32x2 lo = {regs[i][0], regs[i][1]}, hi = {regs[i][2], regs[i][3]};
;         *(u32x2*)(sT + row * 136 + g * 16 + (odd ? 4 : 0)) = lo;
;         *(u32x2*)(sT + row * 136 + g * 16 + (odd ? 12 : 8)) = hi;
;       }
;     }
;   }
;   __syncthreads();
; }
; DI void retention_out_unit(const Params& p, int unit, char* smem) {
;     ...
; #pragma unroll 1
;   for (int dir = 0; dir < 2; ++dir) {
;     stage_tile128(sT, (const bf16_t*)(p.ws + (dir ? OFF_KVB : OFF_KVF)) + (size_t)unit * 16384, 128, false);
;     u32x4 qf[8];
;     load_qf8(qp, qf);
;     const float xi = dir ? ex2((float)(128 - cq) * lgb) : ex2((float)(cq + 1) * lgf);
; #pragma unroll
;     for (int eb = 0; eb < 4; ++eb) {
;       f32x16 t;
; #pragma unroll
;       for (int q = 0; q < 16; ++q) t[q] = 0.f;
;       const bf16_t* cS = sT + (32 * eb + r) * 136 + 8 * h;
; #pragma unroll
;       for (int ds = 0; ds < 8; ++ds) { u32x4 sv = *(const u32x4*)(cS + 16 * ds); t = MFMA32(sv, qf[ds], t); }
; #pragma unroll
;       for (int q = 0; q < 16; ++q) o[eb][q] += xi * t[q];
;     }
.LBB0_995:
	s_and_b64 vcc, s[22:23], exec
	v_mov_b32_e32 v64, v196
	s_cselect_b32 s54, s75, 0x1daf0000
	s_add_u32 s54, s1, s54
	v_lshlrev_b32_e32 v66, 4, v64
	v_bfe_u32 v64, v64, 4, 4
	s_addc_u32 s55, s4, 0
	v_and_b32_e32 v128, 0xf0, v66
	v_lshlrev_b32_e32 v88, 8, v64
	v_mul_u32_u24_e32 v70, 0x110, v64
	v_lshl_add_u64 v[90:91], s[54:55], 0, v[128:129]
	v_add3_u32 v96, s24, v128, v70
	v_or_b32_e32 v128, 0x4000, v88
	v_lshl_add_u64 v[80:81], v[90:91], 0, v[128:129]
	v_or_b32_e32 v128, 0x5000, v88
	v_lshl_add_u64 v[84:85], v[90:91], 0, v[128:129]
	v_or_b32_e32 v128, 0x6000, v88
	v_mov_b32_e32 v89, v129
	v_mov_b32_e32 v65, v129
	v_mov_b32_e32 v67, v129
	v_mov_b32_e32 v69, v129
	v_or_b32_e32 v64, 0x1000, v88
	v_or_b32_e32 v66, 0x2000, v88
	v_or_b32_e32 v68, 0x3000, v88
	v_lshl_add_u64 v[92:93], v[90:91], 0, v[128:129]
	v_or_b32_e32 v128, 0x7000, v88
	v_lshl_add_u64 v[70:71], v[90:91], 0, v[88:89]
	v_lshl_add_u64 v[72:73], v[90:91], 0, v[64:65]
	v_lshl_add_u64 v[74:75], v[90:91], 0, v[66:67]
	v_lshl_add_u64 v[76:77], v[90:91], 0, v[68:69]
	v_lshl_add_u64 v[94:95], v[90:91], 0, v[128:129]
	s_barrier
	global_load_dwordx4 v[64:67], v[70:71], off
	s_nop 0
	global_load_dwordx4 v[68:71], v[72:73], off
	s_nop 0
	global_load_dwordx4 v[72:75], v[74:75], off
	s_nop 0
	global_load_dwordx4 v[76:79], v[76:77], off
	s_nop 0
	global_load_dwordx4 v[80:83], v[80:81], off
	s_nop 0
	global_load_dwordx4 v[84:87], v[84:85], off
	s_nop 0
	global_load_dwordx4 v[88:91], v[92:93], off
	s_nop 0
	global_load_dwordx4 v[92:95], v[94:95], off
	v_cndmask_b32_e64 v128, v131, v147, s[22:23]
	s_mov_b64 s[22:23], 0
	s_waitcnt vmcnt(7)
	ds_write_b128 v96, v[64:67]
	s_waitcnt vmcnt(6)
	ds_write_b128 v96, v[68:71] offset:4352
	s_waitcnt vmcnt(5)
	ds_write_b128 v96, v[72:75] offset:8704
	s_waitcnt vmcnt(4)
	ds_write_b128 v96, v[76:79] offset:13056
	s_waitcnt vmcnt(3)
	ds_write_b128 v96, v[80:83] offset:17408
	s_waitcnt vmcnt(2)
	ds_write_b128 v96, v[84:87] offset:21760
	s_waitcnt vmcnt(1)
	ds_write_b128 v96, v[88:91] offset:26112
	s_waitcnt vmcnt(0)
	ds_write_b128 v96, v[92:95] offset:30464
	s_waitcnt lgkmcnt(0)
	s_barrier
	ds_read_b128 v[64:67], v133
	ds_read_b128 v[152:155], v133 offset:32
	ds_read_b128 v[80:83], v133 offset:8704
	ds_read_b128 v[156:159], v133 offset:8736
	ds_read_b128 v[96:99], v133 offset:17408
	ds_read_b128 v[160:163], v133 offset:17440
	ds_read_b128 v[116:119], v133 offset:26112
	ds_read_b128 v[164:167], v133 offset:26144
	s_waitcnt lgkmcnt(7)
	v_mfma_f32_32x32x16_bf16 v[64:79], v[64:67], v[200:203], 0
	s_waitcnt lgkmcnt(6)
	v_mfma_f32_32x32x16_bf16 v[64:79], v[152:155], v[204:207], v[64:79]
	s_waitcnt lgkmcnt(5)
	v_mfma_f32_32x32x16_bf16 v[80:95], v[80:83], v[200:203], 0
	s_waitcnt lgkmcnt(3)
	v_mfma_f32_32x32x16_bf16 v[96:111], v[96:99], v[200:203], 0
	s_waitcnt lgkmcnt(1)
	v_mfma_f32_32x32x16_bf16 v[112:127], v[116:119], v[200:203], 0
	v_mfma_f32_32x32x16_bf16 v[80:95], v[156:159], v[204:207], v[80:95]
	v_mfma_f32_32x32x16_bf16 v[96:111], v[160:163], v[204:207], v[96:111]
	s_waitcnt lgkmcnt(0)
	v_mfma_f32_32x32x16_bf16 v[112:127], v[164:167], v[204:207], v[112:127]
	ds_read_b128 v[148:151], v133 offset:64
	ds_read_b128 v[160:163], v133 offset:96
	s_waitcnt lgkmcnt(1)
	v_mfma_f32_32x32x16_bf16 v[64:79], v[148:151], v[208:211], v[64:79]
	ds_read_b128 v[148:151], v133 offset:8768
	ds_read_b128 v[164:167], v133 offset:8800
	s_waitcnt lgkmcnt(1)
	v_mfma_f32_32x32x16_bf16 v[80:95], v[148:151], v[208:211], v[80:95]
	ds_read_b128 v[148:151], v133 offset:17472
	ds_read_b128 v[168:171], v133 offset:17504
	s_waitcnt lgkmcnt(1)
	v_mfma_f32_32x32x16_bf16 v[96:111], v[148:151], v[208:211], v[96:111]
	ds_read_b128 v[148:151], v133 offset:26176
	ds_read_b128 v[172:175], v133 offset:26208
	s_waitcnt lgkmcnt(1)
	v_mfma_f32_32x32x16_bf16 v[112:127], v[148:151], v[208:211], v[112:127]
	v_mfma_f32_32x32x16_bf16 v[64:79], v[160:163], v[212:215], v[64:79]
	v_mfma_f32_32x32x16_bf16 v[80:95], v[164:167], v[212:215], v[80:95]
	v_mfma_f32_32x32x16_bf16 v[96:111], v[168:171], v[212:215], v[96:111]
	s_waitcnt lgkmcnt(0)
	v_mfma_f32_32x32x16_bf16 v[112:127], v[172:175], v[212:215], v[112:127]
	ds_read_b128 v[156:159], v133 offset:128
	ds_read_b128 v[160:163], v133 offset:160
	s_waitcnt lgkmcnt(1)
	v_mfma_f32_32x32x16_bf16 v[64:79], v[156:159], v[216:219], v[64:79]
	ds_read_b128 v[156:159], v133 offset:8832
	ds_read_b128 v[164:167], v133 offset:8864
	s_waitcnt lgkmcnt(1)
	v_mfma_f32_32x32x16_bf16 v[80:95], v[156:159], v[216:219], v[80:95]
	ds_read_b128 v[156:159], v133 offset:17536
	ds_read_b128 v[168:171], v133 offset:17568
	s_waitcnt lgkmcnt(1)
	v_mfma_f32_32x32x16_bf16 v[96:111], v[156:159], v[216:219], v[96:111]
	ds_read_b128 v[156:159], v133 offset:26240
	ds_read_b128 v[172:175], v133 offset:26272
	s_waitcnt lgkmcnt(1)
	v_mfma_f32_32x32x16_bf16 v[112:127], v[156:159], v[216:219], v[112:127]
	v_mfma_f32_32x32x16_bf16 v[64:79], v[160:163], v[220:223], v[64:79]
	v_mfma_f32_32x32x16_bf16 v[80:95], v[164:167], v[220:223], v[80:95]
	v_mfma_f32_32x32x16_bf16 v[96:111], v[168:171], v[220:223], v[96:111]
	s_waitcnt lgkmcnt(0)
	v_mfma_f32_32x32x16_bf16 v[112:127], v[172:175], v[220:223], v[112:127]
	ds_read_b128 v[152:155], v133 offset:192
	ds_read_b128 v[160:163], v133 offset:224
	s_waitcnt lgkmcnt(1)
	v_mfma_f32_32x32x16_bf16 v[64:79], v[152:155], v[224:227], v[64:79]
	ds_read_b128 v[152:155], v133 offset:8896
	ds_read_b128 v[164:167], v133 offset:8928
	s_waitcnt lgkmcnt(1)
	v_mfma_f32_32x32x16_bf16 v[80:95], v[152:155], v[224:227], v[80:95]
	ds_read_b128 v[152:155], v133 offset:17600
	ds_read_b128 v[168:171], v133 offset:17632
	s_waitcnt lgkmcnt(1)
; #define MFMA32(a, b, c) __builtin_amdgcn_mfma_f32_32x32x16_bf16(__builtin_bit_cast(bf16x8, (a)), __builtin_bit_cast(bf16x8, (b)), (c), 0, 0, 0)
; DI void retention_out_unit(const Params& p, int unit, char* smem) {
;     ...
; #pragma unroll
;     for (int eb = 0; eb < 4; ++eb) {
;       f32x16 t;
; #pragma unroll
;       for (int q = 0; q < 16; ++q) t[q] = 0.f;
;       const bf16_t* cS = sT + (32 * eb + r) * 136 + 8 * h;
; #pragma unroll
;       for (int ds = 0; ds < 8; ++ds) { u32x4 sv = *(const u32x4*)(cS + 16 * ds); t = MFMA32(sv, qf[ds], t); }
; #pragma unroll
;       for (int q = 0; q < 16; ++q) o[eb][q] += xi * t[q];
;     }
;   }
;   float ss = 0.f;
; #pragma unroll
;   for (int eb = 0; eb < 4; ++eb)
; #pragma unroll
;     for (int q = 0; q < 16; ++q) ss += o[eb][q] * o[eb][q];
;   ss += __shfl_xor(ss, 32);
;   const float rn = rsqrtf(ss * (1.f / 128.f) + EPS);
;   const bf16_t* gp = (const bf16_t*)(p.ws + OFF_RG) + (tok0 + cq) * 512 + hh * 128;
;   bf16_t* op = (bf16_t*)(p.ws + OFF_AB) + (tok0 + cq) * 1024 + hh * 128;
; #pragma unroll
;   for (int eb = 0; eb < 4; ++eb)
; #pragma unroll
;     for (int g4 = 0; g4 < 4; ++g4) {
;       int e = 32 * eb + 8 * g4 + 4 * h;
;       u32x2 gu = *(const u32x2*)(gp + e);
	v_mfma_f32_32x32x16_bf16 v[96:111], v[152:155], v[224:227], v[96:111]
	ds_read_b128 v[152:155], v133 offset:26304
	ds_read_b128 v[172:175], v133 offset:26336
	s_waitcnt lgkmcnt(1)
	v_mfma_f32_32x32x16_bf16 v[112:127], v[152:155], v[224:227], v[112:127]
	v_mfma_f32_32x32x16_bf16 v[64:79], v[160:163], v[228:231], v[64:79]
	v_mfma_f32_32x32x16_bf16 v[80:95], v[164:167], v[228:231], v[80:95]
	s_nop 10
	v_fma_f32 v48, v128, v64, v48
	v_fma_f32 v49, v128, v65, v49
	v_fma_f32 v50, v128, v66, v50
	v_fma_f32 v51, v128, v67, v51
	v_fma_f32 v52, v128, v68, v52
	v_fma_f32 v53, v128, v69, v53
	v_pk_fma_f32 v[54:55], v[128:129], v[70:71], v[54:55] op_sel_hi:[0,1,1]
	v_pk_fma_f32 v[56:57], v[128:129], v[72:73], v[56:57] op_sel_hi:[0,1,1]
	v_pk_fma_f32 v[58:59], v[128:129], v[74:75], v[58:59] op_sel_hi:[0,1,1]
	v_pk_fma_f32 v[60:61], v[128:129], v[76:77], v[60:61] op_sel_hi:[0,1,1]
	v_mfma_f32_32x32x16_bf16 v[96:111], v[168:171], v[228:231], v[96:111]
	v_fma_f32 v62, v128, v78, v62
	v_fma_f32 v63, v128, v79, v63
	v_fma_f32 v32, v128, v80, v32
	v_fma_f32 v33, v128, v81, v33
	v_fma_f32 v34, v128, v82, v34
	v_fma_f32 v35, v128, v83, v35
	v_pk_fma_f32 v[36:37], v[128:129], v[84:85], v[36:37] op_sel_hi:[0,1,1]
	v_pk_fma_f32 v[38:39], v[128:129], v[86:87], v[38:39] op_sel_hi:[0,1,1]
	v_pk_fma_f32 v[40:41], v[128:129], v[88:89], v[40:41] op_sel_hi:[0,1,1]
	v_pk_fma_f32 v[42:43], v[128:129], v[90:91], v[42:43] op_sel_hi:[0,1,1]
	s_waitcnt lgkmcnt(0)
	v_mfma_f32_32x32x16_bf16 v[112:127], v[172:175], v[228:231], v[112:127]
	v_fma_f32 v44, v128, v92, v44
	v_fma_f32 v45, v128, v93, v45
	v_fma_f32 v46, v128, v94, v46
	v_fma_f32 v47, v128, v95, v47
	v_fma_f32 v16, v128, v96, v16
	v_fma_f32 v17, v128, v97, v17
	v_pk_fma_f32 v[18:19], v[128:129], v[98:99], v[18:19] op_sel_hi:[0,1,1]
	v_pk_fma_f32 v[20:21], v[128:129], v[100:101], v[20:21] op_sel_hi:[0,1,1]
	v_pk_fma_f32 v[22:23], v[128:129], v[102:103], v[22:23] op_sel_hi:[0,1,1]
	v_pk_fma_f32 v[24:25], v[128:129], v[104:105], v[24:25] op_sel_hi:[0,1,1]
	v_pk_fma_f32 v[26:27], v[128:129], v[106:107], v[26:27] op_sel_hi:[0,1,1]
	v_pk_fma_f32 v[28:29], v[128:129], v[108:109], v[28:29] op_sel_hi:[0,1,1]
	v_pk_fma_f32 v[30:31], v[128:129], v[110:111], v[30:31] op_sel_hi:[0,1,1]
	v_pk_fma_f32 v[0:1], v[128:129], v[112:113], v[0:1] op_sel_hi:[0,1,1]
	v_pk_fma_f32 v[2:3], v[128:129], v[114:115], v[2:3] op_sel_hi:[0,1,1]
	v_pk_fma_f32 v[4:5], v[128:129], v[116:117], v[4:5] op_sel_hi:[0,1,1]
	v_pk_fma_f32 v[6:7], v[128:129], v[118:119], v[6:7] op_sel_hi:[0,1,1]
	v_pk_fma_f32 v[8:9], v[128:129], v[120:121], v[8:9] op_sel_hi:[0,1,1]
	v_pk_fma_f32 v[10:11], v[128:129], v[122:123], v[10:11] op_sel_hi:[0,1,1]
	v_pk_fma_f32 v[12:13], v[128:129], v[124:125], v[12:13] op_sel_hi:[0,1,1]
	v_pk_fma_f32 v[14:15], v[128:129], v[126:127], v[14:15] op_sel_hi:[0,1,1]
	s_cbranch_vccnz .LBB0_995
	v_pk_mul_f32 v[64:65], v[48:49], v[48:49]
	v_pk_mul_f32 v[66:67], v[50:51], v[50:51]
	v_add_f32_e32 v64, v64, v65
	v_add_f32_e32 v64, v66, v64
	v_pk_mul_f32 v[68:69], v[52:53], v[52:53]
	v_add_f32_e32 v64, v67, v64
	v_add_f32_e32 v64, v68, v64
	v_pk_mul_f32 v[70:71], v[54:55], v[54:55]
	v_add_f32_e32 v64, v69, v64
	v_add_f32_e32 v64, v70, v64
	v_pk_mul_f32 v[72:73], v[56:57], v[56:57]
	v_add_f32_e32 v64, v71, v64
	v_add_f32_e32 v64, v72, v64
	v_pk_mul_f32 v[74:75], v[58:59], v[58:59]
	v_add_f32_e32 v64, v73, v64
	v_ashrrev_i32_e32 v133, 31, v132
	v_add_f32_e32 v64, v74, v64
	v_lshl_add_u64 v[68:69], s[2:3], 0, v[132:133]
	v_add_f32_e32 v66, v75, v64
	v_lshlrev_b64 v[64:65], 10, v[68:69]
	v_lshl_add_u64 v[64:65], s[16:17], 0, v[64:65]
	s_lshl_b32 s4, s60, 1
	v_lshl_add_u64 v[64:65], v[64:65], 0, s[4:5]
	v_lshlrev_b32_e32 v128, 3, v146
	v_lshl_add_u64 v[64:65], v[64:65], 0, v[128:129]
	global_load_dwordx2 v[70:71], v[64:65], off
	global_load_dwordx2 v[72:73], v[64:65], off offset:16
	v_pk_mul_f32 v[76:77], v[60:61], v[60:61]
	v_pk_mul_f32 v[78:79], v[62:63], v[62:63]
	v_add_f32_e32 v66, v76, v66
	v_add_f32_e32 v66, v77, v66
	v_add_f32_e32 v66, v78, v66
	v_pk_mul_f32 v[80:81], v[32:33], v[32:33]
	v_add_f32_e32 v66, v79, v66
	v_add_f32_e32 v66, v66, v80
	v_pk_mul_f32 v[82:83], v[34:35], v[34:35]
	v_add_f32_e32 v66, v81, v66
	v_add_f32_e32 v66, v82, v66
	v_pk_mul_f32 v[84:85], v[36:37], v[36:37]
	v_add_f32_e32 v66, v83, v66
	v_add_f32_e32 v66, v84, v66
	v_pk_mul_f32 v[86:87], v[38:39], v[38:39]
	v_add_f32_e32 v66, v85, v66
	v_add_f32_e32 v66, v86, v66
	v_pk_mul_f32 v[88:89], v[40:41], v[40:41]
	v_add_f32_e32 v66, v87, v66
	v_add_f32_e32 v66, v88, v66
	v_pk_mul_f32 v[90:91], v[42:43], v[42:43]
	v_add_f32_e32 v66, v89, v66
	v_add_f32_e32 v66, v90, v66
	v_pk_mul_f32 v[92:93], v[44:45], v[44:45]
	v_add_f32_e32 v66, v91, v66
	v_add_f32_e32 v66, v92, v66
	v_pk_mul_f32 v[94:95], v[46:47], v[46:47]
	v_add_f32_e32 v66, v93, v66
	v_add_f32_e32 v66, v94, v66
	v_pk_mul_f32 v[96:97], v[16:17], v[16:17]
	v_add_f32_e32 v66, v95, v66
	v_add_f32_e32 v66, v66, v96
	v_pk_mul_f32 v[98:99], v[18:19], v[18:19]
	v_add_f32_e32 v66, v97, v66
	v_add_f32_e32 v66, v98, v66
	v_pk_mul_f32 v[100:101], v[20:21], v[20:21]
	v_add_f32_e32 v66, v99, v66
	v_add_f32_e32 v66, v100, v66
	v_and_b32_e32 v74, 64, v197
	v_pk_mul_f32 v[102:103], v[22:23], v[22:23]
	v_add_f32_e32 v66, v101, v66
	v_xor_b32_e32 v67, 32, v197
	v_add_u32_e32 v74, 64, v74
	v_add_f32_e32 v66, v102, v66
	v_cmp_lt_i32_e32 vcc, v67, v74
	global_load_dwordx2 v[74:75], v[64:65], off offset:32
	global_load_dwordx2 v[76:77], v[64:65], off offset:48
	v_pk_mul_f32 v[104:105], v[24:25], v[24:25]
	v_add_f32_e32 v66, v103, v66
	v_add_f32_e32 v66, v104, v66
	v_pk_mul_f32 v[106:107], v[26:27], v[26:27]
	v_add_f32_e32 v66, v105, v66
	v_add_f32_e32 v66, v106, v66
	v_pk_mul_f32 v[108:109], v[28:29], v[28:29]
	v_add_f32_e32 v66, v107, v66
	v_add_f32_e32 v66, v108, v66
	v_pk_mul_f32 v[110:111], v[30:31], v[30:31]
	v_add_f32_e32 v66, v109, v66
	v_add_f32_e32 v66, v110, v66
	v_pk_mul_f32 v[112:113], v[0:1], v[0:1]
	v_add_f32_e32 v66, v111, v66
	v_add_f32_e32 v66, v66, v112
	v_pk_mul_f32 v[114:115], v[2:3], v[2:3]
	v_add_f32_e32 v66, v113, v66
	v_add_f32_e32 v66, v114, v66
	v_pk_mul_f32 v[116:117], v[4:5], v[4:5]
	v_add_f32_e32 v66, v115, v66
	v_add_f32_e32 v66, v116, v66
	v_pk_mul_f32 v[118:119], v[6:7], v[6:7]
	v_add_f32_e32 v66, v117, v66
	v_add_f32_e32 v66, v118, v66
	v_pk_mul_f32 v[120:121], v[8:9], v[8:9]
	v_add_f32_e32 v66, v119, v66
	v_add_f32_e32 v66, v120, v66
	v_pk_mul_f32 v[122:123], v[10:11], v[10:11]
	v_add_f32_e32 v66, v121, v66
	v_add_f32_e32 v66, v122, v66
	v_pk_mul_f32 v[124:125], v[12:13], v[12:13]
	v_add_f32_e32 v66, v123, v66
	v_add_f32_e32 v66, v124, v66
	v_pk_mul_f32 v[126:127], v[14:15], v[14:15]
	v_add_f32_e32 v66, v125, v66
	v_add_f32_e32 v66, v126, v66
	v_cndmask_b32_e32 v67, v197, v67, vcc
	v_add_f32_e32 v66, v127, v66
	v_lshlrev_b32_e32 v67, 2, v67
	ds_bpermute_b32 v67, v67, v66
	s_waitcnt vmcnt(3)
; DI unsigned pack2(float a, float b) { f2_t f = {a, b}; bf2_t r = __builtin_convertvector(f, bf2_t); return __builtin_bit_cast(unsigned, r); }
; DI float bflo(unsigned u) { return __uint_as_float(u << 16); }
; DI float bfhi(unsigned u) { return __uint_as_float(u & 0xffff0000u); }
; DI void retention_out_unit(const Params& p, int unit, char* smem) {
;     ...
; #pragma unroll
;   for (int eb = 0; eb < 4; ++eb)
; #pragma unroll
;     for (int g4 = 0; g4 < 4; ++g4) {
;       int e = 32 * eb + 8 * g4 + 4 * h;
;       u32x2 gu = *(const u32x2*)(gp + e);
;       float gv[4] = {bflo(gu[0]), bfhi(gu[0]), bflo(gu[1]), bfhi(gu[1])};
;       float ov[4];
; #pragma unroll
;       for (int q = 0; q < 4; ++q) { float gg = gv[q]; float sl = gg * __builtin_amdgcn_rcpf(1.f + __expf(-gg)); ov[q] = o[eb][4 * g4 + q] * rn * sl; }
;       u32x2 st = {pack2(ov[0], ov[1]), pack2(ov[2], ov[3])};
;       *(u32x2*)(op + e) = st;
;     }
	v_lshlrev_b32_e32 v78, 16, v70
	v_and_b32_e32 v79, 0xffff0000, v70
	v_mul_f32_e32 v70, 0xbfb8aa3b, v79
	v_exp_f32_e32 v80, v70
	s_waitcnt lgkmcnt(0)
	v_add_f32_e32 v66, v66, v67
	v_fmamk_f32 v66, v66, 0x3c000000, v137
	v_mul_f32_e32 v67, 0x4b800000, v66
	v_cmp_gt_f32_e32 vcc, s68, v66
	v_and_b32_e32 v81, 0xffff0000, v71
	v_readlane_b32 s2, v246, 36
	v_cndmask_b32_e32 v66, v66, v67, vcc
	v_rsq_f32_e32 v66, v66
	v_lshlrev_b64 v[68:69], 11, v[68:69]
	v_readlane_b32 s3, v246, 37
	v_mul_f32_e32 v67, 0x45800000, v66
	v_cndmask_b32_e32 v66, v66, v67, vcc
	v_mul_f32_e32 v67, 0xbfb8aa3b, v78
	v_exp_f32_e32 v67, v67
	v_lshl_add_u64 v[68:69], s[2:3], 0, v[68:69]
	v_lshl_add_u64 v[68:69], v[68:69], 0, s[4:5]
	v_add_f32_e32 v67, 1.0, v67
	v_rcp_f32_e32 v70, v67
	v_add_f32_e32 v67, 1.0, v80
	v_lshlrev_b32_e32 v80, 16, v71
	v_mul_f32_e32 v71, 0xbfb8aa3b, v80
	v_exp_f32_e32 v82, v71
	v_mul_f32_e32 v71, 0xbfb8aa3b, v81
	v_exp_f32_e32 v83, v71
	v_rcp_f32_e32 v71, v67
	v_add_f32_e32 v67, 1.0, v82
	v_rcp_f32_e32 v82, v67
	v_add_f32_e32 v67, 1.0, v83
	v_rcp_f32_e32 v83, v67
	v_pk_mul_f32 v[70:71], v[70:71], v[78:79]
	v_pk_mul_f32 v[48:49], v[48:49], v[66:67] op_sel_hi:[1,0]
	v_pk_mul_f32 v[50:51], v[50:51], v[66:67] op_sel_hi:[1,0]
	v_pk_mul_f32 v[48:49], v[70:71], v[48:49]
	v_pk_mul_f32 v[70:71], v[82:83], v[80:81]
	global_load_dwordx2 v[78:79], v[64:65], off offset:64
	v_pk_mul_f32 v[50:51], v[70:71], v[50:51]
	v_cvt_pk_bf16_f32 v70, v48, v49
	v_cvt_pk_bf16_f32 v71, v50, v51
	s_waitcnt vmcnt(3)
	v_lshlrev_b32_e32 v50, 16, v72
	v_and_b32_e32 v51, 0xffff0000, v72
	v_mul_f32_e32 v67, 0xbfb8aa3b, v50
	v_lshl_add_u64 v[48:49], v[68:69], 0, v[128:129]
	v_exp_f32_e32 v67, v67
	v_mul_f32_e32 v68, 0xbfb8aa3b, v51
	v_exp_f32_e32 v69, v68
	global_store_dwordx2 v[48:49], v[70:71], off
	v_add_f32_e32 v67, 1.0, v67
	v_lshlrev_b32_e32 v70, 16, v73
	v_rcp_f32_e32 v68, v67
	v_add_f32_e32 v67, 1.0, v69
	v_and_b32_e32 v71, 0xffff0000, v73
	v_mul_f32_e32 v69, 0xbfb8aa3b, v70
	v_exp_f32_e32 v72, v69
	v_mul_f32_e32 v69, 0xbfb8aa3b, v71
	v_exp_f32_e32 v73, v69
	v_rcp_f32_e32 v69, v67
	v_add_f32_e32 v67, 1.0, v72
	v_rcp_f32_e32 v72, v67
	v_add_f32_e32 v67, 1.0, v73
	v_rcp_f32_e32 v73, v67
	v_pk_mul_f32 v[50:51], v[68:69], v[50:51]
	v_pk_mul_f32 v[52:53], v[52:53], v[66:67] op_sel_hi:[1,0]
	v_pk_mul_f32 v[54:55], v[54:55], v[66:67] op_sel_hi:[1,0]
	v_pk_mul_f32 v[50:51], v[52:53], v[50:51]
	v_pk_mul_f32 v[52:53], v[72:73], v[70:71]
	v_cvt_pk_bf16_f32 v50, v50, v51
	v_pk_mul_f32 v[52:53], v[54:55], v[52:53]
	s_waitcnt vmcnt(3)
	v_lshlrev_b32_e32 v68, 16, v75
	v_cvt_pk_bf16_f32 v51, v52, v53
	v_lshlrev_b32_e32 v52, 16, v74
	v_and_b32_e32 v53, 0xffff0000, v74
	v_mul_f32_e32 v54, 0xbfb8aa3b, v52
	v_mul_f32_e32 v55, 0xbfb8aa3b, v53
	v_exp_f32_e32 v54, v54
	v_exp_f32_e32 v55, v55
	global_store_dwordx2 v[48:49], v[50:51], off offset:16
	v_and_b32_e32 v69, 0xffff0000, v75
	v_add_f32_e32 v50, 1.0, v54
	v_add_f32_e32 v51, 1.0, v55
	global_load_dwordx2 v[54:55], v[64:65], off offset:80
	v_mul_f32_e32 v67, 0xbfb8aa3b, v68
	v_exp_f32_e32 v67, v67
	v_mul_f32_e32 v70, 0xbfb8aa3b, v69
	v_exp_f32_e32 v71, v70
	v_rcp_f32_e32 v50, v50
	v_add_f32_e32 v67, 1.0, v67
	v_rcp_f32_e32 v51, v51
	v_rcp_f32_e32 v70, v67
	v_add_f32_e32 v67, 1.0, v71
	v_rcp_f32_e32 v71, v67
	v_pk_mul_f32 v[50:51], v[50:51], v[52:53]
	v_pk_mul_f32 v[52:53], v[56:57], v[66:67] op_sel_hi:[1,0]
	v_pk_mul_f32 v[56:57], v[58:59], v[66:67] op_sel_hi:[1,0]
	v_pk_mul_f32 v[50:51], v[52:53], v[50:51]
	v_pk_mul_f32 v[52:53], v[70:71], v[68:69]
	v_cvt_pk_bf16_f32 v50, v50, v51
	v_pk_mul_f32 v[52:53], v[56:57], v[52:53]
	s_waitcnt vmcnt(4)
	v_lshlrev_b32_e32 v58, 16, v77
	v_cvt_pk_bf16_f32 v51, v52, v53
	v_lshlrev_b32_e32 v52, 16, v76
	v_and_b32_e32 v53, 0xffff0000, v76
	v_mul_f32_e32 v56, 0xbfb8aa3b, v52
	v_mul_f32_e32 v57, 0xbfb8aa3b, v53
	v_exp_f32_e32 v56, v56
	v_exp_f32_e32 v57, v57
	global_store_dwordx2 v[48:49], v[50:51], off offset:32
	v_and_b32_e32 v59, 0xffff0000, v77
	v_add_f32_e32 v50, 1.0, v56
	v_add_f32_e32 v51, 1.0, v57
	global_load_dwordx2 v[56:57], v[64:65], off offset:96
	v_mul_f32_e32 v67, 0xbfb8aa3b, v58
	v_exp_f32_e32 v67, v67
	v_mul_f32_e32 v68, 0xbfb8aa3b, v59
	v_exp_f32_e32 v69, v68
	v_rcp_f32_e32 v50, v50
	v_add_f32_e32 v67, 1.0, v67
	v_rcp_f32_e32 v51, v51
	v_rcp_f32_e32 v68, v67
	v_add_f32_e32 v67, 1.0, v69
	v_rcp_f32_e32 v69, v67
	v_pk_mul_f32 v[50:51], v[50:51], v[52:53]
	v_pk_mul_f32 v[52:53], v[60:61], v[66:67] op_sel_hi:[1,0]
	v_pk_mul_f32 v[32:33], v[32:33], v[66:67] op_sel_hi:[1,0]
	v_pk_mul_f32 v[50:51], v[52:53], v[50:51]
	v_pk_mul_f32 v[52:53], v[68:69], v[58:59]
	v_pk_mul_f32 v[58:59], v[62:63], v[66:67] op_sel_hi:[1,0]
	v_cvt_pk_bf16_f32 v50, v50, v51
	v_pk_mul_f32 v[52:53], v[58:59], v[52:53]
	v_pk_mul_f32 v[34:35], v[34:35], v[66:67] op_sel_hi:[1,0]
	v_cvt_pk_bf16_f32 v51, v52, v53
	global_load_dwordx2 v[52:53], v[64:65], off offset:112
	s_waitcnt vmcnt(6)
	v_lshlrev_b32_e32 v58, 16, v78
	v_and_b32_e32 v59, 0xffff0000, v78
	v_mul_f32_e32 v60, 0xbfb8aa3b, v58
	v_mul_f32_e32 v61, 0xbfb8aa3b, v59
	v_exp_f32_e32 v60, v60
	v_exp_f32_e32 v61, v61
	global_store_dwordx2 v[48:49], v[50:51], off offset:48
	v_pk_mul_f32 v[16:17], v[16:17], v[66:67] op_sel_hi:[1,0]
	v_add_f32_e32 v50, 1.0, v60
	v_add_f32_e32 v51, 1.0, v61
	v_lshlrev_b32_e32 v60, 16, v79
	v_and_b32_e32 v61, 0xffff0000, v79
	v_mul_f32_e32 v62, 0xbfb8aa3b, v60
	v_mul_f32_e32 v63, 0xbfb8aa3b, v61
	v_exp_f32_e32 v62, v62
	v_exp_f32_e32 v63, v63
	v_rcp_f32_e32 v50, v50
	v_rcp_f32_e32 v51, v51
	v_add_f32_e32 v62, 1.0, v62
	v_add_f32_e32 v63, 1.0, v63
	v_rcp_f32_e32 v62, v62
	v_rcp_f32_e32 v63, v63
	v_pk_mul_f32 v[50:51], v[50:51], v[58:59]
	global_load_dwordx2 v[58:59], v[64:65], off offset:128
	v_pk_mul_f32 v[32:33], v[32:33], v[50:51]
	v_pk_mul_f32 v[50:51], v[62:63], v[60:61]
	v_cvt_pk_bf16_f32 v32, v32, v33
	v_pk_mul_f32 v[34:35], v[34:35], v[50:51]
	v_pk_mul_f32 v[18:19], v[18:19], v[66:67] op_sel_hi:[1,0]
	v_cvt_pk_bf16_f32 v33, v34, v35
	s_waitcnt vmcnt(5)
; DI unsigned pack2(float a, float b) { f2_t f = {a, b}; bf2_t r = __builtin_convertvector(f, bf2_t); return __builtin_bit_cast(unsigned, r); }
; DI float bflo(unsigned u) { return __uint_as_float(u << 16); }
; DI float bfhi(unsigned u) { return __uint_as_float(u & 0xffff0000u); }
; DI void retention_out_unit(const Params& p, int unit, char* smem) {
;     ...
; #pragma unroll
;   for (int eb = 0; eb < 4; ++eb)
; #pragma unroll
;     for (int g4 = 0; g4 < 4; ++g4) {
;       int e = 32 * eb + 8 * g4 + 4 * h;
;       u32x2 gu = *(const u32x2*)(gp + e);
;       float gv[4] = {bflo(gu[0]), bfhi(gu[0]), bflo(gu[1]), bfhi(gu[1])};
;       float ov[4];
; #pragma unroll
;       for (int q = 0; q < 4; ++q) { float gg = gv[q]; float sl = gg * __builtin_amdgcn_rcpf(1.f + __expf(-gg)); ov[q] = o[eb][4 * g4 + q] * rn * sl; }
;       u32x2 st = {pack2(ov[0], ov[1]), pack2(ov[2], ov[3])};
;       *(u32x2*)(op + e) = st;
;     }
	v_lshlrev_b32_e32 v34, 16, v54
	v_and_b32_e32 v35, 0xffff0000, v54
	v_mul_f32_e32 v50, 0xbfb8aa3b, v34
	v_mul_f32_e32 v51, 0xbfb8aa3b, v35
	v_exp_f32_e32 v50, v50
	v_exp_f32_e32 v51, v51
	global_store_dwordx2 v[48:49], v[32:33], off offset:64
	v_pk_mul_f32 v[0:1], v[0:1], v[66:67] op_sel_hi:[1,0]
	v_add_f32_e32 v32, 1.0, v50
	v_add_f32_e32 v33, 1.0, v51
	v_lshlrev_b32_e32 v50, 16, v55
	v_and_b32_e32 v51, 0xffff0000, v55
	v_mul_f32_e32 v54, 0xbfb8aa3b, v50
	v_mul_f32_e32 v55, 0xbfb8aa3b, v51
	v_exp_f32_e32 v54, v54
	v_exp_f32_e32 v55, v55
	v_rcp_f32_e32 v32, v32
	v_rcp_f32_e32 v33, v33
	v_add_f32_e32 v54, 1.0, v54
	v_add_f32_e32 v55, 1.0, v55
	v_rcp_f32_e32 v54, v54
	v_rcp_f32_e32 v55, v55
	v_pk_mul_f32 v[32:33], v[32:33], v[34:35]
	v_pk_mul_f32 v[34:35], v[36:37], v[66:67] op_sel_hi:[1,0]
	v_pk_mul_f32 v[36:37], v[38:39], v[66:67] op_sel_hi:[1,0]
	v_pk_mul_f32 v[32:33], v[34:35], v[32:33]
	v_pk_mul_f32 v[34:35], v[54:55], v[50:51]
	v_cvt_pk_bf16_f32 v32, v32, v33
	v_pk_mul_f32 v[34:35], v[36:37], v[34:35]
	s_waitcnt vmcnt(4)
	v_lshlrev_b32_e32 v38, 16, v57
	v_cvt_pk_bf16_f32 v33, v34, v35
	v_lshlrev_b32_e32 v34, 16, v56
	v_and_b32_e32 v35, 0xffff0000, v56
	v_mul_f32_e32 v36, 0xbfb8aa3b, v34
	v_mul_f32_e32 v37, 0xbfb8aa3b, v35
	v_exp_f32_e32 v36, v36
	v_exp_f32_e32 v37, v37
	global_store_dwordx2 v[48:49], v[32:33], off offset:80
	v_and_b32_e32 v39, 0xffff0000, v57
	v_add_f32_e32 v32, 1.0, v36
	v_add_f32_e32 v33, 1.0, v37
	global_load_dwordx2 v[36:37], v[64:65], off offset:144
	v_mul_f32_e32 v50, 0xbfb8aa3b, v38
	v_mul_f32_e32 v51, 0xbfb8aa3b, v39
	v_exp_f32_e32 v50, v50
	v_exp_f32_e32 v51, v51
	v_rcp_f32_e32 v32, v32
	v_rcp_f32_e32 v33, v33
	v_add_f32_e32 v50, 1.0, v50
	v_add_f32_e32 v51, 1.0, v51
	v_rcp_f32_e32 v50, v50
	v_rcp_f32_e32 v51, v51
	v_pk_mul_f32 v[32:33], v[32:33], v[34:35]
	v_pk_mul_f32 v[34:35], v[40:41], v[66:67] op_sel_hi:[1,0]
	s_waitcnt vmcnt(5)
	v_lshlrev_b32_e32 v40, 16, v53
	v_pk_mul_f32 v[32:33], v[34:35], v[32:33]
	v_pk_mul_f32 v[34:35], v[50:51], v[38:39]
	v_pk_mul_f32 v[38:39], v[42:43], v[66:67] op_sel_hi:[1,0]
	v_cvt_pk_bf16_f32 v32, v32, v33
	v_pk_mul_f32 v[34:35], v[38:39], v[34:35]
	v_and_b32_e32 v41, 0xffff0000, v53
	v_cvt_pk_bf16_f32 v33, v34, v35
	v_lshlrev_b32_e32 v34, 16, v52
	v_and_b32_e32 v35, 0xffff0000, v52
	v_mul_f32_e32 v38, 0xbfb8aa3b, v34
	v_mul_f32_e32 v39, 0xbfb8aa3b, v35
	v_exp_f32_e32 v38, v38
	v_exp_f32_e32 v39, v39
	global_store_dwordx2 v[48:49], v[32:33], off offset:96
	v_mul_f32_e32 v42, 0xbfb8aa3b, v40
	v_add_f32_e32 v32, 1.0, v38
	v_add_f32_e32 v33, 1.0, v39
	global_load_dwordx2 v[38:39], v[64:65], off offset:160
	v_mul_f32_e32 v43, 0xbfb8aa3b, v41
	v_exp_f32_e32 v42, v42
	v_exp_f32_e32 v43, v43
	v_rcp_f32_e32 v32, v32
	v_rcp_f32_e32 v33, v33
	v_add_f32_e32 v42, 1.0, v42
	v_add_f32_e32 v43, 1.0, v43
	v_rcp_f32_e32 v42, v42
	v_rcp_f32_e32 v43, v43
	v_pk_mul_f32 v[32:33], v[32:33], v[34:35]
	v_pk_mul_f32 v[34:35], v[44:45], v[66:67] op_sel_hi:[1,0]
	v_pk_mul_f32 v[2:3], v[2:3], v[66:67] op_sel_hi:[1,0]
	v_pk_mul_f32 v[32:33], v[34:35], v[32:33]
	v_pk_mul_f32 v[34:35], v[42:43], v[40:41]
	v_pk_mul_f32 v[40:41], v[46:47], v[66:67] op_sel_hi:[1,0]
	v_cvt_pk_bf16_f32 v32, v32, v33
	v_pk_mul_f32 v[34:35], v[40:41], v[34:35]
	s_nop 0
	v_cvt_pk_bf16_f32 v33, v34, v35
	global_load_dwordx2 v[34:35], v[64:65], off offset:176
	s_waitcnt vmcnt(6)
	v_lshlrev_b32_e32 v40, 16, v58
	v_and_b32_e32 v41, 0xffff0000, v58
	v_mul_f32_e32 v42, 0xbfb8aa3b, v40
	v_mul_f32_e32 v43, 0xbfb8aa3b, v41
	v_exp_f32_e32 v42, v42
	v_exp_f32_e32 v43, v43
	global_store_dwordx2 v[48:49], v[32:33], off offset:112
	v_add_f32_e32 v32, 1.0, v42
	v_add_f32_e32 v33, 1.0, v43
	v_lshlrev_b32_e32 v42, 16, v59
	v_and_b32_e32 v43, 0xffff0000, v59
	v_mul_f32_e32 v44, 0xbfb8aa3b, v42
	v_mul_f32_e32 v45, 0xbfb8aa3b, v43
	v_exp_f32_e32 v44, v44
	v_exp_f32_e32 v45, v45
	v_rcp_f32_e32 v32, v32
	v_rcp_f32_e32 v33, v33
	v_add_f32_e32 v44, 1.0, v44
	v_add_f32_e32 v45, 1.0, v45
	v_rcp_f32_e32 v44, v44
	v_rcp_f32_e32 v45, v45
	v_pk_mul_f32 v[32:33], v[32:33], v[40:41]
	global_load_dwordx2 v[40:41], v[64:65], off offset:192
	v_pk_mul_f32 v[16:17], v[16:17], v[32:33]
	v_pk_mul_f32 v[32:33], v[44:45], v[42:43]
	v_cvt_pk_bf16_f32 v16, v16, v17
	v_pk_mul_f32 v[18:19], v[18:19], v[32:33]
	s_nop 0
	v_cvt_pk_bf16_f32 v17, v18, v19
	s_waitcnt vmcnt(5)
	v_lshlrev_b32_e32 v18, 16, v36
	v_and_b32_e32 v19, 0xffff0000, v36
	v_mul_f32_e32 v32, 0xbfb8aa3b, v18
	v_mul_f32_e32 v33, 0xbfb8aa3b, v19
	v_exp_f32_e32 v32, v32
	v_exp_f32_e32 v33, v33
	global_store_dwordx2 v[48:49], v[16:17], off offset:128
	v_add_f32_e32 v16, 1.0, v32
	v_add_f32_e32 v17, 1.0, v33
	v_lshlrev_b32_e32 v32, 16, v37
	v_and_b32_e32 v33, 0xffff0000, v37
	v_mul_f32_e32 v36, 0xbfb8aa3b, v32
	v_mul_f32_e32 v37, 0xbfb8aa3b, v33
	v_exp_f32_e32 v36, v36
	v_exp_f32_e32 v37, v37
	v_rcp_f32_e32 v16, v16
	v_rcp_f32_e32 v17, v17
	v_add_f32_e32 v36, 1.0, v36
	v_add_f32_e32 v37, 1.0, v37
	v_rcp_f32_e32 v36, v36
	v_rcp_f32_e32 v37, v37
	v_pk_mul_f32 v[16:17], v[16:17], v[18:19]
	v_pk_mul_f32 v[18:19], v[20:21], v[66:67] op_sel_hi:[1,0]
	v_pk_mul_f32 v[20:21], v[22:23], v[66:67] op_sel_hi:[1,0]
	v_pk_mul_f32 v[16:17], v[18:19], v[16:17]
	v_pk_mul_f32 v[18:19], v[36:37], v[32:33]
	v_cvt_pk_bf16_f32 v16, v16, v17
	v_pk_mul_f32 v[18:19], v[20:21], v[18:19]
	s_waitcnt vmcnt(4)
; DI unsigned pack2(float a, float b) { f2_t f = {a, b}; bf2_t r = __builtin_convertvector(f, bf2_t); return __builtin_bit_cast(unsigned, r); }
; DI float bflo(unsigned u) { return __uint_as_float(u << 16); }
; DI float bfhi(unsigned u) { return __uint_as_float(u & 0xffff0000u); }
; DI void retention_out_unit(const Params& p, int unit, char* smem) {
;     ...
; #pragma unroll
;   for (int eb = 0; eb < 4; ++eb)
; #pragma unroll
;     for (int g4 = 0; g4 < 4; ++g4) {
;       int e = 32 * eb + 8 * g4 + 4 * h;
;       u32x2 gu = *(const u32x2*)(gp + e);
;       float gv[4] = {bflo(gu[0]), bfhi(gu[0]), bflo(gu[1]), bfhi(gu[1])};
;       float ov[4];
; #pragma unroll
;       for (int q = 0; q < 4; ++q) { float gg = gv[q]; float sl = gg * __builtin_amdgcn_rcpf(1.f + __expf(-gg)); ov[q] = o[eb][4 * g4 + q] * rn * sl; }
;       u32x2 st = {pack2(ov[0], ov[1]), pack2(ov[2], ov[3])};
;       *(u32x2*)(op + e) = st;
;     }
	v_lshlrev_b32_e32 v22, 16, v39
	v_cvt_pk_bf16_f32 v17, v18, v19
	v_lshlrev_b32_e32 v18, 16, v38
	v_and_b32_e32 v19, 0xffff0000, v38
	v_mul_f32_e32 v20, 0xbfb8aa3b, v18
	v_mul_f32_e32 v21, 0xbfb8aa3b, v19
	v_exp_f32_e32 v20, v20
	v_exp_f32_e32 v21, v21
	global_store_dwordx2 v[48:49], v[16:17], off offset:144
	v_and_b32_e32 v23, 0xffff0000, v39
	v_add_f32_e32 v16, 1.0, v20
	v_add_f32_e32 v17, 1.0, v21
	global_load_dwordx2 v[20:21], v[64:65], off offset:208
	v_mul_f32_e32 v32, 0xbfb8aa3b, v22
	v_mul_f32_e32 v33, 0xbfb8aa3b, v23
	v_exp_f32_e32 v32, v32
	v_exp_f32_e32 v33, v33
	v_rcp_f32_e32 v16, v16
	v_rcp_f32_e32 v17, v17
	v_add_f32_e32 v32, 1.0, v32
	v_add_f32_e32 v33, 1.0, v33
	v_rcp_f32_e32 v32, v32
	v_rcp_f32_e32 v33, v33
	v_pk_mul_f32 v[16:17], v[16:17], v[18:19]
	v_pk_mul_f32 v[18:19], v[24:25], v[66:67] op_sel_hi:[1,0]
	s_waitcnt vmcnt(5)
	v_lshlrev_b32_e32 v24, 16, v35
	v_pk_mul_f32 v[16:17], v[18:19], v[16:17]
	v_pk_mul_f32 v[18:19], v[32:33], v[22:23]
	v_pk_mul_f32 v[22:23], v[26:27], v[66:67] op_sel_hi:[1,0]
	v_cvt_pk_bf16_f32 v16, v16, v17
	v_pk_mul_f32 v[18:19], v[22:23], v[18:19]
	global_load_dwordx2 v[22:23], v[64:65], off offset:224
	v_cvt_pk_bf16_f32 v17, v18, v19
	global_store_dwordx2 v[48:49], v[16:17], off offset:160
	v_lshlrev_b32_e32 v16, 16, v34
	v_mul_f32_e32 v17, 0xbfb8aa3b, v16
	v_exp_f32_e32 v18, v17
	v_and_b32_e32 v17, 0xffff0000, v34
	v_mul_f32_e32 v19, 0xbfb8aa3b, v17
	v_and_b32_e32 v25, 0xffff0000, v35
	v_exp_f32_e32 v19, v19
	v_mul_f32_e32 v26, 0xbfb8aa3b, v24
	v_mul_f32_e32 v27, 0xbfb8aa3b, v25
	v_exp_f32_e32 v26, v26
	v_exp_f32_e32 v27, v27
	v_add_f32_e32 v18, 1.0, v18
	v_add_f32_e32 v19, 1.0, v19
	v_rcp_f32_e32 v18, v18
	v_rcp_f32_e32 v19, v19
	v_add_f32_e32 v26, 1.0, v26
	v_add_f32_e32 v27, 1.0, v27
	v_rcp_f32_e32 v26, v26
	v_rcp_f32_e32 v27, v27
	v_pk_mul_f32 v[16:17], v[18:19], v[16:17]
	v_pk_mul_f32 v[18:19], v[28:29], v[66:67] op_sel_hi:[1,0]
	s_nop 0
	v_pk_mul_f32 v[16:17], v[18:19], v[16:17]
	v_pk_mul_f32 v[18:19], v[26:27], v[24:25]
	v_pk_mul_f32 v[24:25], v[30:31], v[66:67] op_sel_hi:[1,0]
	v_cvt_pk_bf16_f32 v16, v16, v17
	v_pk_mul_f32 v[18:19], v[24:25], v[18:19]
	s_nop 0
	v_cvt_pk_bf16_f32 v17, v18, v19
	global_load_dwordx2 v[18:19], v[64:65], off offset:240
	s_waitcnt vmcnt(6)
	v_lshlrev_b32_e32 v24, 16, v40
	v_and_b32_e32 v25, 0xffff0000, v40
	v_mul_f32_e32 v26, 0xbfb8aa3b, v24
	v_mul_f32_e32 v27, 0xbfb8aa3b, v25
	v_exp_f32_e32 v26, v26
	v_exp_f32_e32 v27, v27
	global_store_dwordx2 v[48:49], v[16:17], off offset:176
	v_add_f32_e32 v16, 1.0, v26
	v_add_f32_e32 v17, 1.0, v27
	v_lshlrev_b32_e32 v26, 16, v41
	v_and_b32_e32 v27, 0xffff0000, v41
	v_mul_f32_e32 v28, 0xbfb8aa3b, v26
	v_mul_f32_e32 v29, 0xbfb8aa3b, v27
	v_exp_f32_e32 v28, v28
	v_exp_f32_e32 v29, v29
	v_rcp_f32_e32 v16, v16
	v_rcp_f32_e32 v17, v17
	v_add_f32_e32 v28, 1.0, v28
	v_add_f32_e32 v29, 1.0, v29
	v_rcp_f32_e32 v28, v28
	v_rcp_f32_e32 v29, v29
	v_pk_mul_f32 v[16:17], v[16:17], v[24:25]
	s_nop 0
	v_pk_mul_f32 v[0:1], v[0:1], v[16:17]
	v_pk_mul_f32 v[16:17], v[28:29], v[26:27]
	v_cvt_pk_bf16_f32 v0, v0, v1
	v_pk_mul_f32 v[2:3], v[2:3], v[16:17]
	s_nop 0
	v_cvt_pk_bf16_f32 v1, v2, v3
	s_waitcnt vmcnt(4)
	v_lshlrev_b32_e32 v2, 16, v20
	v_and_b32_e32 v3, 0xffff0000, v20
	v_mul_f32_e32 v16, 0xbfb8aa3b, v2
	v_mul_f32_e32 v17, 0xbfb8aa3b, v3
	v_exp_f32_e32 v16, v16
	v_exp_f32_e32 v17, v17
	global_store_dwordx2 v[48:49], v[0:1], off offset:192
	v_add_f32_e32 v0, 1.0, v16
	v_add_f32_e32 v1, 1.0, v17
	v_lshlrev_b32_e32 v16, 16, v21
	v_and_b32_e32 v17, 0xffff0000, v21
	v_mul_f32_e32 v20, 0xbfb8aa3b, v16
	v_mul_f32_e32 v21, 0xbfb8aa3b, v17
	v_exp_f32_e32 v20, v20
	v_exp_f32_e32 v21, v21
	v_rcp_f32_e32 v0, v0
	v_rcp_f32_e32 v1, v1
	v_add_f32_e32 v20, 1.0, v20
	v_add_f32_e32 v21, 1.0, v21
	v_rcp_f32_e32 v20, v20
	v_rcp_f32_e32 v21, v21
	v_pk_mul_f32 v[0:1], v[0:1], v[2:3]
	v_pk_mul_f32 v[2:3], v[4:5], v[66:67] op_sel_hi:[1,0]
	v_pk_mul_f32 v[4:5], v[6:7], v[66:67] op_sel_hi:[1,0]
	v_pk_mul_f32 v[0:1], v[2:3], v[0:1]
	v_pk_mul_f32 v[2:3], v[20:21], v[16:17]
	v_cvt_pk_bf16_f32 v0, v0, v1
	v_pk_mul_f32 v[2:3], v[4:5], v[2:3]
	s_nop 0
	v_cvt_pk_bf16_f32 v1, v2, v3
	s_waitcnt vmcnt(4)
	v_lshlrev_b32_e32 v2, 16, v22
	v_and_b32_e32 v3, 0xffff0000, v22
	v_mul_f32_e32 v4, 0xbfb8aa3b, v2
	v_mul_f32_e32 v5, 0xbfb8aa3b, v3
	v_exp_f32_e32 v4, v4
	v_exp_f32_e32 v5, v5
	global_store_dwordx2 v[48:49], v[0:1], off offset:208
	v_add_f32_e32 v0, 1.0, v4
	v_add_f32_e32 v1, 1.0, v5
	v_lshlrev_b32_e32 v4, 16, v23
	v_and_b32_e32 v5, 0xffff0000, v23
	v_mul_f32_e32 v6, 0xbfb8aa3b, v4
	v_mul_f32_e32 v7, 0xbfb8aa3b, v5
	v_exp_f32_e32 v6, v6
	v_exp_f32_e32 v7, v7
	v_rcp_f32_e32 v0, v0
	v_rcp_f32_e32 v1, v1
	v_add_f32_e32 v6, 1.0, v6
	v_add_f32_e32 v7, 1.0, v7
	v_rcp_f32_e32 v6, v6
	v_rcp_f32_e32 v7, v7
	v_pk_mul_f32 v[0:1], v[0:1], v[2:3]
	v_pk_mul_f32 v[2:3], v[8:9], v[66:67] op_sel_hi:[1,0]
	s_nop 0
	v_pk_mul_f32 v[0:1], v[2:3], v[0:1]
	v_pk_mul_f32 v[2:3], v[6:7], v[4:5]
	v_pk_mul_f32 v[4:5], v[10:11], v[66:67] op_sel_hi:[1,0]
	v_cvt_pk_bf16_f32 v0, v0, v1
	v_pk_mul_f32 v[2:3], v[4:5], v[2:3]
	s_nop 0
	v_cvt_pk_bf16_f32 v1, v2, v3
	s_waitcnt vmcnt(3)
	v_lshlrev_b32_e32 v2, 16, v18
	v_and_b32_e32 v3, 0xffff0000, v18
	v_mul_f32_e32 v4, 0xbfb8aa3b, v2
	v_mul_f32_e32 v5, 0xbfb8aa3b, v3
	v_exp_f32_e32 v4, v4
	v_exp_f32_e32 v5, v5
	global_store_dwordx2 v[48:49], v[0:1], off offset:224
	v_add_f32_e32 v0, 1.0, v4
	v_add_f32_e32 v1, 1.0, v5
	v_lshlrev_b32_e32 v4, 16, v19
	v_and_b32_e32 v5, 0xffff0000, v19
	v_mul_f32_e32 v6, 0xbfb8aa3b, v4
	v_mul_f32_e32 v7, 0xbfb8aa3b, v5
	v_exp_f32_e32 v6, v6
	v_exp_f32_e32 v7, v7
	v_rcp_f32_e32 v0, v0
	v_rcp_f32_e32 v1, v1
	v_add_f32_e32 v6, 1.0, v6
	v_add_f32_e32 v7, 1.0, v7
	v_rcp_f32_e32 v6, v6
	v_rcp_f32_e32 v7, v7
	v_pk_mul_f32 v[0:1], v[0:1], v[2:3]
	v_pk_mul_f32 v[2:3], v[12:13], v[66:67] op_sel_hi:[1,0]
	s_nop 0
	v_pk_mul_f32 v[0:1], v[2:3], v[0:1]
	v_pk_mul_f32 v[2:3], v[6:7], v[4:5]
	v_pk_mul_f32 v[4:5], v[14:15], v[66:67] op_sel_hi:[1,0]
	v_cvt_pk_bf16_f32 v0, v0, v1
	v_pk_mul_f32 v[2:3], v[4:5], v[2:3]
	s_nop 0
	v_cvt_pk_bf16_f32 v1, v2, v3
	global_store_dwordx2 v[48:49], v[0:1], off offset:240
	s_branch .LBB0_986

; #define G_LOADA(kt_) { _Pragma("unroll") for (int i = 0; i < 4; ++i) ra[i] = al(lrow + 64 * i, (kt_) * 64 + lck * 8); }
; #define G_LOADB(kt_) { _Pragma("unroll") for (int i = 0; i < 4; ++i) rb[i] = bl(lrow + 64 * i, (kt_) * 64 + lck * 8); }
; #define G_STOREA(buf_) { bf16_t* nA = sA + (buf_) * 256 * GLD; _Pragma("unroll") for (int i = 0; i < 4; ++i) *(u32x4*)(nA + (lrow + 64 * i) * GLD + lck * 8) = ra[i]; }
; #define G_STOREB(buf_) { bf16_t* nB = sB + (buf_) * 256 * GLD; _Pragma("unroll") for (int i = 0; i < 4; ++i) *(u32x4*)(nB + (lrow + 64 * i) * GLD + lck * 8) = rb[i]; }
; template <class AL, class BL, class EP>
; DI void gemm_tile256(AL al, BL bl, EP ep, int K, char* smem) {
;     ...
;   G_LOADA(0); G_LOADB(0);
;   __syncthreads();
;   G_STOREA(0); G_STOREB(0);
;   if (KT > 1) G_LOADB(1);
;   __syncthreads();
;   for (int kt = 0; kt < KT; kt += 2) {
;     G_STEP(0, kt);
;     if (kt + 1 >= KT) break;
;     G_STEP(1, kt + 1);
;   }
.Lgk_ph13_loop:
	s_waitcnt lgkmcnt(0)
	v_mfma_f32_32x32x16_bf16 v[112:127], v[184:187], v[152:155], v[112:127]
	ds_read_b128 v[192:195], v199
	ds_read_b128 v[168:171], v151
	v_mfma_f32_32x32x16_bf16 v[96:111], v[188:191], v[152:155], v[96:111]
	ds_read_b128 v[200:203], v199 offset:2048
	ds_read_b128 v[172:175], v151 offset:2048
	v_mfma_f32_32x32x16_bf16 v[80:95], v[184:187], v[156:159], v[80:95]
	ds_read_b128 v[176:179], v151 offset:4096
	ds_read_b128 v[180:183], v151 offset:6144
	v_mfma_f32_32x32x16_bf16 v[64:79], v[188:191], v[156:159], v[64:79]
	s_add_u32 m0, s23, 0x22000
	s_nop 0
	global_load_lds_dwordx4 v[214:215], off
	v_lshl_add_u64 v[214:215], v[214:215], 0, s[4:5]
	v_mfma_f32_32x32x16_bf16 v[48:63], v[184:187], v[160:163], v[48:63]
	v_mfma_f32_32x32x16_bf16 v[32:47], v[188:191], v[160:163], v[32:47]
	v_mfma_f32_32x32x16_bf16 v[16:31], v[184:187], v[164:167], v[16:31]
	v_mfma_f32_32x32x16_bf16 v[0:15], v[188:191], v[164:167], v[0:15]
	s_add_u32 m0, s23, 0x26000
	s_nop 0
	global_load_lds_dwordx4 v[218:219], off
	v_lshl_add_u64 v[218:219], v[218:219], 0, s[4:5]
	s_waitcnt lgkmcnt(0)
	s_waitcnt vmcnt(12)
	s_barrier
	s_waitcnt lgkmcnt(0)
	v_mfma_f32_32x32x16_bf16 v[112:127], v[192:195], v[168:171], v[112:127]
	ds_read_b128 v[184:187], v198 offset:32768
	ds_read_b128 v[152:155], v132 offset:32768
	v_mfma_f32_32x32x16_bf16 v[96:111], v[200:203], v[168:171], v[96:111]
	ds_read_b128 v[188:191], v198 offset:34816
	ds_read_b128 v[156:159], v132 offset:34816
	v_mfma_f32_32x32x16_bf16 v[80:95], v[192:195], v[172:175], v[80:95]
	ds_read_b128 v[160:163], v132 offset:36864
	ds_read_b128 v[164:167], v132 offset:38912
	v_mfma_f32_32x32x16_bf16 v[64:79], v[200:203], v[172:175], v[64:79]
	s_add_u32 m0, s23, 0x0
	s_nop 0
	global_load_lds_dwordx4 v[212:213], off
	v_lshl_add_u64 v[212:213], v[212:213], 0, s[4:5]
	v_mfma_f32_32x32x16_bf16 v[48:63], v[192:195], v[176:179], v[48:63]
	v_mfma_f32_32x32x16_bf16 v[32:47], v[200:203], v[176:179], v[32:47]
	v_mfma_f32_32x32x16_bf16 v[16:31], v[192:195], v[180:183], v[16:31]
	v_mfma_f32_32x32x16_bf16 v[0:15], v[200:203], v[180:183], v[0:15]
	s_add_u32 m0, s23, 0x4000
	s_nop 0
	global_load_lds_dwordx4 v[216:217], off
	v_lshl_add_u64 v[216:217], v[216:217], 0, s[4:5]
	s_waitcnt lgkmcnt(0)
	v_mfma_f32_32x32x16_bf16 v[112:127], v[184:187], v[152:155], v[112:127]
	ds_read_b128 v[192:195], v199 offset:32768
	ds_read_b128 v[168:171], v151 offset:32768
	v_mfma_f32_32x32x16_bf16 v[96:111], v[188:191], v[152:155], v[96:111]
	ds_read_b128 v[200:203], v199 offset:34816
	ds_read_b128 v[172:175], v151 offset:34816
	v_mfma_f32_32x32x16_bf16 v[80:95], v[184:187], v[156:159], v[80:95]
	ds_read_b128 v[176:179], v151 offset:36864
	ds_read_b128 v[180:183], v151 offset:38912
	v_mfma_f32_32x32x16_bf16 v[64:79], v[188:191], v[156:159], v[64:79]
	s_add_u32 m0, s23, 0x2000
	s_nop 0
	global_load_lds_dwordx4 v[214:215], off
	v_lshl_add_u64 v[214:215], v[214:215], 0, s[4:5]
	v_mfma_f32_32x32x16_bf16 v[48:63], v[184:187], v[160:163], v[48:63]
	v_mfma_f32_32x32x16_bf16 v[32:47], v[188:191], v[160:163], v[32:47]
	v_mfma_f32_32x32x16_bf16 v[16:31], v[184:187], v[164:167], v[16:31]
	v_mfma_f32_32x32x16_bf16 v[0:15], v[188:191], v[164:167], v[0:15]
	s_add_u32 m0, s23, 0x6000
	s_nop 0
	global_load_lds_dwordx4 v[218:219], off
	v_lshl_add_u64 v[218:219], v[218:219], 0, s[4:5]
	s_waitcnt lgkmcnt(0)
	s_waitcnt vmcnt(12)
	s_barrier
	s_waitcnt lgkmcnt(0)
	v_mfma_f32_32x32x16_bf16 v[112:127], v[192:195], v[168:171], v[112:127]
	ds_read_b128 v[184:187], v206
	ds_read_b128 v[152:155], v204
	v_mfma_f32_32x32x16_bf16 v[96:111], v[200:203], v[168:171], v[96:111]
	ds_read_b128 v[188:191], v206 offset:2048
	ds_read_b128 v[156:159], v204 offset:2048
	v_mfma_f32_32x32x16_bf16 v[80:95], v[192:195], v[172:175], v[80:95]
	ds_read_b128 v[160:163], v204 offset:4096
	ds_read_b128 v[164:167], v204 offset:6144
	v_mfma_f32_32x32x16_bf16 v[64:79], v[200:203], v[172:175], v[64:79]
	s_add_u32 m0, s23, 0x8000
	s_nop 0
	global_load_lds_dwordx4 v[212:213], off
	v_lshl_add_u64 v[212:213], v[212:213], 0, s[4:5]
	v_mfma_f32_32x32x16_bf16 v[48:63], v[192:195], v[176:179], v[48:63]
	v_mfma_f32_32x32x16_bf16 v[32:47], v[200:203], v[176:179], v[32:47]
	v_mfma_f32_32x32x16_bf16 v[16:31], v[192:195], v[180:183], v[16:31]
	v_mfma_f32_32x32x16_bf16 v[0:15], v[200:203], v[180:183], v[0:15]
	s_add_u32 m0, s23, 0xc000
	s_nop 0
	global_load_lds_dwordx4 v[216:217], off
	v_lshl_add_u64 v[216:217], v[216:217], 0, s[4:5]
	s_waitcnt lgkmcnt(0)
	v_mfma_f32_32x32x16_bf16 v[112:127], v[184:187], v[152:155], v[112:127]
	ds_read_b128 v[192:195], v207
	ds_read_b128 v[168:171], v205
	v_mfma_f32_32x32x16_bf16 v[96:111], v[188:191], v[152:155], v[96:111]
	ds_read_b128 v[200:203], v207 offset:2048
	ds_read_b128 v[172:175], v205 offset:2048
	v_mfma_f32_32x32x16_bf16 v[80:95], v[184:187], v[156:159], v[80:95]
	ds_read_b128 v[176:179], v205 offset:4096
	ds_read_b128 v[180:183], v205 offset:6144
	v_mfma_f32_32x32x16_bf16 v[64:79], v[188:191], v[156:159], v[64:79]
	s_add_u32 m0, s23, 0xa000
	s_nop 0
	global_load_lds_dwordx4 v[214:215], off
	v_lshl_add_u64 v[214:215], v[214:215], 0, s[4:5]
	v_mfma_f32_32x32x16_bf16 v[48:63], v[184:187], v[160:163], v[48:63]
	v_mfma_f32_32x32x16_bf16 v[32:47], v[188:191], v[160:163], v[32:47]
	v_mfma_f32_32x32x16_bf16 v[16:31], v[184:187], v[164:167], v[16:31]
	v_mfma_f32_32x32x16_bf16 v[0:15], v[188:191], v[164:167], v[0:15]
	s_add_u32 m0, s23, 0xe000
	s_nop 0
	global_load_lds_dwordx4 v[218:219], off
	v_lshl_add_u64 v[218:219], v[218:219], 0, s[4:5]
	s_waitcnt lgkmcnt(0)
	s_waitcnt vmcnt(12)
	s_barrier
; #define G_LOADA(kt_) { _Pragma("unroll") for (int i = 0; i < 4; ++i) ra[i] = al(lrow + 64 * i, (kt_) * 64 + lck * 8); }
; #define G_LOADB(kt_) { _Pragma("unroll") for (int i = 0; i < 4; ++i) rb[i] = bl(lrow + 64 * i, (kt_) * 64 + lck * 8); }
; #define G_STOREA(buf_) { bf16_t* nA = sA + (buf_) * 256 * GLD; _Pragma("unroll") for (int i = 0; i < 4; ++i) *(u32x4*)(nA + (lrow + 64 * i) * GLD + lck * 8) = ra[i]; }
; #define G_STOREB(buf_) { bf16_t* nB = sB + (buf_) * 256 * GLD; _Pragma("unroll") for (int i = 0; i < 4; ++i) *(u32x4*)(nB + (lrow + 64 * i) * GLD + lck * 8) = rb[i]; }
; template <class AL, class BL, class EP>
; DI void gemm_tile256(AL al, BL bl, EP ep, int K, char* smem) {
;     ...
;   G_LOADA(0); G_LOADB(0);
;   __syncthreads();
;   G_STOREA(0); G_STOREB(0);
;   if (KT > 1) G_LOADB(1);
;   __syncthreads();
;   for (int kt = 0; kt < KT; kt += 2) {
;     G_STEP(0, kt);
;     if (kt + 1 >= KT) break;
;     G_STEP(1, kt + 1);
;   }
	s_waitcnt lgkmcnt(0)
	v_mfma_f32_32x32x16_bf16 v[112:127], v[192:195], v[168:171], v[112:127]
	ds_read_b128 v[184:187], v206 offset:32768
	ds_read_b128 v[152:155], v204 offset:32768
	v_mfma_f32_32x32x16_bf16 v[96:111], v[200:203], v[168:171], v[96:111]
	ds_read_b128 v[188:191], v206 offset:34816
	ds_read_b128 v[156:159], v204 offset:34816
	v_mfma_f32_32x32x16_bf16 v[80:95], v[192:195], v[172:175], v[80:95]
	ds_read_b128 v[160:163], v204 offset:36864
	ds_read_b128 v[164:167], v204 offset:38912
	v_mfma_f32_32x32x16_bf16 v[64:79], v[200:203], v[172:175], v[64:79]
	s_add_u32 m0, s23, 0x10000
	s_nop 0
	global_load_lds_dwordx4 v[212:213], off
	v_lshl_add_u64 v[212:213], v[212:213], 0, s[4:5]
	v_mfma_f32_32x32x16_bf16 v[48:63], v[192:195], v[176:179], v[48:63]
	v_mfma_f32_32x32x16_bf16 v[32:47], v[200:203], v[176:179], v[32:47]
	v_mfma_f32_32x32x16_bf16 v[16:31], v[192:195], v[180:183], v[16:31]
	v_mfma_f32_32x32x16_bf16 v[0:15], v[200:203], v[180:183], v[0:15]
	s_add_u32 m0, s23, 0x14000
	s_nop 0
	global_load_lds_dwordx4 v[216:217], off
	v_lshl_add_u64 v[216:217], v[216:217], 0, s[4:5]
	s_waitcnt lgkmcnt(0)
	v_mfma_f32_32x32x16_bf16 v[112:127], v[184:187], v[152:155], v[112:127]
	ds_read_b128 v[192:195], v207 offset:32768
	ds_read_b128 v[168:171], v205 offset:32768
	v_mfma_f32_32x32x16_bf16 v[96:111], v[188:191], v[152:155], v[96:111]
	ds_read_b128 v[200:203], v207 offset:34816
	ds_read_b128 v[172:175], v205 offset:34816
	v_mfma_f32_32x32x16_bf16 v[80:95], v[184:187], v[156:159], v[80:95]
	ds_read_b128 v[176:179], v205 offset:36864
	ds_read_b128 v[180:183], v205 offset:38912
	v_mfma_f32_32x32x16_bf16 v[64:79], v[188:191], v[156:159], v[64:79]
	s_add_u32 m0, s23, 0x12000
	s_nop 0
	global_load_lds_dwordx4 v[214:215], off
	v_lshl_add_u64 v[214:215], v[214:215], 0, s[4:5]
	v_mfma_f32_32x32x16_bf16 v[48:63], v[184:187], v[160:163], v[48:63]
	v_mfma_f32_32x32x16_bf16 v[32:47], v[188:191], v[160:163], v[32:47]
	v_mfma_f32_32x32x16_bf16 v[16:31], v[184:187], v[164:167], v[16:31]
	v_mfma_f32_32x32x16_bf16 v[0:15], v[188:191], v[164:167], v[0:15]
	s_add_u32 m0, s23, 0x16000
	s_nop 0
	global_load_lds_dwordx4 v[218:219], off
	v_lshl_add_u64 v[218:219], v[218:219], 0, s[4:5]
	s_waitcnt lgkmcnt(0)
	s_waitcnt vmcnt(12)
	s_barrier
	s_waitcnt lgkmcnt(0)
	v_mfma_f32_32x32x16_bf16 v[112:127], v[192:195], v[168:171], v[112:127]
	ds_read_b128 v[184:187], v210
	ds_read_b128 v[152:155], v208
	v_mfma_f32_32x32x16_bf16 v[96:111], v[200:203], v[168:171], v[96:111]
	ds_read_b128 v[188:191], v210 offset:2048
	ds_read_b128 v[156:159], v208 offset:2048
	v_mfma_f32_32x32x16_bf16 v[80:95], v[192:195], v[172:175], v[80:95]
	ds_read_b128 v[160:163], v208 offset:4096
	ds_read_b128 v[164:167], v208 offset:6144
	v_mfma_f32_32x32x16_bf16 v[64:79], v[200:203], v[172:175], v[64:79]
	s_add_u32 m0, s23, 0x18000
	s_nop 0
	global_load_lds_dwordx4 v[212:213], off
	v_lshl_add_u64 v[212:213], v[212:213], 0, s[4:5]
	v_mfma_f32_32x32x16_bf16 v[48:63], v[192:195], v[176:179], v[48:63]
	v_mfma_f32_32x32x16_bf16 v[32:47], v[200:203], v[176:179], v[32:47]
	v_mfma_f32_32x32x16_bf16 v[16:31], v[192:195], v[180:183], v[16:31]
	v_mfma_f32_32x32x16_bf16 v[0:15], v[200:203], v[180:183], v[0:15]
	s_add_u32 m0, s23, 0x1c000
	s_nop 0
	global_load_lds_dwordx4 v[216:217], off
	v_lshl_add_u64 v[216:217], v[216:217], 0, s[4:5]
	s_waitcnt lgkmcnt(0)
	v_mfma_f32_32x32x16_bf16 v[112:127], v[184:187], v[152:155], v[112:127]
	ds_read_b128 v[192:195], v211
	ds_read_b128 v[168:171], v209
	v_mfma_f32_32x32x16_bf16 v[96:111], v[188:191], v[152:155], v[96:111]
	ds_read_b128 v[200:203], v211 offset:2048
	ds_read_b128 v[172:175], v209 offset:2048
	v_mfma_f32_32x32x16_bf16 v[80:95], v[184:187], v[156:159], v[80:95]
	ds_read_b128 v[176:179], v209 offset:4096
	ds_read_b128 v[180:183], v209 offset:6144
	v_mfma_f32_32x32x16_bf16 v[64:79], v[188:191], v[156:159], v[64:79]
	s_add_u32 m0, s23, 0x1a000
	s_nop 0
	global_load_lds_dwordx4 v[214:215], off
	v_lshl_add_u64 v[214:215], v[214:215], 0, s[4:5]
	v_mfma_f32_32x32x16_bf16 v[48:63], v[184:187], v[160:163], v[48:63]
	v_mfma_f32_32x32x16_bf16 v[32:47], v[188:191], v[160:163], v[32:47]
	v_mfma_f32_32x32x16_bf16 v[16:31], v[184:187], v[164:167], v[16:31]
	v_mfma_f32_32x32x16_bf16 v[0:15], v[188:191], v[164:167], v[0:15]
	s_add_u32 m0, s23, 0x1e000
	s_nop 0
	global_load_lds_dwordx4 v[218:219], off
	v_lshl_add_u64 v[218:219], v[218:219], 0, s[4:5]
	s_waitcnt lgkmcnt(0)
	s_waitcnt vmcnt(12)
	s_barrier
	s_waitcnt lgkmcnt(0)
	v_mfma_f32_32x32x16_bf16 v[112:127], v[192:195], v[168:171], v[112:127]
	ds_read_b128 v[184:187], v198
	ds_read_b128 v[152:155], v132
	v_mfma_f32_32x32x16_bf16 v[96:111], v[200:203], v[168:171], v[96:111]
	ds_read_b128 v[188:191], v198 offset:2048
	ds_read_b128 v[156:159], v132 offset:2048
	v_mfma_f32_32x32x16_bf16 v[80:95], v[192:195], v[172:175], v[80:95]
	ds_read_b128 v[160:163], v132 offset:4096
	ds_read_b128 v[164:167], v132 offset:6144
	v_mfma_f32_32x32x16_bf16 v[64:79], v[200:203], v[172:175], v[64:79]
	s_add_u32 m0, s23, 0x20000
	s_nop 0
	global_load_lds_dwordx4 v[212:213], off
	v_lshl_add_u64 v[212:213], v[212:213], 0, s[4:5]
	v_mfma_f32_32x32x16_bf16 v[48:63], v[192:195], v[176:179], v[48:63]
	v_mfma_f32_32x32x16_bf16 v[32:47], v[200:203], v[176:179], v[32:47]
	v_mfma_f32_32x32x16_bf16 v[16:31], v[192:195], v[180:183], v[16:31]
	v_mfma_f32_32x32x16_bf16 v[0:15], v[200:203], v[180:183], v[0:15]
	s_add_u32 m0, s23, 0x24000
	s_nop 0
	global_load_lds_dwordx4 v[216:217], off
	v_lshl_add_u64 v[216:217], v[216:217], 0, s[4:5]
	s_sub_u32 s24, s24, 1
	s_cmp_lg_u32 s24, 0
	s_cbranch_scc1 .Lgk_ph13_loop
; #define G_LOADA(kt_) { _Pragma("unroll") for (int i = 0; i < 4; ++i) ra[i] = al(lrow + 64 * i, (kt_) * 64 + lck * 8); }
; #define G_LOADB(kt_) { _Pragma("unroll") for (int i = 0; i < 4; ++i) rb[i] = bl(lrow + 64 * i, (kt_) * 64 + lck * 8); }
; #define G_STOREA(buf_) { bf16_t* nA = sA + (buf_) * 256 * GLD; _Pragma("unroll") for (int i = 0; i < 4; ++i) *(u32x4*)(nA + (lrow + 64 * i) * GLD + lck * 8) = ra[i]; }
; #define G_STOREB(buf_) { bf16_t* nB = sB + (buf_) * 256 * GLD; _Pragma("unroll") for (int i = 0; i < 4; ++i) *(u32x4*)(nB + (lrow + 64 * i) * GLD + lck * 8) = rb[i]; }
; template <class AL, class BL, class EP>
; DI void gemm_tile256(AL al, BL bl, EP ep, int K, char* smem) {
;     ...
;   G_LOADA(0); G_LOADB(0);
;   __syncthreads();
;   G_STOREA(0); G_STOREB(0);
;   if (KT > 1) G_LOADB(1);
;   __syncthreads();
;   for (int kt = 0; kt < KT; kt += 2) {
;     G_STEP(0, kt);
;     if (kt + 1 >= KT) break;
;     G_STEP(1, kt + 1);
;   }
	s_waitcnt lgkmcnt(0)
	v_mfma_f32_32x32x16_bf16 v[112:127], v[184:187], v[152:155], v[112:127]
	ds_read_b128 v[192:195], v199
	ds_read_b128 v[168:171], v151
	v_mfma_f32_32x32x16_bf16 v[96:111], v[188:191], v[152:155], v[96:111]
	ds_read_b128 v[200:203], v199 offset:2048
	ds_read_b128 v[172:175], v151 offset:2048
	v_mfma_f32_32x32x16_bf16 v[80:95], v[184:187], v[156:159], v[80:95]
	ds_read_b128 v[176:179], v151 offset:4096
	ds_read_b128 v[180:183], v151 offset:6144
	v_mfma_f32_32x32x16_bf16 v[64:79], v[188:191], v[156:159], v[64:79]
	s_add_u32 m0, s23, 0x22000
	s_nop 0
	global_load_lds_dwordx4 v[214:215], off
	v_lshl_add_u64 v[214:215], v[214:215], 0, s[4:5]
	v_mfma_f32_32x32x16_bf16 v[48:63], v[184:187], v[160:163], v[48:63]
	v_mfma_f32_32x32x16_bf16 v[32:47], v[188:191], v[160:163], v[32:47]
	v_mfma_f32_32x32x16_bf16 v[16:31], v[184:187], v[164:167], v[16:31]
	v_mfma_f32_32x32x16_bf16 v[0:15], v[188:191], v[164:167], v[0:15]
	s_add_u32 m0, s23, 0x26000
	s_nop 0
	global_load_lds_dwordx4 v[218:219], off
	v_lshl_add_u64 v[218:219], v[218:219], 0, s[4:5]
	s_waitcnt lgkmcnt(0)
	s_waitcnt vmcnt(12)
	s_barrier
	s_waitcnt lgkmcnt(0)
	v_mfma_f32_32x32x16_bf16 v[112:127], v[192:195], v[168:171], v[112:127]
	ds_read_b128 v[184:187], v198 offset:32768
	ds_read_b128 v[152:155], v132 offset:32768
	v_mfma_f32_32x32x16_bf16 v[96:111], v[200:203], v[168:171], v[96:111]
	ds_read_b128 v[188:191], v198 offset:34816
	ds_read_b128 v[156:159], v132 offset:34816
	v_mfma_f32_32x32x16_bf16 v[80:95], v[192:195], v[172:175], v[80:95]
	ds_read_b128 v[160:163], v132 offset:36864
	ds_read_b128 v[164:167], v132 offset:38912
	v_mfma_f32_32x32x16_bf16 v[64:79], v[200:203], v[172:175], v[64:79]
	s_add_u32 m0, s23, 0x0
	s_nop 0
	global_load_lds_dwordx4 v[212:213], off
	v_lshl_add_u64 v[212:213], v[212:213], 0, s[4:5]
	v_mfma_f32_32x32x16_bf16 v[48:63], v[192:195], v[176:179], v[48:63]
	v_mfma_f32_32x32x16_bf16 v[32:47], v[200:203], v[176:179], v[32:47]
	v_mfma_f32_32x32x16_bf16 v[16:31], v[192:195], v[180:183], v[16:31]
	v_mfma_f32_32x32x16_bf16 v[0:15], v[200:203], v[180:183], v[0:15]
	s_add_u32 m0, s23, 0x4000
	s_nop 0
	global_load_lds_dwordx4 v[216:217], off
	v_lshl_add_u64 v[216:217], v[216:217], 0, s[4:5]
	s_waitcnt lgkmcnt(0)
	v_mfma_f32_32x32x16_bf16 v[112:127], v[184:187], v[152:155], v[112:127]
	ds_read_b128 v[192:195], v199 offset:32768
	ds_read_b128 v[168:171], v151 offset:32768
	v_mfma_f32_32x32x16_bf16 v[96:111], v[188:191], v[152:155], v[96:111]
	ds_read_b128 v[200:203], v199 offset:34816
	ds_read_b128 v[172:175], v151 offset:34816
	v_mfma_f32_32x32x16_bf16 v[80:95], v[184:187], v[156:159], v[80:95]
	ds_read_b128 v[176:179], v151 offset:36864
	ds_read_b128 v[180:183], v151 offset:38912
	v_mfma_f32_32x32x16_bf16 v[64:79], v[188:191], v[156:159], v[64:79]
	s_add_u32 m0, s23, 0x2000
	s_nop 0
	global_load_lds_dwordx4 v[214:215], off
	v_lshl_add_u64 v[214:215], v[214:215], 0, s[4:5]
	v_mfma_f32_32x32x16_bf16 v[48:63], v[184:187], v[160:163], v[48:63]
	v_mfma_f32_32x32x16_bf16 v[32:47], v[188:191], v[160:163], v[32:47]
	v_mfma_f32_32x32x16_bf16 v[16:31], v[184:187], v[164:167], v[16:31]
	v_mfma_f32_32x32x16_bf16 v[0:15], v[188:191], v[164:167], v[0:15]
	s_add_u32 m0, s23, 0x6000
	s_nop 0
	global_load_lds_dwordx4 v[218:219], off
	v_lshl_add_u64 v[218:219], v[218:219], 0, s[4:5]
	s_waitcnt lgkmcnt(0)
	s_waitcnt vmcnt(12)
	s_barrier
	s_waitcnt lgkmcnt(0)
	v_mfma_f32_32x32x16_bf16 v[112:127], v[192:195], v[168:171], v[112:127]
	ds_read_b128 v[184:187], v206
	ds_read_b128 v[152:155], v204
	v_mfma_f32_32x32x16_bf16 v[96:111], v[200:203], v[168:171], v[96:111]
	ds_read_b128 v[188:191], v206 offset:2048
	ds_read_b128 v[156:159], v204 offset:2048
	v_mfma_f32_32x32x16_bf16 v[80:95], v[192:195], v[172:175], v[80:95]
	ds_read_b128 v[160:163], v204 offset:4096
	ds_read_b128 v[164:167], v204 offset:6144
	v_mfma_f32_32x32x16_bf16 v[64:79], v[200:203], v[172:175], v[64:79]
	s_add_u32 m0, s23, 0x8000
	s_nop 0
	global_load_lds_dwordx4 v[212:213], off
	v_lshl_add_u64 v[212:213], v[212:213], 0, s[4:5]
	v_mfma_f32_32x32x16_bf16 v[48:63], v[192:195], v[176:179], v[48:63]
	v_mfma_f32_32x32x16_bf16 v[32:47], v[200:203], v[176:179], v[32:47]
	v_mfma_f32_32x32x16_bf16 v[16:31], v[192:195], v[180:183], v[16:31]
	v_mfma_f32_32x32x16_bf16 v[0:15], v[200:203], v[180:183], v[0:15]
	s_add_u32 m0, s23, 0xc000
	s_nop 0
	global_load_lds_dwordx4 v[216:217], off
	v_lshl_add_u64 v[216:217], v[216:217], 0, s[4:5]
	s_waitcnt lgkmcnt(0)
	v_mfma_f32_32x32x16_bf16 v[112:127], v[184:187], v[152:155], v[112:127]
	ds_read_b128 v[192:195], v207
	ds_read_b128 v[168:171], v205
	v_mfma_f32_32x32x16_bf16 v[96:111], v[188:191], v[152:155], v[96:111]
	ds_read_b128 v[200:203], v207 offset:2048
	ds_read_b128 v[172:175], v205 offset:2048
	v_mfma_f32_32x32x16_bf16 v[80:95], v[184:187], v[156:159], v[80:95]
	ds_read_b128 v[176:179], v205 offset:4096
	ds_read_b128 v[180:183], v205 offset:6144
	v_mfma_f32_32x32x16_bf16 v[64:79], v[188:191], v[156:159], v[64:79]
	s_add_u32 m0, s23, 0xa000
	s_nop 0
	global_load_lds_dwordx4 v[214:215], off
	v_lshl_add_u64 v[214:215], v[214:215], 0, s[4:5]
	v_mfma_f32_32x32x16_bf16 v[48:63], v[184:187], v[160:163], v[48:63]
	v_mfma_f32_32x32x16_bf16 v[32:47], v[188:191], v[160:163], v[32:47]
	v_mfma_f32_32x32x16_bf16 v[16:31], v[184:187], v[164:167], v[16:31]
	v_mfma_f32_32x32x16_bf16 v[0:15], v[188:191], v[164:167], v[0:15]
	s_add_u32 m0, s23, 0xe000
	s_nop 0
	global_load_lds_dwordx4 v[218:219], off
	v_lshl_add_u64 v[218:219], v[218:219], 0, s[4:5]
	s_waitcnt lgkmcnt(0)
	s_waitcnt vmcnt(12)
	s_barrier
; #define G_LOADA(kt_) { _Pragma("unroll") for (int i = 0; i < 4; ++i) ra[i] = al(lrow + 64 * i, (kt_) * 64 + lck * 8); }
; #define G_LOADB(kt_) { _Pragma("unroll") for (int i = 0; i < 4; ++i) rb[i] = bl(lrow + 64 * i, (kt_) * 64 + lck * 8); }
; #define G_STOREA(buf_) { bf16_t* nA = sA + (buf_) * 256 * GLD; _Pragma("unroll") for (int i = 0; i < 4; ++i) *(u32x4*)(nA + (lrow + 64 * i) * GLD + lck * 8) = ra[i]; }
; #define G_STOREB(buf_) { bf16_t* nB = sB + (buf_) * 256 * GLD; _Pragma("unroll") for (int i = 0; i < 4; ++i) *(u32x4*)(nB + (lrow + 64 * i) * GLD + lck * 8) = rb[i]; }
; template <class AL, class BL, class EP>
; DI void gemm_tile256(AL al, BL bl, EP ep, int K, char* smem) {
;     ...
;   G_LOADA(0); G_LOADB(0);
;   __syncthreads();
;   G_STOREA(0); G_STOREB(0);
;   if (KT > 1) G_LOADB(1);
;   __syncthreads();
;   for (int kt = 0; kt < KT; kt += 2) {
;     G_STEP(0, kt);
;     if (kt + 1 >= KT) break;
;     G_STEP(1, kt + 1);
;   }
	s_waitcnt lgkmcnt(0)
	v_mfma_f32_32x32x16_bf16 v[112:127], v[192:195], v[168:171], v[112:127]
	ds_read_b128 v[184:187], v206 offset:32768
	ds_read_b128 v[152:155], v204 offset:32768
	v_mfma_f32_32x32x16_bf16 v[96:111], v[200:203], v[168:171], v[96:111]
	ds_read_b128 v[188:191], v206 offset:34816
	ds_read_b128 v[156:159], v204 offset:34816
	v_mfma_f32_32x32x16_bf16 v[80:95], v[192:195], v[172:175], v[80:95]
	ds_read_b128 v[160:163], v204 offset:36864
	ds_read_b128 v[164:167], v204 offset:38912
	v_mfma_f32_32x32x16_bf16 v[64:79], v[200:203], v[172:175], v[64:79]
	v_mfma_f32_32x32x16_bf16 v[48:63], v[192:195], v[176:179], v[48:63]
	v_mfma_f32_32x32x16_bf16 v[32:47], v[200:203], v[176:179], v[32:47]
	v_mfma_f32_32x32x16_bf16 v[16:31], v[192:195], v[180:183], v[16:31]
	v_mfma_f32_32x32x16_bf16 v[0:15], v[200:203], v[180:183], v[0:15]
	s_waitcnt lgkmcnt(0)
	v_mfma_f32_32x32x16_bf16 v[112:127], v[184:187], v[152:155], v[112:127]
	ds_read_b128 v[192:195], v207 offset:32768
	ds_read_b128 v[168:171], v205 offset:32768
	v_mfma_f32_32x32x16_bf16 v[96:111], v[188:191], v[152:155], v[96:111]
	ds_read_b128 v[200:203], v207 offset:34816
	ds_read_b128 v[172:175], v205 offset:34816
	v_mfma_f32_32x32x16_bf16 v[80:95], v[184:187], v[156:159], v[80:95]
	ds_read_b128 v[176:179], v205 offset:36864
	ds_read_b128 v[180:183], v205 offset:38912
	v_mfma_f32_32x32x16_bf16 v[64:79], v[188:191], v[156:159], v[64:79]
	v_mfma_f32_32x32x16_bf16 v[48:63], v[184:187], v[160:163], v[48:63]
	v_mfma_f32_32x32x16_bf16 v[32:47], v[188:191], v[160:163], v[32:47]
	v_mfma_f32_32x32x16_bf16 v[16:31], v[184:187], v[164:167], v[16:31]
	v_mfma_f32_32x32x16_bf16 v[0:15], v[188:191], v[164:167], v[0:15]
	s_waitcnt lgkmcnt(0)
	s_waitcnt vmcnt(8)
	s_barrier
	s_waitcnt lgkmcnt(0)
	v_mfma_f32_32x32x16_bf16 v[112:127], v[192:195], v[168:171], v[112:127]
	ds_read_b128 v[184:187], v210
	ds_read_b128 v[152:155], v208
	v_mfma_f32_32x32x16_bf16 v[96:111], v[200:203], v[168:171], v[96:111]
	ds_read_b128 v[188:191], v210 offset:2048
	ds_read_b128 v[156:159], v208 offset:2048
	v_mfma_f32_32x32x16_bf16 v[80:95], v[192:195], v[172:175], v[80:95]
	ds_read_b128 v[160:163], v208 offset:4096
	ds_read_b128 v[164:167], v208 offset:6144
	v_mfma_f32_32x32x16_bf16 v[64:79], v[200:203], v[172:175], v[64:79]
	v_mfma_f32_32x32x16_bf16 v[48:63], v[192:195], v[176:179], v[48:63]
	v_mfma_f32_32x32x16_bf16 v[32:47], v[200:203], v[176:179], v[32:47]
	v_mfma_f32_32x32x16_bf16 v[16:31], v[192:195], v[180:183], v[16:31]
	v_mfma_f32_32x32x16_bf16 v[0:15], v[200:203], v[180:183], v[0:15]
	s_waitcnt lgkmcnt(0)
	v_mfma_f32_32x32x16_bf16 v[112:127], v[184:187], v[152:155], v[112:127]
	ds_read_b128 v[192:195], v211
	ds_read_b128 v[168:171], v209
	v_mfma_f32_32x32x16_bf16 v[96:111], v[188:191], v[152:155], v[96:111]
	ds_read_b128 v[200:203], v211 offset:2048
	ds_read_b128 v[172:175], v209 offset:2048
	v_mfma_f32_32x32x16_bf16 v[80:95], v[184:187], v[156:159], v[80:95]
	ds_read_b128 v[176:179], v209 offset:4096
	ds_read_b128 v[180:183], v209 offset:6144
	v_mfma_f32_32x32x16_bf16 v[64:79], v[188:191], v[156:159], v[64:79]
	v_mfma_f32_32x32x16_bf16 v[48:63], v[184:187], v[160:163], v[48:63]
	v_mfma_f32_32x32x16_bf16 v[32:47], v[188:191], v[160:163], v[32:47]
	v_mfma_f32_32x32x16_bf16 v[16:31], v[184:187], v[164:167], v[16:31]
	v_mfma_f32_32x32x16_bf16 v[0:15], v[188:191], v[164:167], v[0:15]
	s_waitcnt lgkmcnt(0)
	s_waitcnt vmcnt(4)
	s_barrier
	s_waitcnt lgkmcnt(0)
	v_mfma_f32_32x32x16_bf16 v[112:127], v[192:195], v[168:171], v[112:127]
	ds_read_b128 v[184:187], v198
	ds_read_b128 v[152:155], v132
	v_mfma_f32_32x32x16_bf16 v[96:111], v[200:203], v[168:171], v[96:111]
	ds_read_b128 v[188:191], v198 offset:2048
	ds_read_b128 v[156:159], v132 offset:2048
	v_mfma_f32_32x32x16_bf16 v[80:95], v[192:195], v[172:175], v[80:95]
	ds_read_b128 v[160:163], v132 offset:4096
	ds_read_b128 v[164:167], v132 offset:6144
	v_mfma_f32_32x32x16_bf16 v[64:79], v[200:203], v[172:175], v[64:79]
	v_mfma_f32_32x32x16_bf16 v[48:63], v[192:195], v[176:179], v[48:63]
	v_mfma_f32_32x32x16_bf16 v[32:47], v[200:203], v[176:179], v[32:47]
	v_mfma_f32_32x32x16_bf16 v[16:31], v[192:195], v[180:183], v[16:31]
	v_mfma_f32_32x32x16_bf16 v[0:15], v[200:203], v[180:183], v[0:15]
	s_waitcnt lgkmcnt(0)
	v_mfma_f32_32x32x16_bf16 v[112:127], v[184:187], v[152:155], v[112:127]
	ds_read_b128 v[192:195], v199
	ds_read_b128 v[168:171], v151
	v_mfma_f32_32x32x16_bf16 v[96:111], v[188:191], v[152:155], v[96:111]
	ds_read_b128 v[200:203], v199 offset:2048
	ds_read_b128 v[172:175], v151 offset:2048
	v_mfma_f32_32x32x16_bf16 v[80:95], v[184:187], v[156:159], v[80:95]
	ds_read_b128 v[176:179], v151 offset:4096
	ds_read_b128 v[180:183], v151 offset:6144
	v_mfma_f32_32x32x16_bf16 v[64:79], v[188:191], v[156:159], v[64:79]
	v_mfma_f32_32x32x16_bf16 v[48:63], v[184:187], v[160:163], v[48:63]
	v_mfma_f32_32x32x16_bf16 v[32:47], v[188:191], v[160:163], v[32:47]
	v_mfma_f32_32x32x16_bf16 v[16:31], v[184:187], v[164:167], v[16:31]
	v_mfma_f32_32x32x16_bf16 v[0:15], v[188:191], v[164:167], v[0:15]
	s_waitcnt lgkmcnt(0)
	s_waitcnt vmcnt(0)
	s_barrier
; DI unsigned pack2(float a, float b) { f2_t f = {a, b}; bf2_t r = __builtin_convertvector(f, bf2_t); return __builtin_bit_cast(unsigned, r); }
; template <class AL, class BL, class EP>
; DI void gemm_tile256(AL al, BL bl, EP ep, int K, char* smem) {
;     ...
;   for (int kt = 0; kt < KT; kt += 2) {
;     G_STEP(0, kt);
;     if (kt + 1 >= KT) break;
;     G_STEP(1, kt + 1);
;   }
;     ...
;   if constexpr (EP::kBf16) {
;     bf16_t* sCb = (bf16_t*)smem;
; #pragma unroll
;     for (int i = 0; i < 4; ++i)
; #pragma unroll
;       for (int j = 0; j < 2; ++j)
; #pragma unroll
;         for (int g = 0; g < 4; ++g) {
;           u32x2 v = {pack2(acc[i][j][4 * g], acc[i][j][4 * g + 1]), pack2(acc[i][j][4 * g + 2], acc[i][j][4 * g + 3])};
;           *(u32x2*)(sCb + (128 * wm + 32 * i + r) * BLD + 64 * wn + 32 * j + 8 * g + 4 * h) = v;
;         }
;     __syncthreads();
	s_waitcnt lgkmcnt(0)
	v_mfma_f32_32x32x16_bf16 v[112:127], v[192:195], v[168:171], v[112:127]
	ds_read_b128 v[184:187], v198 offset:32768
	ds_read_b128 v[152:155], v132 offset:32768
	v_mfma_f32_32x32x16_bf16 v[96:111], v[200:203], v[168:171], v[96:111]
	ds_read_b128 v[188:191], v198 offset:34816
	ds_read_b128 v[156:159], v132 offset:34816
	v_mfma_f32_32x32x16_bf16 v[80:95], v[192:195], v[172:175], v[80:95]
	ds_read_b128 v[160:163], v132 offset:36864
	ds_read_b128 v[164:167], v132 offset:38912
	v_mfma_f32_32x32x16_bf16 v[64:79], v[200:203], v[172:175], v[64:79]
	v_mfma_f32_32x32x16_bf16 v[48:63], v[192:195], v[176:179], v[48:63]
	v_mfma_f32_32x32x16_bf16 v[32:47], v[200:203], v[176:179], v[32:47]
	v_mfma_f32_32x32x16_bf16 v[16:31], v[192:195], v[180:183], v[16:31]
	v_mfma_f32_32x32x16_bf16 v[0:15], v[200:203], v[180:183], v[0:15]
	s_waitcnt lgkmcnt(0)
	v_mfma_f32_32x32x16_bf16 v[112:127], v[184:187], v[152:155], v[112:127]
	ds_read_b128 v[192:195], v199 offset:32768
	ds_read_b128 v[168:171], v151 offset:32768
	v_mfma_f32_32x32x16_bf16 v[96:111], v[188:191], v[152:155], v[96:111]
	ds_read_b128 v[200:203], v199 offset:34816
	ds_read_b128 v[172:175], v151 offset:34816
	v_mfma_f32_32x32x16_bf16 v[80:95], v[184:187], v[156:159], v[80:95]
	ds_read_b128 v[176:179], v151 offset:36864
	ds_read_b128 v[180:183], v151 offset:38912
	v_mfma_f32_32x32x16_bf16 v[64:79], v[188:191], v[156:159], v[64:79]
	v_mfma_f32_32x32x16_bf16 v[48:63], v[184:187], v[160:163], v[48:63]
	v_mfma_f32_32x32x16_bf16 v[32:47], v[188:191], v[160:163], v[32:47]
	v_mfma_f32_32x32x16_bf16 v[16:31], v[184:187], v[164:167], v[16:31]
	v_mfma_f32_32x32x16_bf16 v[0:15], v[188:191], v[164:167], v[0:15]
	s_waitcnt lgkmcnt(0)
	s_waitcnt lgkmcnt(0)
	v_mfma_f32_32x32x16_bf16 v[112:127], v[192:195], v[168:171], v[112:127]
	v_mfma_f32_32x32x16_bf16 v[96:111], v[200:203], v[168:171], v[96:111]
	v_mfma_f32_32x32x16_bf16 v[80:95], v[192:195], v[172:175], v[80:95]
	v_mfma_f32_32x32x16_bf16 v[64:79], v[200:203], v[172:175], v[64:79]
	v_mfma_f32_32x32x16_bf16 v[48:63], v[192:195], v[176:179], v[48:63]
	v_mfma_f32_32x32x16_bf16 v[32:47], v[200:203], v[176:179], v[32:47]
	v_mfma_f32_32x32x16_bf16 v[16:31], v[192:195], v[180:183], v[16:31]
	v_mfma_f32_32x32x16_bf16 v[0:15], v[200:203], v[180:183], v[0:15]
	s_nop 15
	s_nop 3
	v_lshl_or_b32 v128, v128, 7, v150
	s_waitcnt lgkmcnt(4)
	v_mad_u64_u32 v[130:131], s[2:3], v133, s17, v[128:129]
	s_waitcnt lgkmcnt(0)
	s_barrier
	s_nop 8
	v_cvt_pk_bf16_f32 v112, v112, v113
	v_cvt_pk_bf16_f32 v113, v114, v115
	v_cvt_pk_bf16_f32 v114, v116, v117
	v_cvt_pk_bf16_f32 v115, v118, v119
	ds_write2_b64 v130, v[112:113], v[114:115] offset1:2
	v_cvt_pk_bf16_f32 v112, v120, v121
	v_cvt_pk_bf16_f32 v113, v122, v123
	v_cvt_pk_bf16_f32 v114, v124, v125
	s_nop 3
	v_cvt_pk_bf16_f32 v16, v16, v17
	v_cvt_pk_bf16_f32 v17, v18, v19
	v_cvt_pk_bf16_f32 v18, v20, v21
	v_add_u32_e32 v20, 0xc000, v130
	v_cvt_pk_bf16_f32 v19, v22, v23
	v_cvt_pk_bf16_f32 v115, v126, v127
	ds_write2_b64 v20, v[16:17], v[18:19] offset0:192 offset1:194
	v_cvt_pk_bf16_f32 v0, v0, v1
	v_cvt_pk_bf16_f32 v1, v2, v3
	v_cvt_pk_bf16_f32 v2, v4, v5
	v_cvt_pk_bf16_f32 v3, v6, v7
	ds_write2_b64 v20, v[0:1], v[2:3] offset0:200 offset1:202
	v_cvt_pk_bf16_f32 v0, v8, v9
	v_cvt_pk_bf16_f32 v1, v10, v11
	s_nop 3
	v_cvt_pk_bf16_f32 v96, v96, v97
	v_cvt_pk_bf16_f32 v97, v98, v99
	v_cvt_pk_bf16_f32 v98, v100, v101
	v_cvt_pk_bf16_f32 v99, v102, v103
	v_cvt_pk_bf16_f32 v2, v12, v13
	v_cvt_pk_bf16_f32 v3, v14, v15
	ds_write2_b64 v130, v[96:97], v[98:99] offset0:8 offset1:10
	v_cvt_pk_bf16_f32 v80, v80, v81
	v_cvt_pk_bf16_f32 v81, v82, v83
	v_cvt_pk_bf16_f32 v82, v84, v85
	v_cvt_pk_bf16_f32 v83, v86, v87
	v_add_u32_e32 v84, 0x4000, v130
	v_cvt_pk_bf16_f32 v96, v104, v105
	v_cvt_pk_bf16_f32 v97, v106, v107
	s_nop 3
	v_cvt_pk_bf16_f32 v64, v64, v65
	v_cvt_pk_bf16_f32 v65, v66, v67
	v_cvt_pk_bf16_f32 v66, v68, v69
	v_cvt_pk_bf16_f32 v67, v70, v71
	v_cvt_pk_bf16_f32 v98, v108, v109
	v_cvt_pk_bf16_f32 v99, v110, v111
	ds_write2_b64 v84, v[80:81], v[82:83] offset0:64 offset1:66
	v_cvt_pk_bf16_f32 v48, v48, v49
	v_cvt_pk_bf16_f32 v49, v50, v51
	v_cvt_pk_bf16_f32 v50, v52, v53
	v_cvt_pk_bf16_f32 v51, v54, v55
	v_add_u32_e32 v52, 0x8000, v130
	v_cvt_pk_bf16_f32 v80, v88, v89
	v_cvt_pk_bf16_f32 v81, v90, v91
	s_nop 4
	v_cvt_pk_bf16_f32 v32, v32, v33
	v_cvt_pk_bf16_f32 v33, v34, v35
	v_cvt_pk_bf16_f32 v34, v36, v37
	v_cvt_pk_bf16_f32 v35, v38, v39
	v_cvt_pk_bf16_f32 v82, v92, v93
	v_cvt_pk_bf16_f32 v83, v94, v95
	ds_write2_b64 v84, v[64:65], v[66:67] offset0:72 offset1:74
	v_cvt_pk_bf16_f32 v64, v72, v73
	v_cvt_pk_bf16_f32 v65, v74, v75
	v_cvt_pk_bf16_f32 v66, v76, v77
	v_cvt_pk_bf16_f32 v67, v78, v79
	ds_write2_b64 v52, v[48:49], v[50:51] offset0:128 offset1:130
	v_cvt_pk_bf16_f32 v48, v56, v57
	v_cvt_pk_bf16_f32 v49, v58, v59
	v_cvt_pk_bf16_f32 v50, v60, v61
	v_cvt_pk_bf16_f32 v51, v62, v63
	ds_write2_b64 v52, v[32:33], v[34:35] offset0:136 offset1:138
	v_cvt_pk_bf16_f32 v32, v40, v41
	v_cvt_pk_bf16_f32 v33, v42, v43
	v_cvt_pk_bf16_f32 v34, v44, v45
	v_cvt_pk_bf16_f32 v35, v46, v47
	v_cvt_pk_bf16_f32 v16, v24, v25
	v_cvt_pk_bf16_f32 v17, v26, v27
	v_cvt_pk_bf16_f32 v18, v28, v29
	v_cvt_pk_bf16_f32 v19, v30, v31
	ds_write2_b64 v20, v[0:1], v[2:3] offset0:204 offset1:206
	v_mov_b32_e32 v2, v196
	ds_write2_b64 v130, v[112:113], v[114:115] offset0:4 offset1:6
	ds_write2_b64 v130, v[96:97], v[98:99] offset0:12 offset1:14
	ds_write2_b64 v84, v[80:81], v[82:83] offset0:68 offset1:70
	ds_write2_b64 v84, v[64:65], v[66:67] offset0:76 offset1:78
	ds_write2_b64 v52, v[48:49], v[50:51] offset0:132 offset1:134
	ds_write2_b64 v52, v[32:33], v[34:35] offset0:140 offset1:142
	ds_write2_b64 v20, v[16:17], v[18:19] offset0:196 offset1:198
	s_waitcnt lgkmcnt(0)
	s_barrier
; DI int tid512() { int t = threadIdx_x_raw(); asm volatile("" : "+v"(t)); return t; }
;   DI void operator()(const bf16_t* sCb) const {
;     for (int id = tid512(); id < 8192; id += 512) {
;       int row = id >> 5, c8 = (id & 31) * 8, n = n0 + c8;
;       if (n < N) *(u32x4*)(dst + (size_t)(m0 + row) * ld + n) = *(const u32x4*)(sCb + row * BLD + c8);
;     }
	s_nop 0
	v_cmp_gt_i32_e32 vcc, s18, v2
	s_and_saveexec_b64 s[2:3], vcc
	s_cbranch_execz .LBB0_1046
	v_lshlrev_b32_e32 v3, 3, v2
	v_and_b32_e32 v1, 0xf8, v3
	v_or_b32_e32 v0, s21, v1
	v_cmp_gt_i32_e32 vcc, s19, v0
	s_and_saveexec_b64 s[6:7], vcc
	s_cbranch_execz .Lep_done_1046
; DI int tid512() { int t = threadIdx_x_raw(); asm volatile("" : "+v"(t)); return t; }
;   DI void operator()(const bf16_t* sCb) const {
;     for (int id = tid512(); id < 8192; id += 512) {
;       int row = id >> 5, c8 = (id & 31) * 8, n = n0 + c8;
;       if (n < N) *(u32x4*)(dst + (size_t)(m0 + row) * ld + n) = *(const u32x4*)(sCb + row * BLD + c8);
;     }
	v_ashrrev_i32_e32 v8, 5, v2
	v_mul_lo_u32 v4, v8, s17
	v_lshl_add_u32 v1, v1, 1, v4
	v_add_u32_e32 v10, 0x10800, v1
	ds_read_b128 v[64:67], v1
	ds_read_b128 v[68:71], v1 offset:8448
	ds_read_b128 v[72:75], v1 offset:16896
	ds_read_b128 v[76:79], v1 offset:25344
	ds_read_b128 v[80:83], v1 offset:33792
	ds_read_b128 v[84:87], v1 offset:42240
	ds_read_b128 v[88:91], v1 offset:50688
	ds_read_b128 v[92:95], v1 offset:59136
	ds_read_b128 v[96:99], v10
	ds_read_b128 v[100:103], v10 offset:8448
	ds_read_b128 v[104:107], v10 offset:16896
	ds_read_b128 v[108:111], v10 offset:25344
	ds_read_b128 v[112:115], v10 offset:33792
	ds_read_b128 v[116:119], v10 offset:42240
	ds_read_b128 v[120:123], v10 offset:50688
	ds_read_b128 v[124:127], v10 offset:59136
	v_and_b32_e32 v1, 0xf8, v3
	v_or_b32_e32 v0, s21, v1
	v_ashrrev_i32_e32 v8, 5, v2
	v_add_u32_e32 v8, s22, v8
	v_ashrrev_i32_e32 v9, 31, v8
	v_lshlrev_b64 v[8:9], 11, v[8:9]
	v_lshl_add_u64 v[8:9], s[8:9], 0, v[8:9]
	v_ashrrev_i32_e32 v1, 31, v0
	v_lshl_add_u64 v[0:1], v[0:1], 1, v[8:9]
	s_waitcnt lgkmcnt(15)
	global_store_dwordx4 v[0:1], v[64:67], off
	v_add_u32_e32 v2, 0x200, v2
	v_and_b32_e32 v1, 0xf8, v3
	v_or_b32_e32 v0, s21, v1
	v_ashrrev_i32_e32 v8, 5, v2
	v_add_u32_e32 v8, s22, v8
	v_ashrrev_i32_e32 v9, 31, v8
	v_lshlrev_b64 v[8:9], 11, v[8:9]
	v_lshl_add_u64 v[8:9], s[8:9], 0, v[8:9]
	v_ashrrev_i32_e32 v1, 31, v0
	v_lshl_add_u64 v[0:1], v[0:1], 1, v[8:9]
	s_waitcnt lgkmcnt(14)
	global_store_dwordx4 v[0:1], v[68:71], off
	v_add_u32_e32 v2, 0x200, v2
	v_and_b32_e32 v1, 0xf8, v3
	v_or_b32_e32 v0, s21, v1
	v_ashrrev_i32_e32 v8, 5, v2
	v_add_u32_e32 v8, s22, v8
	v_ashrrev_i32_e32 v9, 31, v8
	v_lshlrev_b64 v[8:9], 11, v[8:9]
	v_lshl_add_u64 v[8:9], s[8:9], 0, v[8:9]
	v_ashrrev_i32_e32 v1, 31, v0
	v_lshl_add_u64 v[0:1], v[0:1], 1, v[8:9]
	s_waitcnt lgkmcnt(13)
	global_store_dwordx4 v[0:1], v[72:75], off
	v_add_u32_e32 v2, 0x200, v2
	v_and_b32_e32 v1, 0xf8, v3
	v_or_b32_e32 v0, s21, v1
	v_ashrrev_i32_e32 v8, 5, v2
	v_add_u32_e32 v8, s22, v8
	v_ashrrev_i32_e32 v9, 31, v8
	v_lshlrev_b64 v[8:9], 11, v[8:9]
	v_lshl_add_u64 v[8:9], s[8:9], 0, v[8:9]
	v_ashrrev_i32_e32 v1, 31, v0
	v_lshl_add_u64 v[0:1], v[0:1], 1, v[8:9]
	s_waitcnt lgkmcnt(12)
	global_store_dwordx4 v[0:1], v[76:79], off
	v_add_u32_e32 v2, 0x200, v2
	v_and_b32_e32 v1, 0xf8, v3
	v_or_b32_e32 v0, s21, v1
	v_ashrrev_i32_e32 v8, 5, v2
	v_add_u32_e32 v8, s22, v8
	v_ashrrev_i32_e32 v9, 31, v8
	v_lshlrev_b64 v[8:9], 11, v[8:9]
	v_lshl_add_u64 v[8:9], s[8:9], 0, v[8:9]
	v_ashrrev_i32_e32 v1, 31, v0
	v_lshl_add_u64 v[0:1], v[0:1], 1, v[8:9]
	s_waitcnt lgkmcnt(11)
	global_store_dwordx4 v[0:1], v[80:83], off
	v_add_u32_e32 v2, 0x200, v2
	v_and_b32_e32 v1, 0xf8, v3
	v_or_b32_e32 v0, s21, v1
	v_ashrrev_i32_e32 v8, 5, v2
	v_add_u32_e32 v8, s22, v8
	v_ashrrev_i32_e32 v9, 31, v8
	v_lshlrev_b64 v[8:9], 11, v[8:9]
	v_lshl_add_u64 v[8:9], s[8:9], 0, v[8:9]
	v_ashrrev_i32_e32 v1, 31, v0
	v_lshl_add_u64 v[0:1], v[0:1], 1, v[8:9]
	s_waitcnt lgkmcnt(10)
	global_store_dwordx4 v[0:1], v[84:87], off
	v_add_u32_e32 v2, 0x200, v2
	v_and_b32_e32 v1, 0xf8, v3
	v_or_b32_e32 v0, s21, v1
	v_ashrrev_i32_e32 v8, 5, v2
	v_add_u32_e32 v8, s22, v8
	v_ashrrev_i32_e32 v9, 31, v8
	v_lshlrev_b64 v[8:9], 11, v[8:9]
	v_lshl_add_u64 v[8:9], s[8:9], 0, v[8:9]
	v_ashrrev_i32_e32 v1, 31, v0
	v_lshl_add_u64 v[0:1], v[0:1], 1, v[8:9]
	s_waitcnt lgkmcnt(9)
	global_store_dwordx4 v[0:1], v[88:91], off
	v_add_u32_e32 v2, 0x200, v2
	v_and_b32_e32 v1, 0xf8, v3
	v_or_b32_e32 v0, s21, v1
	v_ashrrev_i32_e32 v8, 5, v2
	v_add_u32_e32 v8, s22, v8
	v_ashrrev_i32_e32 v9, 31, v8
	v_lshlrev_b64 v[8:9], 11, v[8:9]
	v_lshl_add_u64 v[8:9], s[8:9], 0, v[8:9]
	v_ashrrev_i32_e32 v1, 31, v0
	v_lshl_add_u64 v[0:1], v[0:1], 1, v[8:9]
	s_waitcnt lgkmcnt(8)
	global_store_dwordx4 v[0:1], v[92:95], off
	v_add_u32_e32 v2, 0x200, v2
	v_and_b32_e32 v1, 0xf8, v3
	v_or_b32_e32 v0, s21, v1
	v_ashrrev_i32_e32 v8, 5, v2
	v_add_u32_e32 v8, s22, v8
	v_ashrrev_i32_e32 v9, 31, v8
	v_lshlrev_b64 v[8:9], 11, v[8:9]
	v_lshl_add_u64 v[8:9], s[8:9], 0, v[8:9]
	v_ashrrev_i32_e32 v1, 31, v0
	v_lshl_add_u64 v[0:1], v[0:1], 1, v[8:9]
	s_waitcnt lgkmcnt(7)
	global_store_dwordx4 v[0:1], v[96:99], off
	v_add_u32_e32 v2, 0x200, v2
	v_and_b32_e32 v1, 0xf8, v3
	v_or_b32_e32 v0, s21, v1
	v_ashrrev_i32_e32 v8, 5, v2
	v_add_u32_e32 v8, s22, v8
	v_ashrrev_i32_e32 v9, 31, v8
	v_lshlrev_b64 v[8:9], 11, v[8:9]
	v_lshl_add_u64 v[8:9], s[8:9], 0, v[8:9]
	v_ashrrev_i32_e32 v1, 31, v0
	v_lshl_add_u64 v[0:1], v[0:1], 1, v[8:9]
	s_waitcnt lgkmcnt(6)
	global_store_dwordx4 v[0:1], v[100:103], off
	v_add_u32_e32 v2, 0x200, v2
	v_and_b32_e32 v1, 0xf8, v3
	v_or_b32_e32 v0, s21, v1
	v_ashrrev_i32_e32 v8, 5, v2
	v_add_u32_e32 v8, s22, v8
	v_ashrrev_i32_e32 v9, 31, v8
	v_lshlrev_b64 v[8:9], 11, v[8:9]
	v_lshl_add_u64 v[8:9], s[8:9], 0, v[8:9]
	v_ashrrev_i32_e32 v1, 31, v0
	v_lshl_add_u64 v[0:1], v[0:1], 1, v[8:9]
	s_waitcnt lgkmcnt(5)
	global_store_dwordx4 v[0:1], v[104:107], off
	v_add_u32_e32 v2, 0x200, v2
	v_and_b32_e32 v1, 0xf8, v3
	v_or_b32_e32 v0, s21, v1
	v_ashrrev_i32_e32 v8, 5, v2
	v_add_u32_e32 v8, s22, v8
	v_ashrrev_i32_e32 v9, 31, v8
	v_lshlrev_b64 v[8:9], 11, v[8:9]
	v_lshl_add_u64 v[8:9], s[8:9], 0, v[8:9]
	v_ashrrev_i32_e32 v1, 31, v0
	v_lshl_add_u64 v[0:1], v[0:1], 1, v[8:9]
	s_waitcnt lgkmcnt(4)
	global_store_dwordx4 v[0:1], v[108:111], off
	v_add_u32_e32 v2, 0x200, v2
	v_and_b32_e32 v1, 0xf8, v3
	v_or_b32_e32 v0, s21, v1
	v_ashrrev_i32_e32 v8, 5, v2
	v_add_u32_e32 v8, s22, v8
	v_ashrrev_i32_e32 v9, 31, v8
	v_lshlrev_b64 v[8:9], 11, v[8:9]
	v_lshl_add_u64 v[8:9], s[8:9], 0, v[8:9]
	v_ashrrev_i32_e32 v1, 31, v0
	v_lshl_add_u64 v[0:1], v[0:1], 1, v[8:9]
	s_waitcnt lgkmcnt(3)
	global_store_dwordx4 v[0:1], v[112:115], off
	v_add_u32_e32 v2, 0x200, v2
	v_and_b32_e32 v1, 0xf8, v3
	v_or_b32_e32 v0, s21, v1
	v_ashrrev_i32_e32 v8, 5, v2
	v_add_u32_e32 v8, s22, v8
	v_ashrrev_i32_e32 v9, 31, v8
	v_lshlrev_b64 v[8:9], 11, v[8:9]
	v_lshl_add_u64 v[8:9], s[8:9], 0, v[8:9]
	v_ashrrev_i32_e32 v1, 31, v0
	v_lshl_add_u64 v[0:1], v[0:1], 1, v[8:9]
	s_waitcnt lgkmcnt(2)
	global_store_dwordx4 v[0:1], v[116:119], off
	v_add_u32_e32 v2, 0x200, v2
	v_and_b32_e32 v1, 0xf8, v3
	v_or_b32_e32 v0, s21, v1
	v_ashrrev_i32_e32 v8, 5, v2
	v_add_u32_e32 v8, s22, v8
	v_ashrrev_i32_e32 v9, 31, v8
	v_lshlrev_b64 v[8:9], 11, v[8:9]
	v_lshl_add_u64 v[8:9], s[8:9], 0, v[8:9]
	v_ashrrev_i32_e32 v1, 31, v0
	v_lshl_add_u64 v[0:1], v[0:1], 1, v[8:9]
	s_waitcnt lgkmcnt(1)
	global_store_dwordx4 v[0:1], v[120:123], off
	v_add_u32_e32 v2, 0x200, v2
	v_and_b32_e32 v1, 0xf8, v3
	v_or_b32_e32 v0, s21, v1
	v_ashrrev_i32_e32 v8, 5, v2
	v_add_u32_e32 v8, s22, v8
	v_ashrrev_i32_e32 v9, 31, v8
	v_lshlrev_b64 v[8:9], 11, v[8:9]
	v_lshl_add_u64 v[8:9], s[8:9], 0, v[8:9]
	v_ashrrev_i32_e32 v1, 31, v0
	v_lshl_add_u64 v[0:1], v[0:1], 1, v[8:9]
	s_waitcnt lgkmcnt(0)
	global_store_dwordx4 v[0:1], v[124:127], off

; DI unsigned pack2(float a, float b) { f2_t f = {a, b}; bf2_t r = __builtin_convertvector(f, bf2_t); return __builtin_bit_cast(unsigned, r); }
; DI int tid512() { int t = threadIdx_x_raw(); asm volatile("" : "+v"(t)); return t; }
; template <class AL, class BL, class EP>
; DI void gemm_tile256(AL al, BL bl, EP ep, int K, char* smem) {
;     ...
;   if constexpr (EP::kBf16) {
;     bf16_t* sCb = (bf16_t*)smem;
; #pragma unroll
;     for (int i = 0; i < 4; ++i)
; #pragma unroll
;       for (int j = 0; j < 2; ++j)
; #pragma unroll
;         for (int g = 0; g < 4; ++g) {
;           u32x2 v = {pack2(acc[i][j][4 * g], acc[i][j][4 * g + 1]), pack2(acc[i][j][4 * g + 2], acc[i][j][4 * g + 3])};
;           *(u32x2*)(sCb + (128 * wm + 32 * i + r) * BLD + 64 * wn + 32 * j + 8 * g + 4 * h) = v;
;         }
;     __syncthreads();
;   DI void operator()(const bf16_t* sCb) const {
;     for (int id = tid512(); id < 8192; id += 512) {
;       int row = id >> 5, c8 = (id & 31) * 8, n = n0 + c8;
;       if (n < N) *(u32x4*)(dst + (size_t)(m0 + row) * ld + n) = *(const u32x4*)(sCb + row * BLD + c8);
;     }
.LBB0_1268:
	v_lshl_or_b32 v128, v198, 7, v200
	v_mad_u64_u32 v[128:129], s[0:1], v199, s17, v[128:129]
	s_nop 7
	v_cvt_pk_bf16_f32 v16, v16, v17
	v_cvt_pk_bf16_f32 v17, v18, v19
	v_cvt_pk_bf16_f32 v18, v20, v21
	v_add_u32_e32 v20, 0xc000, v128
	v_cvt_pk_bf16_f32 v0, v0, v1
	v_cvt_pk_bf16_f32 v1, v2, v3
	v_cvt_pk_bf16_f32 v2, v4, v5
	v_cvt_pk_bf16_f32 v3, v6, v7
	v_cvt_pk_bf16_f32 v112, v112, v113
	v_cvt_pk_bf16_f32 v113, v114, v115
	v_cvt_pk_bf16_f32 v114, v116, v117
	v_cvt_pk_bf16_f32 v115, v118, v119
	v_cvt_pk_bf16_f32 v96, v96, v97
	v_cvt_pk_bf16_f32 v97, v98, v99
	v_cvt_pk_bf16_f32 v98, v100, v101
	v_cvt_pk_bf16_f32 v99, v102, v103
	v_cvt_pk_bf16_f32 v80, v80, v81
	v_cvt_pk_bf16_f32 v81, v82, v83
	v_cvt_pk_bf16_f32 v82, v84, v85
	v_cvt_pk_bf16_f32 v83, v86, v87
	v_add_u32_e32 v84, 0x4000, v128
	v_cvt_pk_bf16_f32 v64, v64, v65
	v_cvt_pk_bf16_f32 v65, v66, v67
	v_cvt_pk_bf16_f32 v66, v68, v69
	v_cvt_pk_bf16_f32 v67, v70, v71
	v_cvt_pk_bf16_f32 v48, v48, v49
	v_cvt_pk_bf16_f32 v49, v50, v51
	v_cvt_pk_bf16_f32 v50, v52, v53
	v_cvt_pk_bf16_f32 v51, v54, v55
	v_add_u32_e32 v52, 0x8000, v128
	v_cvt_pk_bf16_f32 v32, v32, v33
	v_cvt_pk_bf16_f32 v33, v34, v35
	v_cvt_pk_bf16_f32 v34, v36, v37
	v_cvt_pk_bf16_f32 v35, v38, v39
	v_cvt_pk_bf16_f32 v19, v22, v23
	ds_write2_b64 v20, v[0:1], v[2:3] offset0:200 offset1:202
	v_cvt_pk_bf16_f32 v0, v8, v9
	v_cvt_pk_bf16_f32 v1, v10, v11
	v_cvt_pk_bf16_f32 v2, v12, v13
	v_cvt_pk_bf16_f32 v3, v14, v15
	ds_write2_b64 v128, v[112:113], v[114:115] offset1:2
	v_cvt_pk_bf16_f32 v112, v120, v121
	v_cvt_pk_bf16_f32 v113, v122, v123
	v_cvt_pk_bf16_f32 v114, v124, v125
	v_cvt_pk_bf16_f32 v115, v126, v127
	ds_write2_b64 v128, v[96:97], v[98:99] offset0:8 offset1:10
	v_cvt_pk_bf16_f32 v96, v104, v105
	v_cvt_pk_bf16_f32 v97, v106, v107
	v_cvt_pk_bf16_f32 v98, v108, v109
	v_cvt_pk_bf16_f32 v99, v110, v111
	ds_write2_b64 v84, v[80:81], v[82:83] offset0:64 offset1:66
	v_cvt_pk_bf16_f32 v80, v88, v89
	v_cvt_pk_bf16_f32 v81, v90, v91
	v_cvt_pk_bf16_f32 v82, v92, v93
	v_cvt_pk_bf16_f32 v83, v94, v95
	ds_write2_b64 v84, v[64:65], v[66:67] offset0:72 offset1:74
	v_cvt_pk_bf16_f32 v64, v72, v73
	v_cvt_pk_bf16_f32 v65, v74, v75
	v_cvt_pk_bf16_f32 v66, v76, v77
	v_cvt_pk_bf16_f32 v67, v78, v79
	ds_write2_b64 v52, v[48:49], v[50:51] offset0:128 offset1:130
	v_cvt_pk_bf16_f32 v48, v56, v57
	v_cvt_pk_bf16_f32 v49, v58, v59
	v_cvt_pk_bf16_f32 v50, v60, v61
	v_cvt_pk_bf16_f32 v51, v62, v63
	ds_write2_b64 v52, v[32:33], v[34:35] offset0:136 offset1:138
	v_cvt_pk_bf16_f32 v32, v40, v41
	v_cvt_pk_bf16_f32 v33, v42, v43
	v_cvt_pk_bf16_f32 v34, v44, v45
	v_cvt_pk_bf16_f32 v35, v46, v47
	ds_write2_b64 v20, v[16:17], v[18:19] offset0:192 offset1:194
	v_cvt_pk_bf16_f32 v16, v24, v25
	v_cvt_pk_bf16_f32 v17, v26, v27
	v_cvt_pk_bf16_f32 v18, v28, v29
	v_cvt_pk_bf16_f32 v19, v30, v31
	ds_write2_b64 v20, v[0:1], v[2:3] offset0:204 offset1:206
	v_mov_b32_e32 v2, v196
	ds_write2_b64 v128, v[112:113], v[114:115] offset0:4 offset1:6
	ds_write2_b64 v128, v[96:97], v[98:99] offset0:12 offset1:14
	ds_write2_b64 v84, v[80:81], v[82:83] offset0:68 offset1:70
	ds_write2_b64 v84, v[64:65], v[66:67] offset0:76 offset1:78
	ds_write2_b64 v52, v[48:49], v[50:51] offset0:132 offset1:134
	ds_write2_b64 v52, v[32:33], v[34:35] offset0:140 offset1:142
	ds_write2_b64 v20, v[16:17], v[18:19] offset0:196 offset1:198
	s_waitcnt lgkmcnt(0)
	s_barrier
	s_nop 0
	v_cmp_gt_i32_e32 vcc, s18, v2
	s_and_saveexec_b64 s[0:1], vcc
	s_cbranch_execz .LBB0_1273
	v_lshlrev_b32_e32 v3, 3, v2
	v_and_b32_e32 v1, 0xf8, v3
	v_or_b32_e32 v0, s21, v1
	v_cmp_gt_i32_e32 vcc, s19, v0
	s_and_saveexec_b64 s[10:11], vcc
	s_cbranch_execz .Lep_done_1273
; DI int tid512() { int t = threadIdx_x_raw(); asm volatile("" : "+v"(t)); return t; }
;   DI void operator()(const bf16_t* sCb) const {
;     for (int id = tid512(); id < 8192; id += 512) {
;       int row = id >> 5, c8 = (id & 31) * 8, n = n0 + c8;
;       if (n < N) *(u32x4*)(dst + (size_t)(m0 + row) * ld + n) = *(const u32x4*)(sCb + row * BLD + c8);
;     }
	v_ashrrev_i32_e32 v8, 5, v2
	v_mul_lo_u32 v4, v8, s17
	v_lshl_add_u32 v1, v1, 1, v4
	v_add_u32_e32 v10, 0x10800, v1
	ds_read_b128 v[64:67], v1
	ds_read_b128 v[68:71], v1 offset:8448
	ds_read_b128 v[72:75], v1 offset:16896
	ds_read_b128 v[76:79], v1 offset:25344
	ds_read_b128 v[80:83], v1 offset:33792
	ds_read_b128 v[84:87], v1 offset:42240
	ds_read_b128 v[88:91], v1 offset:50688
	ds_read_b128 v[92:95], v1 offset:59136
	ds_read_b128 v[96:99], v10
	ds_read_b128 v[100:103], v10 offset:8448
	ds_read_b128 v[104:107], v10 offset:16896
	ds_read_b128 v[108:111], v10 offset:25344
	ds_read_b128 v[112:115], v10 offset:33792
	ds_read_b128 v[116:119], v10 offset:42240
	ds_read_b128 v[120:123], v10 offset:50688
	ds_read_b128 v[124:127], v10 offset:59136
	v_and_b32_e32 v1, 0xf8, v3
	v_or_b32_e32 v0, s21, v1
	v_ashrrev_i32_e32 v8, 5, v2
	v_add_u32_e32 v8, s22, v8
	v_ashrrev_i32_e32 v9, 31, v8
	v_lshlrev_b64 v[8:9], 11, v[8:9]
	v_lshl_add_u64 v[8:9], s[8:9], 0, v[8:9]
	v_ashrrev_i32_e32 v1, 31, v0
	v_lshl_add_u64 v[0:1], v[0:1], 1, v[8:9]
	s_waitcnt lgkmcnt(15)
	global_store_dwordx4 v[0:1], v[64:67], off
	v_add_u32_e32 v2, 0x200, v2
	v_and_b32_e32 v1, 0xf8, v3
	v_or_b32_e32 v0, s21, v1
	v_ashrrev_i32_e32 v8, 5, v2
	v_add_u32_e32 v8, s22, v8
	v_ashrrev_i32_e32 v9, 31, v8
	v_lshlrev_b64 v[8:9], 11, v[8:9]
	v_lshl_add_u64 v[8:9], s[8:9], 0, v[8:9]
	v_ashrrev_i32_e32 v1, 31, v0
	v_lshl_add_u64 v[0:1], v[0:1], 1, v[8:9]
	s_waitcnt lgkmcnt(14)
	global_store_dwordx4 v[0:1], v[68:71], off
	v_add_u32_e32 v2, 0x200, v2
	v_and_b32_e32 v1, 0xf8, v3
	v_or_b32_e32 v0, s21, v1
	v_ashrrev_i32_e32 v8, 5, v2
	v_add_u32_e32 v8, s22, v8
	v_ashrrev_i32_e32 v9, 31, v8
	v_lshlrev_b64 v[8:9], 11, v[8:9]
	v_lshl_add_u64 v[8:9], s[8:9], 0, v[8:9]
	v_ashrrev_i32_e32 v1, 31, v0
	v_lshl_add_u64 v[0:1], v[0:1], 1, v[8:9]
	s_waitcnt lgkmcnt(13)
	global_store_dwordx4 v[0:1], v[72:75], off
	v_add_u32_e32 v2, 0x200, v2
	v_and_b32_e32 v1, 0xf8, v3
	v_or_b32_e32 v0, s21, v1
	v_ashrrev_i32_e32 v8, 5, v2
	v_add_u32_e32 v8, s22, v8
	v_ashrrev_i32_e32 v9, 31, v8
	v_lshlrev_b64 v[8:9], 11, v[8:9]
	v_lshl_add_u64 v[8:9], s[8:9], 0, v[8:9]
	v_ashrrev_i32_e32 v1, 31, v0
	v_lshl_add_u64 v[0:1], v[0:1], 1, v[8:9]
	s_waitcnt lgkmcnt(12)
	global_store_dwordx4 v[0:1], v[76:79], off
	v_add_u32_e32 v2, 0x200, v2
	v_and_b32_e32 v1, 0xf8, v3
	v_or_b32_e32 v0, s21, v1
	v_ashrrev_i32_e32 v8, 5, v2
	v_add_u32_e32 v8, s22, v8
	v_ashrrev_i32_e32 v9, 31, v8
	v_lshlrev_b64 v[8:9], 11, v[8:9]
	v_lshl_add_u64 v[8:9], s[8:9], 0, v[8:9]
	v_ashrrev_i32_e32 v1, 31, v0
	v_lshl_add_u64 v[0:1], v[0:1], 1, v[8:9]
	s_waitcnt lgkmcnt(11)
	global_store_dwordx4 v[0:1], v[80:83], off
	v_add_u32_e32 v2, 0x200, v2
	v_and_b32_e32 v1, 0xf8, v3
	v_or_b32_e32 v0, s21, v1
	v_ashrrev_i32_e32 v8, 5, v2
	v_add_u32_e32 v8, s22, v8
	v_ashrrev_i32_e32 v9, 31, v8
	v_lshlrev_b64 v[8:9], 11, v[8:9]
	v_lshl_add_u64 v[8:9], s[8:9], 0, v[8:9]
	v_ashrrev_i32_e32 v1, 31, v0
	v_lshl_add_u64 v[0:1], v[0:1], 1, v[8:9]
	s_waitcnt lgkmcnt(10)
	global_store_dwordx4 v[0:1], v[84:87], off
	v_add_u32_e32 v2, 0x200, v2
	v_and_b32_e32 v1, 0xf8, v3
	v_or_b32_e32 v0, s21, v1
	v_ashrrev_i32_e32 v8, 5, v2
	v_add_u32_e32 v8, s22, v8
	v_ashrrev_i32_e32 v9, 31, v8
	v_lshlrev_b64 v[8:9], 11, v[8:9]
	v_lshl_add_u64 v[8:9], s[8:9], 0, v[8:9]
	v_ashrrev_i32_e32 v1, 31, v0
	v_lshl_add_u64 v[0:1], v[0:1], 1, v[8:9]
	s_waitcnt lgkmcnt(9)
	global_store_dwordx4 v[0:1], v[88:91], off
	v_add_u32_e32 v2, 0x200, v2
	v_and_b32_e32 v1, 0xf8, v3
	v_or_b32_e32 v0, s21, v1
	v_ashrrev_i32_e32 v8, 5, v2
	v_add_u32_e32 v8, s22, v8
	v_ashrrev_i32_e32 v9, 31, v8
	v_lshlrev_b64 v[8:9], 11, v[8:9]
	v_lshl_add_u64 v[8:9], s[8:9], 0, v[8:9]
	v_ashrrev_i32_e32 v1, 31, v0
	v_lshl_add_u64 v[0:1], v[0:1], 1, v[8:9]
	s_waitcnt lgkmcnt(8)
	global_store_dwordx4 v[0:1], v[92:95], off
	v_add_u32_e32 v2, 0x200, v2
	v_and_b32_e32 v1, 0xf8, v3
	v_or_b32_e32 v0, s21, v1
	v_ashrrev_i32_e32 v8, 5, v2
	v_add_u32_e32 v8, s22, v8
	v_ashrrev_i32_e32 v9, 31, v8
	v_lshlrev_b64 v[8:9], 11, v[8:9]
	v_lshl_add_u64 v[8:9], s[8:9], 0, v[8:9]
	v_ashrrev_i32_e32 v1, 31, v0
	v_lshl_add_u64 v[0:1], v[0:1], 1, v[8:9]
	s_waitcnt lgkmcnt(7)
	global_store_dwordx4 v[0:1], v[96:99], off
	v_add_u32_e32 v2, 0x200, v2
	v_and_b32_e32 v1, 0xf8, v3
	v_or_b32_e32 v0, s21, v1
	v_ashrrev_i32_e32 v8, 5, v2
	v_add_u32_e32 v8, s22, v8
	v_ashrrev_i32_e32 v9, 31, v8
	v_lshlrev_b64 v[8:9], 11, v[8:9]
	v_lshl_add_u64 v[8:9], s[8:9], 0, v[8:9]
	v_ashrrev_i32_e32 v1, 31, v0
	v_lshl_add_u64 v[0:1], v[0:1], 1, v[8:9]
	s_waitcnt lgkmcnt(6)
	global_store_dwordx4 v[0:1], v[100:103], off
	v_add_u32_e32 v2, 0x200, v2
	v_and_b32_e32 v1, 0xf8, v3
	v_or_b32_e32 v0, s21, v1
	v_ashrrev_i32_e32 v8, 5, v2
	v_add_u32_e32 v8, s22, v8
	v_ashrrev_i32_e32 v9, 31, v8
	v_lshlrev_b64 v[8:9], 11, v[8:9]
	v_lshl_add_u64 v[8:9], s[8:9], 0, v[8:9]
	v_ashrrev_i32_e32 v1, 31, v0
	v_lshl_add_u64 v[0:1], v[0:1], 1, v[8:9]
	s_waitcnt lgkmcnt(5)
	global_store_dwordx4 v[0:1], v[104:107], off
	v_add_u32_e32 v2, 0x200, v2
	v_and_b32_e32 v1, 0xf8, v3
	v_or_b32_e32 v0, s21, v1
	v_ashrrev_i32_e32 v8, 5, v2
	v_add_u32_e32 v8, s22, v8
	v_ashrrev_i32_e32 v9, 31, v8
	v_lshlrev_b64 v[8:9], 11, v[8:9]
	v_lshl_add_u64 v[8:9], s[8:9], 0, v[8:9]
	v_ashrrev_i32_e32 v1, 31, v0
	v_lshl_add_u64 v[0:1], v[0:1], 1, v[8:9]
	s_waitcnt lgkmcnt(4)
	global_store_dwordx4 v[0:1], v[108:111], off
	v_add_u32_e32 v2, 0x200, v2
	v_and_b32_e32 v1, 0xf8, v3
	v_or_b32_e32 v0, s21, v1
	v_ashrrev_i32_e32 v8, 5, v2
	v_add_u32_e32 v8, s22, v8
	v_ashrrev_i32_e32 v9, 31, v8
	v_lshlrev_b64 v[8:9], 11, v[8:9]
	v_lshl_add_u64 v[8:9], s[8:9], 0, v[8:9]
	v_ashrrev_i32_e32 v1, 31, v0
	v_lshl_add_u64 v[0:1], v[0:1], 1, v[8:9]
	s_waitcnt lgkmcnt(3)
	global_store_dwordx4 v[0:1], v[112:115], off
	v_add_u32_e32 v2, 0x200, v2
	v_and_b32_e32 v1, 0xf8, v3
	v_or_b32_e32 v0, s21, v1
	v_ashrrev_i32_e32 v8, 5, v2
	v_add_u32_e32 v8, s22, v8
	v_ashrrev_i32_e32 v9, 31, v8
	v_lshlrev_b64 v[8:9], 11, v[8:9]
	v_lshl_add_u64 v[8:9], s[8:9], 0, v[8:9]
	v_ashrrev_i32_e32 v1, 31, v0
	v_lshl_add_u64 v[0:1], v[0:1], 1, v[8:9]
	s_waitcnt lgkmcnt(2)
	global_store_dwordx4 v[0:1], v[116:119], off
	v_add_u32_e32 v2, 0x200, v2
	v_and_b32_e32 v1, 0xf8, v3
	v_or_b32_e32 v0, s21, v1
	v_ashrrev_i32_e32 v8, 5, v2
	v_add_u32_e32 v8, s22, v8
	v_ashrrev_i32_e32 v9, 31, v8
	v_lshlrev_b64 v[8:9], 11, v[8:9]
	v_lshl_add_u64 v[8:9], s[8:9], 0, v[8:9]
	v_ashrrev_i32_e32 v1, 31, v0
	v_lshl_add_u64 v[0:1], v[0:1], 1, v[8:9]
	s_waitcnt lgkmcnt(1)
	global_store_dwordx4 v[0:1], v[120:123], off
	v_add_u32_e32 v2, 0x200, v2
	v_and_b32_e32 v1, 0xf8, v3
	v_or_b32_e32 v0, s21, v1
	v_ashrrev_i32_e32 v8, 5, v2
	v_add_u32_e32 v8, s22, v8
	v_ashrrev_i32_e32 v9, 31, v8
	v_lshlrev_b64 v[8:9], 11, v[8:9]
	v_lshl_add_u64 v[8:9], s[8:9], 0, v[8:9]
	v_ashrrev_i32_e32 v1, 31, v0
	v_lshl_add_u64 v[0:1], v[0:1], 1, v[8:9]
	s_waitcnt lgkmcnt(0)
	global_store_dwordx4 v[0:1], v[124:127], off
.Lep_done_1273:
	s_or_b64 exec, exec, s[10:11]
	s_branch .LBB0_1273
